# combo20 + GEMM K-loop load segments: the vmcnt(8) and lgkmcnt(0) waits before each barrier merged into one s_waitcnt; s_nop 0 between m0 write and LDS-DMA replaced by reordering the address add
# speedup vs baseline: 1.0000x; 1.0000x over previous
; #define PG8_STAGE(bufoff, gbase, voff) do { _Pragma("unroll") for (int _i = 0; _i < 2; ++_i) \
;         __builtin_amdgcn_global_load_lds((const unsigned*)((const char*)(gbase) + (voff)[_i]), (LAS unsigned*)(lds + (bufoff) + ldsw + _i * 8192), 16, 0, 0); } while (0)
; #define PG8_LDA(dst, b, h) do { _Pragma("unroll") for (int m = 0; m < 4; ++m) _Pragma("unroll") for (int k = 0; k < 2; ++k) dst[m][k] = *(const LAS bf16x8*)(lds + PG8_SA(b, h) + aoff + m * 2048 + k * 1024); } while (0)
; #define PG8_LDB(dst, b, h) do { _Pragma("unroll") for (int n = 0; n < 2; ++n) _Pragma("unroll") for (int k = 0; k < 2; ++k) dst[n][k] = *(const LAS bf16x8*)(lds + PG8_SB(b, h) + boff + n * 2048 + k * 1024); } while (0)
; #define PG8_WAIT_V(n) asm volatile("s_waitcnt vmcnt(" #n ")" ::: "memory")
; #define PG8_WAIT_L(n) asm volatile("s_waitcnt lgkmcnt(" #n ")" ::: "memory")
; template <class Epi>
; __device__ __forceinline__ void gemm_phase(LAS unsigned char* lds, const Gemm g, const StaticOrder& S, const Epi& E, const int tid) {
;     ...
;         for (int t = 0; t < nt; t += 2) {
;             const bool last = (t == nt - 2);
;             const char* a1 = cA + (size_t)(t + 1) * kstep;
;             const char* a2 = last ? nA : cA + (size_t)(t + 2) * kstep; const char* b2 = last ? nB : cB + (size_t)(t + 2) * kstep;
;             const char* a3 = a2 + kstep; const char* b3 = b2 + kstep;
;             PG8_LDB(B0, 0, 0); PG8_LDB(B1, 0, 1); PG8_SCHED; PG8_LDA(At, 0, 0); PG8_STAGE(PG8_SA(1, 1), a1 + hsA, voffA);
;             PG8_WAIT_V(8); PG8_WAIT_L(0); PG8_BAR; PG8_MMA(0, 0, At, B0); PG8_MMA(0, 1, At, B1); PG8_BAR; PG8_SCHED;
;             PG8_LDA(At, 0, 1); PG8_STAGE(PG8_SB(0, 0), b2, voffB); PG8_STAGE(PG8_SB(0, 1), b2 + hsB, voffB); PG8_STAGE(PG8_SA(0, 0), a2, voffA);
;             PG8_WAIT_V(8); PG8_WAIT_L(0); PG8_BAR; PG8_MMA(1, 0, At, B0); PG8_MMA(1, 1, At, B1); PG8_BAR; PG8_SCHED;
;             PG8_LDB(B0, 1, 0); PG8_LDB(B1, 1, 1); PG8_SCHED; PG8_LDA(At, 1, 0); PG8_STAGE(PG8_SA(0, 1), a2 + hsA, voffA);
;             PG8_WAIT_V(8); PG8_WAIT_L(0); PG8_BAR; PG8_MMA(0, 0, At, B0); PG8_MMA(0, 1, At, B1); PG8_BAR; PG8_SCHED;
;             PG8_LDA(At, 1, 1); PG8_STAGE(PG8_SB(1, 0), b3, voffB); PG8_STAGE(PG8_SB(1, 1), b3 + hsB, voffB); PG8_STAGE(PG8_SA(1, 0), a3, voffA);
;             PG8_WAIT_V(8); PG8_WAIT_L(0); PG8_BAR; PG8_MMA(1, 0, At, B0); PG8_MMA(1, 1, At, B1); PG8_BAR; PG8_SCHED;
.Lgprio_a:
	s_add_u32 s0, s34, 0xfff80080
	s_addc_u32 s1, s35, -1
	s_add_i32 s24, 0, 0x10000
	s_cmp_eq_u32 s59, 28
	s_cselect_b32 s39, s15, s1
	s_cselect_b32 s38, s53, s0
	s_cselect_b32 s1, s13, s58
	s_cselect_b32 s0, s56, s57
	s_add_i32 s25, 0, 0x14000
	v_add_u32_e32 v154, s24, v143
	v_add_u32_e32 v166, s25, v143
	ds_read_b128 v[138:141], v154
	ds_read_b128 v[146:149], v154 offset:1024
	ds_read_b128 v[150:153], v154 offset:2048
	ds_read_b128 v[154:157], v154 offset:3072
	ds_read_b128 v[158:161], v166
	ds_read_b128 v[162:165], v166 offset:1024
	ds_read_b128 v[184:187], v166 offset:2048
	ds_read_b128 v[188:191], v166 offset:3072
	v_lshl_add_u64 v[166:167], s[34:35], 0, v[134:135]
	s_add_i32 m0, s42, 0xc000
	ds_read_b128 v[192:195], v145
	ds_read_b128 v[196:199], v145 offset:1024
	ds_read_b128 v[200:203], v145 offset:2048
	ds_read_b128 v[204:207], v145 offset:3072
	ds_read_b128 v[208:211], v145 offset:4096
	ds_read_b128 v[230:233], v145 offset:5120
	ds_read_b128 v[234:237], v145 offset:6144
	ds_read_b128 v[238:241], v145 offset:7168
	global_load_lds_dwordx4 v[166:167], off
	s_add_i32 m0, s42, 0xe000
	v_lshl_add_u64 v[166:167], s[34:35], 0, v[136:137]
	global_load_lds_dwordx4 v[166:167], off
	s_waitcnt vmcnt(8) lgkmcnt(0)
	s_barrier
	v_mfma_f32_16x16x32_bf16 v[124:127], v[138:141], v[192:195], 0
	v_mfma_f32_16x16x32_bf16 v[116:119], v[150:153], v[192:195], 0
	v_mfma_f32_16x16x32_bf16 v[108:111], v[138:141], v[200:203], 0
	v_mfma_f32_16x16x32_bf16 v[100:103], v[150:153], v[200:203], 0
	v_mfma_f32_16x16x32_bf16 v[92:95], v[138:141], v[208:211], 0
	v_mfma_f32_16x16x32_bf16 v[84:87], v[150:153], v[208:211], 0
	v_mfma_f32_16x16x32_bf16 v[76:79], v[138:141], v[234:237], 0
	v_mfma_f32_16x16x32_bf16 v[68:71], v[150:153], v[234:237], 0
	v_mfma_f32_16x16x32_bf16 v[124:127], v[146:149], v[196:199], v[124:127]
	v_mfma_f32_16x16x32_bf16 v[116:119], v[154:157], v[196:199], v[116:119]
	v_mfma_f32_16x16x32_bf16 v[108:111], v[146:149], v[204:207], v[108:111]
	v_mfma_f32_16x16x32_bf16 v[100:103], v[154:157], v[204:207], v[100:103]
	v_mfma_f32_16x16x32_bf16 v[92:95], v[146:149], v[230:233], v[92:95]
	v_mfma_f32_16x16x32_bf16 v[84:87], v[154:157], v[230:233], v[84:87]
	v_mfma_f32_16x16x32_bf16 v[76:79], v[146:149], v[238:241], v[76:79]
	v_mfma_f32_16x16x32_bf16 v[68:71], v[154:157], v[238:241], v[68:71]
	v_mfma_f32_16x16x32_bf16 v[120:123], v[158:161], v[192:195], 0
	v_mfma_f32_16x16x32_bf16 v[112:115], v[184:187], v[192:195], 0
	v_mfma_f32_16x16x32_bf16 v[104:107], v[158:161], v[200:203], 0
	v_mfma_f32_16x16x32_bf16 v[96:99], v[184:187], v[200:203], 0
	v_mfma_f32_16x16x32_bf16 v[88:91], v[158:161], v[208:211], 0
	v_mfma_f32_16x16x32_bf16 v[80:83], v[184:187], v[208:211], 0
	v_mfma_f32_16x16x32_bf16 v[72:75], v[158:161], v[234:237], 0
	v_mfma_f32_16x16x32_bf16 v[64:67], v[184:187], v[234:237], 0
	v_mfma_f32_16x16x32_bf16 v[120:123], v[162:165], v[196:199], v[120:123]
	v_mfma_f32_16x16x32_bf16 v[112:115], v[188:191], v[196:199], v[112:115]
	v_mfma_f32_16x16x32_bf16 v[104:107], v[162:165], v[204:207], v[104:107]
	v_mfma_f32_16x16x32_bf16 v[96:99], v[188:191], v[204:207], v[96:99]
	v_mfma_f32_16x16x32_bf16 v[88:91], v[162:165], v[230:233], v[88:91]
	v_mfma_f32_16x16x32_bf16 v[80:83], v[188:191], v[230:233], v[80:83]
	v_mfma_f32_16x16x32_bf16 v[72:75], v[162:165], v[238:241], v[72:75]
	v_mfma_f32_16x16x32_bf16 v[64:67], v[188:191], v[238:241], v[64:67]
	s_barrier
	s_add_i32 s24, s24, s27
	v_lshl_add_u64 v[166:167], s[0:1], 0, v[168:169]
	s_mov_b32 m0, s24
	ds_read_b128 v[192:195], v145 offset:16384
	ds_read_b128 v[196:199], v145 offset:17408
	ds_read_b128 v[200:203], v145 offset:18432
	ds_read_b128 v[204:207], v145 offset:19456
	ds_read_b128 v[208:211], v145 offset:20480
	ds_read_b128 v[230:233], v145 offset:21504
	ds_read_b128 v[234:237], v145 offset:22528
	ds_read_b128 v[238:241], v145 offset:23552
	global_load_lds_dwordx4 v[166:167], off
	s_add_i32 m0, s24, 0x2000
	s_add_u32 s68, s0, 0x80000
	v_lshl_add_u64 v[212:213], s[0:1], 0, v[132:133]
	s_addc_u32 s69, s1, 0
	s_add_i32 s24, s25, s27
	global_load_lds_dwordx4 v[212:213], off
	v_lshl_add_u64 v[242:243], s[68:69], 0, v[168:169]
	s_mov_b32 m0, s24
	v_lshl_add_u64 v[244:245], s[38:39], 0, v[130:131]
	global_load_lds_dwordx4 v[242:243], off
	s_add_i32 m0, s24, 0x2000
	v_lshl_add_u64 v[242:243], s[68:69], 0, v[132:133]
	global_load_lds_dwordx4 v[242:243], off
	s_mov_b32 m0, s42
	v_lshl_add_u64 v[242:243], s[38:39], 0, v[128:129]
	global_load_lds_dwordx4 v[242:243], off
	s_mov_b32 m0, s43
	s_nop 0
	global_load_lds_dwordx4 v[244:245], off
	s_waitcnt vmcnt(8) lgkmcnt(0)
	s_barrier
	v_mfma_f32_16x16x32_bf16 v[60:63], v[138:141], v[192:195], 0
	v_mfma_f32_16x16x32_bf16 v[52:55], v[150:153], v[192:195], 0
	v_mfma_f32_16x16x32_bf16 v[44:47], v[138:141], v[200:203], 0
	v_mfma_f32_16x16x32_bf16 v[36:39], v[150:153], v[200:203], 0
	v_mfma_f32_16x16x32_bf16 v[28:31], v[138:141], v[208:211], 0
	v_mfma_f32_16x16x32_bf16 v[20:23], v[150:153], v[208:211], 0
	v_mfma_f32_16x16x32_bf16 v[12:15], v[138:141], v[234:237], 0
	v_mfma_f32_16x16x32_bf16 v[4:7], v[150:153], v[234:237], 0
	v_mfma_f32_16x16x32_bf16 v[60:63], v[146:149], v[196:199], v[60:63]
	v_mfma_f32_16x16x32_bf16 v[52:55], v[154:157], v[196:199], v[52:55]
	v_mfma_f32_16x16x32_bf16 v[44:47], v[146:149], v[204:207], v[44:47]
	v_mfma_f32_16x16x32_bf16 v[36:39], v[154:157], v[204:207], v[36:39]
	v_mfma_f32_16x16x32_bf16 v[28:31], v[146:149], v[230:233], v[28:31]
	v_mfma_f32_16x16x32_bf16 v[20:23], v[154:157], v[230:233], v[20:23]
	v_mfma_f32_16x16x32_bf16 v[12:15], v[146:149], v[238:241], v[12:15]
	v_mfma_f32_16x16x32_bf16 v[4:7], v[154:157], v[238:241], v[4:7]
	v_mfma_f32_16x16x32_bf16 v[56:59], v[158:161], v[192:195], 0
	v_mfma_f32_16x16x32_bf16 v[48:51], v[184:187], v[192:195], 0
	v_mfma_f32_16x16x32_bf16 v[40:43], v[158:161], v[200:203], 0
	v_mfma_f32_16x16x32_bf16 v[32:35], v[184:187], v[200:203], 0
	v_mfma_f32_16x16x32_bf16 v[24:27], v[158:161], v[208:211], 0
	v_mfma_f32_16x16x32_bf16 v[16:19], v[184:187], v[208:211], 0
	v_mfma_f32_16x16x32_bf16 v[8:11], v[158:161], v[234:237], 0
	v_mfma_f32_16x16x32_bf16 v[0:3], v[184:187], v[234:237], 0
	v_mfma_f32_16x16x32_bf16 v[56:59], v[162:165], v[196:199], v[56:59]
	v_mfma_f32_16x16x32_bf16 v[48:51], v[188:191], v[196:199], v[48:51]
	v_mfma_f32_16x16x32_bf16 v[40:43], v[162:165], v[204:207], v[40:43]
	v_mfma_f32_16x16x32_bf16 v[32:35], v[188:191], v[204:207], v[32:35]
	v_mfma_f32_16x16x32_bf16 v[24:27], v[162:165], v[230:233], v[24:27]
	v_mfma_f32_16x16x32_bf16 v[16:19], v[188:191], v[230:233], v[16:19]
	v_mfma_f32_16x16x32_bf16 v[8:11], v[162:165], v[238:241], v[8:11]
	v_mfma_f32_16x16x32_bf16 v[0:3], v[188:191], v[238:241], v[0:3]
	s_barrier
; #define PG8_STAGE(bufoff, gbase, voff) do { _Pragma("unroll") for (int _i = 0; _i < 2; ++_i) \
;         __builtin_amdgcn_global_load_lds((const unsigned*)((const char*)(gbase) + (voff)[_i]), (LAS unsigned*)(lds + (bufoff) + ldsw + _i * 8192), 16, 0, 0); } while (0)
; #define PG8_LDA(dst, b, h) do { _Pragma("unroll") for (int m = 0; m < 4; ++m) _Pragma("unroll") for (int k = 0; k < 2; ++k) dst[m][k] = *(const LAS bf16x8*)(lds + PG8_SA(b, h) + aoff + m * 2048 + k * 1024); } while (0)
; #define PG8_WAIT_V(n) asm volatile("s_waitcnt vmcnt(" #n ")" ::: "memory")
; #define PG8_WAIT_L(n) asm volatile("s_waitcnt lgkmcnt(" #n ")" ::: "memory")
; template <class Epi>
; __device__ __forceinline__ void gemm_phase(LAS unsigned char* lds, const Gemm g, const StaticOrder& S, const Epi& E, const int tid) {
;     ...
;     for (;;) {
;         const bool has_next = S.next(ui + 1, nxt);
;         const char* nA = has_next ? PG8_APTR(nxt) : cA; const char* nB = has_next ? PG8_BPTR(nxt) : cB;
;         for (int t = 0; t < nt; t += 2) {
;             const bool last = (t == nt - 2);
;             const char* a1 = cA + (size_t)(t + 1) * kstep;
;             const char* a2 = last ? nA : cA + (size_t)(t + 2) * kstep; const char* b2 = last ? nB : cB + (size_t)(t + 2) * kstep;
;             const char* a3 = a2 + kstep; const char* b3 = b2 + kstep;
;             PG8_LDB(B0, 0, 0); PG8_LDB(B1, 0, 1); PG8_SCHED; PG8_LDA(At, 0, 0); PG8_STAGE(PG8_SA(1, 1), a1 + hsA, voffA);
;             PG8_WAIT_V(8); PG8_WAIT_L(0); PG8_BAR; PG8_MMA(0, 0, At, B0); PG8_MMA(0, 1, At, B1); PG8_BAR; PG8_SCHED;
;             PG8_LDA(At, 0, 1); PG8_STAGE(PG8_SB(0, 0), b2, voffB); PG8_STAGE(PG8_SB(0, 1), b2 + hsB, voffB); PG8_STAGE(PG8_SA(0, 0), a2, voffA);
;             PG8_WAIT_V(8); PG8_WAIT_L(0); PG8_BAR; PG8_MMA(1, 0, At, B0); PG8_MMA(1, 1, At, B1); PG8_BAR; PG8_SCHED;
;             PG8_LDB(B0, 1, 0); PG8_LDB(B1, 1, 1); PG8_SCHED; PG8_LDA(At, 1, 0); PG8_STAGE(PG8_SA(0, 1), a2 + hsA, voffA);
;             PG8_WAIT_V(8); PG8_WAIT_L(0); PG8_BAR; PG8_MMA(0, 0, At, B0); PG8_MMA(0, 1, At, B1); PG8_BAR; PG8_SCHED;
;             PG8_LDA(At, 1, 1); PG8_STAGE(PG8_SB(1, 0), b3, voffB); PG8_STAGE(PG8_SB(1, 1), b3 + hsB, voffB); PG8_STAGE(PG8_SA(1, 0), a3, voffA);
;             PG8_WAIT_V(8); PG8_WAIT_L(0); PG8_BAR; PG8_MMA(1, 0, At, B0); PG8_MMA(1, 1, At, B1); PG8_BAR; PG8_SCHED;
	s_add_i32 s24, 0, 0x18000
	s_add_i32 s25, 0, 0x1c000
	v_add_u32_e32 v154, s24, v143
	v_add_u32_e32 v170, s25, v143
	ds_read_b128 v[138:141], v154
	ds_read_b128 v[146:149], v154 offset:1024
	ds_read_b128 v[150:153], v154 offset:2048
	ds_read_b128 v[154:157], v154 offset:3072
	ds_read_b128 v[158:161], v170
	ds_read_b128 v[162:165], v170 offset:1024
	ds_read_b128 v[184:187], v170 offset:2048
	ds_read_b128 v[188:191], v170 offset:3072
	s_add_u32 s38, s38, 0x80000
	s_addc_u32 s39, s39, 0
	s_mov_b32 m0, s44
	v_lshl_add_u64 v[246:247], s[38:39], 0, v[128:129]
	ds_read_b128 v[192:195], v145 offset:32768
	ds_read_b128 v[196:199], v145 offset:33792
	ds_read_b128 v[200:203], v145 offset:34816
	ds_read_b128 v[204:207], v145 offset:35840
	ds_read_b128 v[208:211], v145 offset:36864
	ds_read_b128 v[230:233], v145 offset:37888
	ds_read_b128 v[234:237], v145 offset:38912
	ds_read_b128 v[238:241], v145 offset:39936
	global_load_lds_dwordx4 v[246:247], off
	s_mov_b32 m0, s45
	v_lshl_add_u64 v[246:247], s[38:39], 0, v[130:131]
	global_load_lds_dwordx4 v[246:247], off
	s_waitcnt vmcnt(8) lgkmcnt(0)
	s_barrier
	v_mfma_f32_16x16x32_bf16 v[124:127], v[138:141], v[192:195], v[124:127]
	v_mfma_f32_16x16x32_bf16 v[116:119], v[150:153], v[192:195], v[116:119]
	v_mfma_f32_16x16x32_bf16 v[108:111], v[138:141], v[200:203], v[108:111]
	v_mfma_f32_16x16x32_bf16 v[100:103], v[150:153], v[200:203], v[100:103]
	v_mfma_f32_16x16x32_bf16 v[92:95], v[138:141], v[208:211], v[92:95]
	v_mfma_f32_16x16x32_bf16 v[84:87], v[150:153], v[208:211], v[84:87]
	v_mfma_f32_16x16x32_bf16 v[76:79], v[138:141], v[234:237], v[76:79]
	v_mfma_f32_16x16x32_bf16 v[68:71], v[150:153], v[234:237], v[68:71]
	v_mfma_f32_16x16x32_bf16 v[124:127], v[146:149], v[196:199], v[124:127]
	v_mfma_f32_16x16x32_bf16 v[116:119], v[154:157], v[196:199], v[116:119]
	v_mfma_f32_16x16x32_bf16 v[108:111], v[146:149], v[204:207], v[108:111]
	v_mfma_f32_16x16x32_bf16 v[100:103], v[154:157], v[204:207], v[100:103]
	v_mfma_f32_16x16x32_bf16 v[92:95], v[146:149], v[230:233], v[92:95]
	v_mfma_f32_16x16x32_bf16 v[84:87], v[154:157], v[230:233], v[84:87]
	v_mfma_f32_16x16x32_bf16 v[76:79], v[146:149], v[238:241], v[76:79]
	v_mfma_f32_16x16x32_bf16 v[68:71], v[154:157], v[238:241], v[68:71]
	v_mfma_f32_16x16x32_bf16 v[120:123], v[158:161], v[192:195], v[120:123]
	v_mfma_f32_16x16x32_bf16 v[112:115], v[184:187], v[192:195], v[112:115]
	v_mfma_f32_16x16x32_bf16 v[104:107], v[158:161], v[200:203], v[104:107]
	v_mfma_f32_16x16x32_bf16 v[96:99], v[184:187], v[200:203], v[96:99]
	v_mfma_f32_16x16x32_bf16 v[88:91], v[158:161], v[208:211], v[88:91]
	v_mfma_f32_16x16x32_bf16 v[80:83], v[184:187], v[208:211], v[80:83]
	v_mfma_f32_16x16x32_bf16 v[72:75], v[158:161], v[234:237], v[72:75]
	v_mfma_f32_16x16x32_bf16 v[64:67], v[184:187], v[234:237], v[64:67]
	v_mfma_f32_16x16x32_bf16 v[120:123], v[162:165], v[196:199], v[120:123]
	v_mfma_f32_16x16x32_bf16 v[112:115], v[188:191], v[196:199], v[112:115]
	v_mfma_f32_16x16x32_bf16 v[104:107], v[162:165], v[204:207], v[104:107]
	v_mfma_f32_16x16x32_bf16 v[96:99], v[188:191], v[204:207], v[96:99]
	v_mfma_f32_16x16x32_bf16 v[88:91], v[162:165], v[230:233], v[88:91]
	v_mfma_f32_16x16x32_bf16 v[80:83], v[188:191], v[230:233], v[80:83]
	v_mfma_f32_16x16x32_bf16 v[72:75], v[162:165], v[238:241], v[72:75]
	v_mfma_f32_16x16x32_bf16 v[64:67], v[188:191], v[238:241], v[64:67]
	s_barrier
	s_add_i32 s24, s24, s27
	v_lshl_add_u64 v[166:167], v[166:167], 0, s[28:29]
	s_mov_b32 m0, s24
	ds_read_b128 v[192:195], v145 offset:49152
	ds_read_b128 v[196:199], v145 offset:50176
	ds_read_b128 v[200:203], v145 offset:51200
	ds_read_b128 v[204:207], v145 offset:52224
	ds_read_b128 v[208:211], v145 offset:53248
	ds_read_b128 v[230:233], v145 offset:54272
	ds_read_b128 v[234:237], v145 offset:55296
	ds_read_b128 v[238:241], v145 offset:56320
	global_load_lds_dwordx4 v[166:167], off
	s_add_i32 m0, s24, 0x2000
	s_add_u32 s0, s0, 0x80080
	v_lshl_add_u64 v[166:167], v[212:213], 0, s[28:29]
	s_addc_u32 s1, s1, 0
	s_add_i32 s24, s25, s27
	global_load_lds_dwordx4 v[166:167], off
	s_mov_b32 m0, s24
	v_lshl_add_u64 v[166:167], s[0:1], 0, v[168:169]
	global_load_lds_dwordx4 v[166:167], off
	s_add_i32 m0, s24, 0x2000
	v_lshl_add_u64 v[166:167], s[0:1], 0, v[132:133]
	global_load_lds_dwordx4 v[166:167], off
	s_mov_b32 m0, s46
	v_lshl_add_u64 v[166:167], v[242:243], 0, s[28:29]
	global_load_lds_dwordx4 v[166:167], off
	s_mov_b32 m0, s47
	v_lshl_add_u64 v[166:167], v[244:245], 0, s[28:29]
	global_load_lds_dwordx4 v[166:167], off
	s_waitcnt vmcnt(8) lgkmcnt(0)
	s_barrier
	v_mfma_f32_16x16x32_bf16 v[60:63], v[138:141], v[192:195], v[60:63]
	v_mfma_f32_16x16x32_bf16 v[52:55], v[150:153], v[192:195], v[52:55]
	v_mfma_f32_16x16x32_bf16 v[44:47], v[138:141], v[200:203], v[44:47]
	v_mfma_f32_16x16x32_bf16 v[36:39], v[150:153], v[200:203], v[36:39]
	v_mfma_f32_16x16x32_bf16 v[28:31], v[138:141], v[208:211], v[28:31]
	v_mfma_f32_16x16x32_bf16 v[20:23], v[150:153], v[208:211], v[20:23]
	v_mfma_f32_16x16x32_bf16 v[12:15], v[138:141], v[234:237], v[12:15]
	v_mfma_f32_16x16x32_bf16 v[4:7], v[150:153], v[234:237], v[4:7]
	v_mfma_f32_16x16x32_bf16 v[60:63], v[146:149], v[196:199], v[60:63]
	v_mfma_f32_16x16x32_bf16 v[52:55], v[154:157], v[196:199], v[52:55]
	v_mfma_f32_16x16x32_bf16 v[44:47], v[146:149], v[204:207], v[44:47]
	v_mfma_f32_16x16x32_bf16 v[36:39], v[154:157], v[204:207], v[36:39]
	v_mfma_f32_16x16x32_bf16 v[28:31], v[146:149], v[230:233], v[28:31]
	v_mfma_f32_16x16x32_bf16 v[20:23], v[154:157], v[230:233], v[20:23]
	v_mfma_f32_16x16x32_bf16 v[12:15], v[146:149], v[238:241], v[12:15]
	v_mfma_f32_16x16x32_bf16 v[4:7], v[154:157], v[238:241], v[4:7]
	v_mfma_f32_16x16x32_bf16 v[56:59], v[158:161], v[192:195], v[56:59]
	v_mfma_f32_16x16x32_bf16 v[48:51], v[184:187], v[192:195], v[48:51]
	v_mfma_f32_16x16x32_bf16 v[40:43], v[158:161], v[200:203], v[40:43]
	v_mfma_f32_16x16x32_bf16 v[32:35], v[184:187], v[200:203], v[32:35]
	v_mfma_f32_16x16x32_bf16 v[24:27], v[158:161], v[208:211], v[24:27]
	v_mfma_f32_16x16x32_bf16 v[16:19], v[184:187], v[208:211], v[16:19]
	v_mfma_f32_16x16x32_bf16 v[8:11], v[158:161], v[234:237], v[8:11]
	v_mfma_f32_16x16x32_bf16 v[0:3], v[184:187], v[234:237], v[0:3]
	v_mfma_f32_16x16x32_bf16 v[56:59], v[162:165], v[196:199], v[56:59]
	v_mfma_f32_16x16x32_bf16 v[48:51], v[188:191], v[196:199], v[48:51]
	v_mfma_f32_16x16x32_bf16 v[40:43], v[162:165], v[204:207], v[40:43]
	v_mfma_f32_16x16x32_bf16 v[32:35], v[188:191], v[204:207], v[32:35]
	v_mfma_f32_16x16x32_bf16 v[24:27], v[162:165], v[230:233], v[24:27]
	v_mfma_f32_16x16x32_bf16 v[16:19], v[188:191], v[230:233], v[16:19]
	v_mfma_f32_16x16x32_bf16 v[8:11], v[162:165], v[238:241], v[8:11]
	v_mfma_f32_16x16x32_bf16 v[0:3], v[188:191], v[238:241], v[0:3]
	s_barrier
	s_add_i32 s59, s59, 2
	s_add_u32 s34, s34, 0x100
	s_addc_u32 s35, s35, 0
	s_add_u32 s57, s57, 0x100
	s_addc_u32 s58, s58, 0
	s_cmp_gt_u32 s59, 29
; #define PG8_STAGE(bufoff, gbase, voff) do { _Pragma("unroll") for (int _i = 0; _i < 2; ++_i) \
;         __builtin_amdgcn_global_load_lds((const unsigned*)((const char*)(gbase) + (voff)[_i]), (LAS unsigned*)(lds + (bufoff) + ldsw + _i * 8192), 16, 0, 0); } while (0)
; #define PG8_LDA(dst, b, h) do { _Pragma("unroll") for (int m = 0; m < 4; ++m) _Pragma("unroll") for (int k = 0; k < 2; ++k) dst[m][k] = *(const LAS bf16x8*)(lds + PG8_SA(b, h) + aoff + m * 2048 + k * 1024); } while (0)
; #define PG8_LDB(dst, b, h) do { _Pragma("unroll") for (int n = 0; n < 2; ++n) _Pragma("unroll") for (int k = 0; k < 2; ++k) dst[n][k] = *(const LAS bf16x8*)(lds + PG8_SB(b, h) + boff + n * 2048 + k * 1024); } while (0)
; #define PG8_WAIT_V(n) asm volatile("s_waitcnt vmcnt(" #n ")" ::: "memory")
; #define PG8_WAIT_L(n) asm volatile("s_waitcnt lgkmcnt(" #n ")" ::: "memory")
; template <class Epi>
; __device__ __forceinline__ void gemm_phase(LAS unsigned char* lds, const Gemm g, const StaticOrder& S, const Epi& E, const int tid) {
;     ...
;         for (int t = 0; t < nt; t += 2) {
;             const bool last = (t == nt - 2);
;             const char* a1 = cA + (size_t)(t + 1) * kstep;
;             const char* a2 = last ? nA : cA + (size_t)(t + 2) * kstep; const char* b2 = last ? nB : cB + (size_t)(t + 2) * kstep;
;             const char* a3 = a2 + kstep; const char* b3 = b2 + kstep;
;             PG8_LDB(B0, 0, 0); PG8_LDB(B1, 0, 1); PG8_SCHED; PG8_LDA(At, 0, 0); PG8_STAGE(PG8_SA(1, 1), a1 + hsA, voffA);
;             PG8_WAIT_V(8); PG8_WAIT_L(0); PG8_BAR; PG8_MMA(0, 0, At, B0); PG8_MMA(0, 1, At, B1); PG8_BAR; PG8_SCHED;
;             PG8_LDA(At, 0, 1); PG8_STAGE(PG8_SB(0, 0), b2, voffB); PG8_STAGE(PG8_SB(0, 1), b2 + hsB, voffB); PG8_STAGE(PG8_SA(0, 0), a2, voffA);
;             PG8_WAIT_V(8); PG8_WAIT_L(0); PG8_BAR; PG8_MMA(1, 0, At, B0); PG8_MMA(1, 1, At, B1); PG8_BAR; PG8_SCHED;
;             PG8_LDB(B0, 1, 0); PG8_LDB(B1, 1, 1); PG8_SCHED; PG8_LDA(At, 1, 0); PG8_STAGE(PG8_SA(0, 1), a2 + hsA, voffA);
;             PG8_WAIT_V(8); PG8_WAIT_L(0); PG8_BAR; PG8_MMA(0, 0, At, B0); PG8_MMA(0, 1, At, B1); PG8_BAR; PG8_SCHED;
;             PG8_LDA(At, 1, 1); PG8_STAGE(PG8_SB(1, 0), b3, voffB); PG8_STAGE(PG8_SB(1, 1), b3 + hsB, voffB); PG8_STAGE(PG8_SA(1, 0), a3, voffA);
;             PG8_WAIT_V(8); PG8_WAIT_L(0); PG8_BAR; PG8_MMA(1, 0, At, B0); PG8_MMA(1, 1, At, B1); PG8_BAR; PG8_SCHED;
.LBB0_161:
	s_add_u32 s0, s34, 0xfff80080
	s_addc_u32 s1, s35, -1
	s_add_i32 s24, 0, 0x10000
	s_cmp_eq_u32 s59, 28
	s_cselect_b32 s39, s15, s1
	s_cselect_b32 s38, s53, s0
	s_cselect_b32 s1, s13, s58
	s_cselect_b32 s0, s56, s57
	s_add_i32 s25, 0, 0x14000
	v_add_u32_e32 v154, s24, v143
	v_add_u32_e32 v166, s25, v143
	ds_read_b128 v[138:141], v154
	ds_read_b128 v[146:149], v154 offset:1024
	ds_read_b128 v[150:153], v154 offset:2048
	ds_read_b128 v[154:157], v154 offset:3072
	ds_read_b128 v[158:161], v166
	ds_read_b128 v[162:165], v166 offset:1024
	ds_read_b128 v[184:187], v166 offset:2048
	ds_read_b128 v[188:191], v166 offset:3072
	v_lshl_add_u64 v[166:167], s[34:35], 0, v[134:135]
	s_add_i32 m0, s42, 0xc000
	ds_read_b128 v[192:195], v145
	ds_read_b128 v[196:199], v145 offset:1024
	ds_read_b128 v[200:203], v145 offset:2048
	ds_read_b128 v[204:207], v145 offset:3072
	ds_read_b128 v[208:211], v145 offset:4096
	ds_read_b128 v[230:233], v145 offset:5120
	ds_read_b128 v[234:237], v145 offset:6144
	ds_read_b128 v[238:241], v145 offset:7168
	global_load_lds_dwordx4 v[166:167], off
	s_add_i32 m0, s42, 0xe000
	v_lshl_add_u64 v[166:167], s[34:35], 0, v[136:137]
	global_load_lds_dwordx4 v[166:167], off
	s_waitcnt vmcnt(8) lgkmcnt(0)
	s_barrier
	v_mfma_f32_16x16x32_bf16 v[124:127], v[138:141], v[192:195], v[124:127]
	v_mfma_f32_16x16x32_bf16 v[116:119], v[150:153], v[192:195], v[116:119]
	v_mfma_f32_16x16x32_bf16 v[108:111], v[138:141], v[200:203], v[108:111]
	v_mfma_f32_16x16x32_bf16 v[100:103], v[150:153], v[200:203], v[100:103]
	v_mfma_f32_16x16x32_bf16 v[92:95], v[138:141], v[208:211], v[92:95]
	v_mfma_f32_16x16x32_bf16 v[84:87], v[150:153], v[208:211], v[84:87]
	v_mfma_f32_16x16x32_bf16 v[76:79], v[138:141], v[234:237], v[76:79]
	v_mfma_f32_16x16x32_bf16 v[68:71], v[150:153], v[234:237], v[68:71]
	v_mfma_f32_16x16x32_bf16 v[124:127], v[146:149], v[196:199], v[124:127]
	v_mfma_f32_16x16x32_bf16 v[116:119], v[154:157], v[196:199], v[116:119]
	v_mfma_f32_16x16x32_bf16 v[108:111], v[146:149], v[204:207], v[108:111]
	v_mfma_f32_16x16x32_bf16 v[100:103], v[154:157], v[204:207], v[100:103]
	v_mfma_f32_16x16x32_bf16 v[92:95], v[146:149], v[230:233], v[92:95]
	v_mfma_f32_16x16x32_bf16 v[84:87], v[154:157], v[230:233], v[84:87]
	v_mfma_f32_16x16x32_bf16 v[76:79], v[146:149], v[238:241], v[76:79]
	v_mfma_f32_16x16x32_bf16 v[68:71], v[154:157], v[238:241], v[68:71]
	v_mfma_f32_16x16x32_bf16 v[120:123], v[158:161], v[192:195], v[120:123]
	v_mfma_f32_16x16x32_bf16 v[112:115], v[184:187], v[192:195], v[112:115]
	v_mfma_f32_16x16x32_bf16 v[104:107], v[158:161], v[200:203], v[104:107]
	v_mfma_f32_16x16x32_bf16 v[96:99], v[184:187], v[200:203], v[96:99]
	v_mfma_f32_16x16x32_bf16 v[88:91], v[158:161], v[208:211], v[88:91]
	v_mfma_f32_16x16x32_bf16 v[80:83], v[184:187], v[208:211], v[80:83]
	v_mfma_f32_16x16x32_bf16 v[72:75], v[158:161], v[234:237], v[72:75]
	v_mfma_f32_16x16x32_bf16 v[64:67], v[184:187], v[234:237], v[64:67]
	v_mfma_f32_16x16x32_bf16 v[120:123], v[162:165], v[196:199], v[120:123]
	v_mfma_f32_16x16x32_bf16 v[112:115], v[188:191], v[196:199], v[112:115]
	v_mfma_f32_16x16x32_bf16 v[104:107], v[162:165], v[204:207], v[104:107]
	v_mfma_f32_16x16x32_bf16 v[96:99], v[188:191], v[204:207], v[96:99]
	v_mfma_f32_16x16x32_bf16 v[88:91], v[162:165], v[230:233], v[88:91]
	v_mfma_f32_16x16x32_bf16 v[80:83], v[188:191], v[230:233], v[80:83]
	v_mfma_f32_16x16x32_bf16 v[72:75], v[162:165], v[238:241], v[72:75]
	v_mfma_f32_16x16x32_bf16 v[64:67], v[188:191], v[238:241], v[64:67]
	s_barrier
	s_add_i32 s24, s24, s27
	v_lshl_add_u64 v[166:167], s[0:1], 0, v[168:169]
	s_mov_b32 m0, s24
	ds_read_b128 v[192:195], v145 offset:16384
	ds_read_b128 v[196:199], v145 offset:17408
	ds_read_b128 v[200:203], v145 offset:18432
	ds_read_b128 v[204:207], v145 offset:19456
	ds_read_b128 v[208:211], v145 offset:20480
	ds_read_b128 v[230:233], v145 offset:21504
	ds_read_b128 v[234:237], v145 offset:22528
	ds_read_b128 v[238:241], v145 offset:23552
	global_load_lds_dwordx4 v[166:167], off
	s_add_i32 m0, s24, 0x2000
	s_add_u32 s68, s0, 0x80000
	v_lshl_add_u64 v[212:213], s[0:1], 0, v[132:133]
	s_addc_u32 s69, s1, 0
	s_add_i32 s24, s25, s27
	global_load_lds_dwordx4 v[212:213], off
	v_lshl_add_u64 v[242:243], s[68:69], 0, v[168:169]
	s_mov_b32 m0, s24
	v_lshl_add_u64 v[244:245], s[38:39], 0, v[130:131]
	global_load_lds_dwordx4 v[242:243], off
	s_add_i32 m0, s24, 0x2000
	v_lshl_add_u64 v[242:243], s[68:69], 0, v[132:133]
	global_load_lds_dwordx4 v[242:243], off
	s_mov_b32 m0, s42
	v_lshl_add_u64 v[242:243], s[38:39], 0, v[128:129]
	global_load_lds_dwordx4 v[242:243], off
	s_mov_b32 m0, s43
	s_nop 0
	global_load_lds_dwordx4 v[244:245], off
	s_waitcnt vmcnt(8) lgkmcnt(0)
	s_barrier
; #define PG8_STAGE(bufoff, gbase, voff) do { _Pragma("unroll") for (int _i = 0; _i < 2; ++_i) \
;         __builtin_amdgcn_global_load_lds((const unsigned*)((const char*)(gbase) + (voff)[_i]), (LAS unsigned*)(lds + (bufoff) + ldsw + _i * 8192), 16, 0, 0); } while (0)
; #define PG8_LDA(dst, b, h) do { _Pragma("unroll") for (int m = 0; m < 4; ++m) _Pragma("unroll") for (int k = 0; k < 2; ++k) dst[m][k] = *(const LAS bf16x8*)(lds + PG8_SA(b, h) + aoff + m * 2048 + k * 1024); } while (0)
; #define PG8_LDB(dst, b, h) do { _Pragma("unroll") for (int n = 0; n < 2; ++n) _Pragma("unroll") for (int k = 0; k < 2; ++k) dst[n][k] = *(const LAS bf16x8*)(lds + PG8_SB(b, h) + boff + n * 2048 + k * 1024); } while (0)
; #define PG8_WAIT_V(n) asm volatile("s_waitcnt vmcnt(" #n ")" ::: "memory")
; #define PG8_WAIT_L(n) asm volatile("s_waitcnt lgkmcnt(" #n ")" ::: "memory")
; template <class Epi>
; __device__ __forceinline__ void gemm_phase(LAS unsigned char* lds, const Gemm g, const StaticOrder& S, const Epi& E, const int tid) {
;     ...
;         for (int t = 0; t < nt; t += 2) {
;             const bool last = (t == nt - 2);
;             const char* a1 = cA + (size_t)(t + 1) * kstep;
;             const char* a2 = last ? nA : cA + (size_t)(t + 2) * kstep; const char* b2 = last ? nB : cB + (size_t)(t + 2) * kstep;
;             const char* a3 = a2 + kstep; const char* b3 = b2 + kstep;
;             PG8_LDB(B0, 0, 0); PG8_LDB(B1, 0, 1); PG8_SCHED; PG8_LDA(At, 0, 0); PG8_STAGE(PG8_SA(1, 1), a1 + hsA, voffA);
;             PG8_WAIT_V(8); PG8_WAIT_L(0); PG8_BAR; PG8_MMA(0, 0, At, B0); PG8_MMA(0, 1, At, B1); PG8_BAR; PG8_SCHED;
;             PG8_LDA(At, 0, 1); PG8_STAGE(PG8_SB(0, 0), b2, voffB); PG8_STAGE(PG8_SB(0, 1), b2 + hsB, voffB); PG8_STAGE(PG8_SA(0, 0), a2, voffA);
;             PG8_WAIT_V(8); PG8_WAIT_L(0); PG8_BAR; PG8_MMA(1, 0, At, B0); PG8_MMA(1, 1, At, B1); PG8_BAR; PG8_SCHED;
;             PG8_LDB(B0, 1, 0); PG8_LDB(B1, 1, 1); PG8_SCHED; PG8_LDA(At, 1, 0); PG8_STAGE(PG8_SA(0, 1), a2 + hsA, voffA);
;             PG8_WAIT_V(8); PG8_WAIT_L(0); PG8_BAR; PG8_MMA(0, 0, At, B0); PG8_MMA(0, 1, At, B1); PG8_BAR; PG8_SCHED;
;             PG8_LDA(At, 1, 1); PG8_STAGE(PG8_SB(1, 0), b3, voffB); PG8_STAGE(PG8_SB(1, 1), b3 + hsB, voffB); PG8_STAGE(PG8_SA(1, 0), a3, voffA);
;             PG8_WAIT_V(8); PG8_WAIT_L(0); PG8_BAR; PG8_MMA(1, 0, At, B0); PG8_MMA(1, 1, At, B1); PG8_BAR; PG8_SCHED;
	v_mfma_f32_16x16x32_bf16 v[60:63], v[138:141], v[192:195], v[60:63]
	v_mfma_f32_16x16x32_bf16 v[52:55], v[150:153], v[192:195], v[52:55]
	v_mfma_f32_16x16x32_bf16 v[44:47], v[138:141], v[200:203], v[44:47]
	v_mfma_f32_16x16x32_bf16 v[36:39], v[150:153], v[200:203], v[36:39]
	v_mfma_f32_16x16x32_bf16 v[28:31], v[138:141], v[208:211], v[28:31]
	v_mfma_f32_16x16x32_bf16 v[20:23], v[150:153], v[208:211], v[20:23]
	v_mfma_f32_16x16x32_bf16 v[12:15], v[138:141], v[234:237], v[12:15]
	v_mfma_f32_16x16x32_bf16 v[4:7], v[150:153], v[234:237], v[4:7]
	v_mfma_f32_16x16x32_bf16 v[60:63], v[146:149], v[196:199], v[60:63]
	v_mfma_f32_16x16x32_bf16 v[52:55], v[154:157], v[196:199], v[52:55]
	v_mfma_f32_16x16x32_bf16 v[44:47], v[146:149], v[204:207], v[44:47]
	v_mfma_f32_16x16x32_bf16 v[36:39], v[154:157], v[204:207], v[36:39]
	v_mfma_f32_16x16x32_bf16 v[28:31], v[146:149], v[230:233], v[28:31]
	v_mfma_f32_16x16x32_bf16 v[20:23], v[154:157], v[230:233], v[20:23]
	v_mfma_f32_16x16x32_bf16 v[12:15], v[146:149], v[238:241], v[12:15]
	v_mfma_f32_16x16x32_bf16 v[4:7], v[154:157], v[238:241], v[4:7]
	v_mfma_f32_16x16x32_bf16 v[56:59], v[158:161], v[192:195], v[56:59]
	v_mfma_f32_16x16x32_bf16 v[48:51], v[184:187], v[192:195], v[48:51]
	v_mfma_f32_16x16x32_bf16 v[40:43], v[158:161], v[200:203], v[40:43]
	v_mfma_f32_16x16x32_bf16 v[32:35], v[184:187], v[200:203], v[32:35]
	v_mfma_f32_16x16x32_bf16 v[24:27], v[158:161], v[208:211], v[24:27]
	v_mfma_f32_16x16x32_bf16 v[16:19], v[184:187], v[208:211], v[16:19]
	v_mfma_f32_16x16x32_bf16 v[8:11], v[158:161], v[234:237], v[8:11]
	v_mfma_f32_16x16x32_bf16 v[0:3], v[184:187], v[234:237], v[0:3]
	v_mfma_f32_16x16x32_bf16 v[56:59], v[162:165], v[196:199], v[56:59]
	v_mfma_f32_16x16x32_bf16 v[48:51], v[188:191], v[196:199], v[48:51]
	v_mfma_f32_16x16x32_bf16 v[40:43], v[162:165], v[204:207], v[40:43]
	v_mfma_f32_16x16x32_bf16 v[32:35], v[188:191], v[204:207], v[32:35]
	v_mfma_f32_16x16x32_bf16 v[24:27], v[162:165], v[230:233], v[24:27]
	v_mfma_f32_16x16x32_bf16 v[16:19], v[188:191], v[230:233], v[16:19]
	v_mfma_f32_16x16x32_bf16 v[8:11], v[162:165], v[238:241], v[8:11]
	v_mfma_f32_16x16x32_bf16 v[0:3], v[188:191], v[238:241], v[0:3]
	s_barrier
	s_add_i32 s24, 0, 0x18000
	s_add_i32 s25, 0, 0x1c000
	v_add_u32_e32 v154, s24, v143
	v_add_u32_e32 v170, s25, v143
	ds_read_b128 v[138:141], v154
	ds_read_b128 v[146:149], v154 offset:1024
	ds_read_b128 v[150:153], v154 offset:2048
	ds_read_b128 v[154:157], v154 offset:3072
	ds_read_b128 v[158:161], v170
	ds_read_b128 v[162:165], v170 offset:1024
	ds_read_b128 v[184:187], v170 offset:2048
	ds_read_b128 v[188:191], v170 offset:3072
	s_add_u32 s38, s38, 0x80000
	s_addc_u32 s39, s39, 0
	s_mov_b32 m0, s44
	v_lshl_add_u64 v[246:247], s[38:39], 0, v[128:129]
	ds_read_b128 v[192:195], v145 offset:32768
	ds_read_b128 v[196:199], v145 offset:33792
	ds_read_b128 v[200:203], v145 offset:34816
	ds_read_b128 v[204:207], v145 offset:35840
	ds_read_b128 v[208:211], v145 offset:36864
	ds_read_b128 v[230:233], v145 offset:37888
	ds_read_b128 v[234:237], v145 offset:38912
	ds_read_b128 v[238:241], v145 offset:39936
	global_load_lds_dwordx4 v[246:247], off
	s_mov_b32 m0, s45
	v_lshl_add_u64 v[246:247], s[38:39], 0, v[130:131]
	global_load_lds_dwordx4 v[246:247], off
	s_waitcnt vmcnt(8) lgkmcnt(0)
	s_barrier
	v_mfma_f32_16x16x32_bf16 v[124:127], v[138:141], v[192:195], v[124:127]
	v_mfma_f32_16x16x32_bf16 v[116:119], v[150:153], v[192:195], v[116:119]
	v_mfma_f32_16x16x32_bf16 v[108:111], v[138:141], v[200:203], v[108:111]
	v_mfma_f32_16x16x32_bf16 v[100:103], v[150:153], v[200:203], v[100:103]
	v_mfma_f32_16x16x32_bf16 v[92:95], v[138:141], v[208:211], v[92:95]
	v_mfma_f32_16x16x32_bf16 v[84:87], v[150:153], v[208:211], v[84:87]
	v_mfma_f32_16x16x32_bf16 v[76:79], v[138:141], v[234:237], v[76:79]
	v_mfma_f32_16x16x32_bf16 v[68:71], v[150:153], v[234:237], v[68:71]
	v_mfma_f32_16x16x32_bf16 v[124:127], v[146:149], v[196:199], v[124:127]
	v_mfma_f32_16x16x32_bf16 v[116:119], v[154:157], v[196:199], v[116:119]
	v_mfma_f32_16x16x32_bf16 v[108:111], v[146:149], v[204:207], v[108:111]
	v_mfma_f32_16x16x32_bf16 v[100:103], v[154:157], v[204:207], v[100:103]
	v_mfma_f32_16x16x32_bf16 v[92:95], v[146:149], v[230:233], v[92:95]
	v_mfma_f32_16x16x32_bf16 v[84:87], v[154:157], v[230:233], v[84:87]
	v_mfma_f32_16x16x32_bf16 v[76:79], v[146:149], v[238:241], v[76:79]
	v_mfma_f32_16x16x32_bf16 v[68:71], v[154:157], v[238:241], v[68:71]
	v_mfma_f32_16x16x32_bf16 v[120:123], v[158:161], v[192:195], v[120:123]
	v_mfma_f32_16x16x32_bf16 v[112:115], v[184:187], v[192:195], v[112:115]
	v_mfma_f32_16x16x32_bf16 v[104:107], v[158:161], v[200:203], v[104:107]
	v_mfma_f32_16x16x32_bf16 v[96:99], v[184:187], v[200:203], v[96:99]
	v_mfma_f32_16x16x32_bf16 v[88:91], v[158:161], v[208:211], v[88:91]
	v_mfma_f32_16x16x32_bf16 v[80:83], v[184:187], v[208:211], v[80:83]
	v_mfma_f32_16x16x32_bf16 v[72:75], v[158:161], v[234:237], v[72:75]
	v_mfma_f32_16x16x32_bf16 v[64:67], v[184:187], v[234:237], v[64:67]
	v_mfma_f32_16x16x32_bf16 v[120:123], v[162:165], v[196:199], v[120:123]
	v_mfma_f32_16x16x32_bf16 v[112:115], v[188:191], v[196:199], v[112:115]
	v_mfma_f32_16x16x32_bf16 v[104:107], v[162:165], v[204:207], v[104:107]
	v_mfma_f32_16x16x32_bf16 v[96:99], v[188:191], v[204:207], v[96:99]
	v_mfma_f32_16x16x32_bf16 v[88:91], v[162:165], v[230:233], v[88:91]
	v_mfma_f32_16x16x32_bf16 v[80:83], v[188:191], v[230:233], v[80:83]
	v_mfma_f32_16x16x32_bf16 v[72:75], v[162:165], v[238:241], v[72:75]
	v_mfma_f32_16x16x32_bf16 v[64:67], v[188:191], v[238:241], v[64:67]
	s_barrier
; #define PG8_STAGE(bufoff, gbase, voff) do { _Pragma("unroll") for (int _i = 0; _i < 2; ++_i) \
;         __builtin_amdgcn_global_load_lds((const unsigned*)((const char*)(gbase) + (voff)[_i]), (LAS unsigned*)(lds + (bufoff) + ldsw + _i * 8192), 16, 0, 0); } while (0)
; #define PG8_LDA(dst, b, h) do { _Pragma("unroll") for (int m = 0; m < 4; ++m) _Pragma("unroll") for (int k = 0; k < 2; ++k) dst[m][k] = *(const LAS bf16x8*)(lds + PG8_SA(b, h) + aoff + m * 2048 + k * 1024); } while (0)
; #define PG8_LDB(dst, b, h) do { _Pragma("unroll") for (int n = 0; n < 2; ++n) _Pragma("unroll") for (int k = 0; k < 2; ++k) dst[n][k] = *(const LAS bf16x8*)(lds + PG8_SB(b, h) + boff + n * 2048 + k * 1024); } while (0)
; #define PG8_WAIT_V(n) asm volatile("s_waitcnt vmcnt(" #n ")" ::: "memory")
; template <class Epi>
; __device__ __forceinline__ void gemm_phase(LAS unsigned char* lds, const Gemm g, const StaticOrder& S, const Epi& E, const int tid) {
;     ...
;         for (int t = 0; t < nt; t += 2) {
;             const bool last = (t == nt - 2);
;             const char* a1 = cA + (size_t)(t + 1) * kstep;
;             const char* a2 = last ? nA : cA + (size_t)(t + 2) * kstep; const char* b2 = last ? nB : cB + (size_t)(t + 2) * kstep;
;             const char* a3 = a2 + kstep; const char* b3 = b2 + kstep;
;             PG8_LDB(B0, 0, 0); PG8_LDB(B1, 0, 1); PG8_SCHED; PG8_LDA(At, 0, 0); PG8_STAGE(PG8_SA(1, 1), a1 + hsA, voffA);
;             PG8_WAIT_V(8); PG8_WAIT_L(0); PG8_BAR; PG8_MMA(0, 0, At, B0); PG8_MMA(0, 1, At, B1); PG8_BAR; PG8_SCHED;
;             PG8_LDA(At, 0, 1); PG8_STAGE(PG8_SB(0, 0), b2, voffB); PG8_STAGE(PG8_SB(0, 1), b2 + hsB, voffB); PG8_STAGE(PG8_SA(0, 0), a2, voffA);
;             PG8_WAIT_V(8); PG8_WAIT_L(0); PG8_BAR; PG8_MMA(1, 0, At, B0); PG8_MMA(1, 1, At, B1); PG8_BAR; PG8_SCHED;
;             PG8_LDB(B0, 1, 0); PG8_LDB(B1, 1, 1); PG8_SCHED; PG8_LDA(At, 1, 0); PG8_STAGE(PG8_SA(0, 1), a2 + hsA, voffA);
;             PG8_WAIT_V(8); PG8_WAIT_L(0); PG8_BAR; PG8_MMA(0, 0, At, B0); PG8_MMA(0, 1, At, B1); PG8_BAR; PG8_SCHED;
;             PG8_LDA(At, 1, 1); PG8_STAGE(PG8_SB(1, 0), b3, voffB); PG8_STAGE(PG8_SB(1, 1), b3 + hsB, voffB); PG8_STAGE(PG8_SA(1, 0), a3, voffA);
;             PG8_WAIT_V(8); PG8_WAIT_L(0); PG8_BAR; PG8_MMA(1, 0, At, B0); PG8_MMA(1, 1, At, B1); PG8_BAR; PG8_SCHED;
;         }
;         if (wr == 0) PG8_BAR;
	s_add_i32 s24, s24, s27
	v_lshl_add_u64 v[166:167], v[166:167], 0, s[28:29]
	s_mov_b32 m0, s24
	ds_read_b128 v[192:195], v145 offset:49152
	ds_read_b128 v[196:199], v145 offset:50176
	ds_read_b128 v[200:203], v145 offset:51200
	ds_read_b128 v[204:207], v145 offset:52224
	ds_read_b128 v[208:211], v145 offset:53248
	ds_read_b128 v[230:233], v145 offset:54272
	ds_read_b128 v[234:237], v145 offset:55296
	ds_read_b128 v[238:241], v145 offset:56320
	global_load_lds_dwordx4 v[166:167], off
	s_add_i32 m0, s24, 0x2000
	s_add_u32 s0, s0, 0x80080
	v_lshl_add_u64 v[166:167], v[212:213], 0, s[28:29]
	s_addc_u32 s1, s1, 0
	s_add_i32 s24, s25, s27
	global_load_lds_dwordx4 v[166:167], off
	s_mov_b32 m0, s24
	v_lshl_add_u64 v[166:167], s[0:1], 0, v[168:169]
	global_load_lds_dwordx4 v[166:167], off
	s_add_i32 m0, s24, 0x2000
	v_lshl_add_u64 v[166:167], s[0:1], 0, v[132:133]
	global_load_lds_dwordx4 v[166:167], off
	s_mov_b32 m0, s46
	v_lshl_add_u64 v[166:167], v[242:243], 0, s[28:29]
	global_load_lds_dwordx4 v[166:167], off
	s_mov_b32 m0, s47
	v_lshl_add_u64 v[166:167], v[244:245], 0, s[28:29]
	global_load_lds_dwordx4 v[166:167], off
	s_waitcnt vmcnt(8) lgkmcnt(0)
	s_barrier
	v_mfma_f32_16x16x32_bf16 v[60:63], v[138:141], v[192:195], v[60:63]
	v_mfma_f32_16x16x32_bf16 v[52:55], v[150:153], v[192:195], v[52:55]
	v_mfma_f32_16x16x32_bf16 v[44:47], v[138:141], v[200:203], v[44:47]
	v_mfma_f32_16x16x32_bf16 v[36:39], v[150:153], v[200:203], v[36:39]
	v_mfma_f32_16x16x32_bf16 v[28:31], v[138:141], v[208:211], v[28:31]
	v_mfma_f32_16x16x32_bf16 v[20:23], v[150:153], v[208:211], v[20:23]
	v_mfma_f32_16x16x32_bf16 v[12:15], v[138:141], v[234:237], v[12:15]
	v_mfma_f32_16x16x32_bf16 v[4:7], v[150:153], v[234:237], v[4:7]
	v_mfma_f32_16x16x32_bf16 v[60:63], v[146:149], v[196:199], v[60:63]
	v_mfma_f32_16x16x32_bf16 v[52:55], v[154:157], v[196:199], v[52:55]
	v_mfma_f32_16x16x32_bf16 v[44:47], v[146:149], v[204:207], v[44:47]
	v_mfma_f32_16x16x32_bf16 v[36:39], v[154:157], v[204:207], v[36:39]
	v_mfma_f32_16x16x32_bf16 v[28:31], v[146:149], v[230:233], v[28:31]
	v_mfma_f32_16x16x32_bf16 v[20:23], v[154:157], v[230:233], v[20:23]
	v_mfma_f32_16x16x32_bf16 v[12:15], v[146:149], v[238:241], v[12:15]
	v_mfma_f32_16x16x32_bf16 v[4:7], v[154:157], v[238:241], v[4:7]
	v_mfma_f32_16x16x32_bf16 v[56:59], v[158:161], v[192:195], v[56:59]
	v_mfma_f32_16x16x32_bf16 v[48:51], v[184:187], v[192:195], v[48:51]
	v_mfma_f32_16x16x32_bf16 v[40:43], v[158:161], v[200:203], v[40:43]
	v_mfma_f32_16x16x32_bf16 v[32:35], v[184:187], v[200:203], v[32:35]
	v_mfma_f32_16x16x32_bf16 v[24:27], v[158:161], v[208:211], v[24:27]
	v_mfma_f32_16x16x32_bf16 v[16:19], v[184:187], v[208:211], v[16:19]
	v_mfma_f32_16x16x32_bf16 v[8:11], v[158:161], v[234:237], v[8:11]
	v_mfma_f32_16x16x32_bf16 v[0:3], v[184:187], v[234:237], v[0:3]
	v_mfma_f32_16x16x32_bf16 v[56:59], v[162:165], v[196:199], v[56:59]
	v_mfma_f32_16x16x32_bf16 v[48:51], v[188:191], v[196:199], v[48:51]
	v_mfma_f32_16x16x32_bf16 v[40:43], v[162:165], v[204:207], v[40:43]
	v_mfma_f32_16x16x32_bf16 v[32:35], v[188:191], v[204:207], v[32:35]
	v_mfma_f32_16x16x32_bf16 v[24:27], v[162:165], v[230:233], v[24:27]
	v_mfma_f32_16x16x32_bf16 v[16:19], v[188:191], v[230:233], v[16:19]
	v_mfma_f32_16x16x32_bf16 v[8:11], v[162:165], v[238:241], v[8:11]
	v_mfma_f32_16x16x32_bf16 v[0:3], v[188:191], v[238:241], v[0:3]
	s_barrier
	s_add_i32 s59, s59, 2
	s_add_u32 s34, s34, 0x100
	s_addc_u32 s35, s35, 0
	s_add_u32 s57, s57, 0x100
	s_addc_u32 s58, s58, 0
	s_cmp_gt_u32 s59, 29
	s_cbranch_scc0 .LBB0_161
	s_and_b64 vcc, exec, s[10:11]
	s_cbranch_vccz .LBB0_164
	s_barrier

; #define PG8_STAGE(bufoff, gbase, voff) do { _Pragma("unroll") for (int _i = 0; _i < 2; ++_i) \
;         __builtin_amdgcn_global_load_lds((const unsigned*)((const char*)(gbase) + (voff)[_i]), (LAS unsigned*)(lds + (bufoff) + ldsw + _i * 8192), 16, 0, 0); } while (0)
; #define PG8_LDA(dst, b, h) do { _Pragma("unroll") for (int m = 0; m < 4; ++m) _Pragma("unroll") for (int k = 0; k < 2; ++k) dst[m][k] = *(const LAS bf16x8*)(lds + PG8_SA(b, h) + aoff + m * 2048 + k * 1024); } while (0)
; #define PG8_LDB(dst, b, h) do { _Pragma("unroll") for (int n = 0; n < 2; ++n) _Pragma("unroll") for (int k = 0; k < 2; ++k) dst[n][k] = *(const LAS bf16x8*)(lds + PG8_SB(b, h) + boff + n * 2048 + k * 1024); } while (0)
; #define PG8_WAIT_V(n) asm volatile("s_waitcnt vmcnt(" #n ")" ::: "memory")
; #define PG8_WAIT_L(n) asm volatile("s_waitcnt lgkmcnt(" #n ")" ::: "memory")
; template <class Epi>
; __device__ __forceinline__ void gemm_phase(LAS unsigned char* lds, const Gemm g, const StaticOrder& S, const Epi& E, const int tid) {
;     ...
;         for (int t = 0; t < nt; t += 2) {
;             const bool last = (t == nt - 2);
;             const char* a1 = cA + (size_t)(t + 1) * kstep;
;             const char* a2 = last ? nA : cA + (size_t)(t + 2) * kstep; const char* b2 = last ? nB : cB + (size_t)(t + 2) * kstep;
;             const char* a3 = a2 + kstep; const char* b3 = b2 + kstep;
;             PG8_LDB(B0, 0, 0); PG8_LDB(B1, 0, 1); PG8_SCHED; PG8_LDA(At, 0, 0); PG8_STAGE(PG8_SA(1, 1), a1 + hsA, voffA);
;             PG8_WAIT_V(8); PG8_WAIT_L(0); PG8_BAR; PG8_MMA(0, 0, At, B0); PG8_MMA(0, 1, At, B1); PG8_BAR; PG8_SCHED;
;             PG8_LDA(At, 0, 1); PG8_STAGE(PG8_SB(0, 0), b2, voffB); PG8_STAGE(PG8_SB(0, 1), b2 + hsB, voffB); PG8_STAGE(PG8_SA(0, 0), a2, voffA);
;             PG8_WAIT_V(8); PG8_WAIT_L(0); PG8_BAR; PG8_MMA(1, 0, At, B0); PG8_MMA(1, 1, At, B1); PG8_BAR; PG8_SCHED;
;             PG8_LDB(B0, 1, 0); PG8_LDB(B1, 1, 1); PG8_SCHED; PG8_LDA(At, 1, 0); PG8_STAGE(PG8_SA(0, 1), a2 + hsA, voffA);
;             PG8_WAIT_V(8); PG8_WAIT_L(0); PG8_BAR; PG8_MMA(0, 0, At, B0); PG8_MMA(0, 1, At, B1); PG8_BAR; PG8_SCHED;
;             PG8_LDA(At, 1, 1); PG8_STAGE(PG8_SB(1, 0), b3, voffB); PG8_STAGE(PG8_SB(1, 1), b3 + hsB, voffB); PG8_STAGE(PG8_SA(1, 0), a3, voffA);
;             PG8_WAIT_V(8); PG8_WAIT_L(0); PG8_BAR; PG8_MMA(1, 0, At, B0); PG8_MMA(1, 1, At, B1); PG8_BAR; PG8_SCHED;
.Lgprio_b:
	s_add_u32 s0, s18, 0x100
	s_addc_u32 s1, s19, 0
	s_add_i32 s24, 0, 0x10000
	s_cmpk_eq_i32 s69, 0x54
	s_cselect_b32 s37, s15, s1
	s_cselect_b32 s36, s14, s0
	s_cselect_b32 s35, s17, s43
	s_cselect_b32 s34, s16, s42
	s_add_i32 s25, 0, 0x14000
	v_add_u32_e32 v152, s24, v193
	v_add_u32_e32 v170, s25, v193
	ds_read_b128 v[128:131], v152
	ds_read_b128 v[132:135], v152 offset:1024
	ds_read_b128 v[136:139], v152 offset:2048
	ds_read_b128 v[152:155], v152 offset:3072
	ds_read_b128 v[156:159], v170
	ds_read_b128 v[160:163], v170 offset:1024
	ds_read_b128 v[164:167], v170 offset:2048
	ds_read_b128 v[184:187], v170 offset:3072
	v_lshl_add_u64 v[212:213], s[18:19], 0, v[148:149]
	s_add_i32 m0, s44, 0xc000
	ds_read_b128 v[188:191], v198
	ds_read_b128 v[200:203], v198 offset:1024
	ds_read_b128 v[204:207], v198 offset:2048
	ds_read_b128 v[208:211], v198 offset:3072
	ds_read_b128 v[230:233], v198 offset:4096
	ds_read_b128 v[234:237], v198 offset:5120
	ds_read_b128 v[238:241], v198 offset:6144
	ds_read_b128 v[242:245], v198 offset:7168
	global_load_lds_dwordx4 v[212:213], off
	s_add_i32 m0, s44, 0xe000
	v_lshl_add_u64 v[212:213], s[18:19], 0, v[150:151]
	global_load_lds_dwordx4 v[212:213], off
	s_waitcnt vmcnt(8) lgkmcnt(0)
	s_barrier
	v_mfma_f32_16x16x32_bf16 v[124:127], v[128:131], v[188:191], 0
	v_mfma_f32_16x16x32_bf16 v[120:123], v[136:139], v[188:191], 0
	v_mfma_f32_16x16x32_bf16 v[116:119], v[128:131], v[204:207], 0
	v_mfma_f32_16x16x32_bf16 v[108:111], v[136:139], v[204:207], 0
	v_mfma_f32_16x16x32_bf16 v[92:95], v[128:131], v[230:233], 0
	v_mfma_f32_16x16x32_bf16 v[88:91], v[136:139], v[230:233], 0
	v_mfma_f32_16x16x32_bf16 v[80:83], v[128:131], v[238:241], 0
	v_mfma_f32_16x16x32_bf16 v[72:75], v[136:139], v[238:241], 0
	v_mfma_f32_16x16x32_bf16 v[124:127], v[132:135], v[200:203], v[124:127]
	v_mfma_f32_16x16x32_bf16 v[120:123], v[152:155], v[200:203], v[120:123]
	v_mfma_f32_16x16x32_bf16 v[116:119], v[132:135], v[208:211], v[116:119]
	v_mfma_f32_16x16x32_bf16 v[108:111], v[152:155], v[208:211], v[108:111]
	v_mfma_f32_16x16x32_bf16 v[92:95], v[132:135], v[234:237], v[92:95]
	v_mfma_f32_16x16x32_bf16 v[88:91], v[152:155], v[234:237], v[88:91]
	v_mfma_f32_16x16x32_bf16 v[80:83], v[132:135], v[242:245], v[80:83]
	v_mfma_f32_16x16x32_bf16 v[72:75], v[152:155], v[242:245], v[72:75]
	v_mfma_f32_16x16x32_bf16 v[112:115], v[156:159], v[188:191], 0
	v_mfma_f32_16x16x32_bf16 v[104:107], v[164:167], v[188:191], 0
	v_mfma_f32_16x16x32_bf16 v[100:103], v[156:159], v[204:207], 0
	v_mfma_f32_16x16x32_bf16 v[96:99], v[164:167], v[204:207], 0
	v_mfma_f32_16x16x32_bf16 v[84:87], v[156:159], v[230:233], 0
	v_mfma_f32_16x16x32_bf16 v[76:79], v[164:167], v[230:233], 0
	v_mfma_f32_16x16x32_bf16 v[68:71], v[156:159], v[238:241], 0
	v_mfma_f32_16x16x32_bf16 v[64:67], v[164:167], v[238:241], 0
	v_mfma_f32_16x16x32_bf16 v[112:115], v[160:163], v[200:203], v[112:115]
	v_mfma_f32_16x16x32_bf16 v[104:107], v[184:187], v[200:203], v[104:107]
	v_mfma_f32_16x16x32_bf16 v[100:103], v[160:163], v[208:211], v[100:103]
	v_mfma_f32_16x16x32_bf16 v[96:99], v[184:187], v[208:211], v[96:99]
	v_mfma_f32_16x16x32_bf16 v[84:87], v[160:163], v[234:237], v[84:87]
	v_mfma_f32_16x16x32_bf16 v[76:79], v[184:187], v[234:237], v[76:79]
	v_mfma_f32_16x16x32_bf16 v[68:71], v[160:163], v[242:245], v[68:71]
	v_mfma_f32_16x16x32_bf16 v[64:67], v[184:187], v[242:245], v[64:67]
	s_barrier
	s_add_i32 s18, s24, s39
	v_lshl_add_u64 v[212:213], s[34:35], 0, v[144:145]
	s_mov_b32 m0, s18
	ds_read_b128 v[188:191], v198 offset:16384
	ds_read_b128 v[200:203], v198 offset:17408
	ds_read_b128 v[204:207], v198 offset:18432
	ds_read_b128 v[208:211], v198 offset:19456
	ds_read_b128 v[230:233], v198 offset:20480
	ds_read_b128 v[234:237], v198 offset:21504
	ds_read_b128 v[238:241], v198 offset:22528
	ds_read_b128 v[242:245], v198 offset:23552
	global_load_lds_dwordx4 v[212:213], off
	s_add_i32 m0, s18, 0x2000
	s_add_u32 s18, s34, 0x160000
	v_lshl_add_u64 v[246:247], s[34:35], 0, v[140:141]
	s_addc_u32 s19, s35, 0
	s_add_i32 s24, s25, s39
	global_load_lds_dwordx4 v[246:247], off
	v_lshl_add_u64 v[248:249], s[18:19], 0, v[144:145]
	s_mov_b32 m0, s24
	v_lshl_add_u64 v[250:251], s[36:37], 0, v[142:143]
	global_load_lds_dwordx4 v[248:249], off
	s_add_i32 m0, s24, 0x2000
	v_lshl_add_u64 v[248:249], s[18:19], 0, v[140:141]
	global_load_lds_dwordx4 v[248:249], off
	s_mov_b32 m0, s44
	v_lshl_add_u64 v[248:249], s[36:37], 0, v[146:147]
	global_load_lds_dwordx4 v[248:249], off
	s_mov_b32 m0, s45
	s_nop 0
	global_load_lds_dwordx4 v[250:251], off
	s_waitcnt vmcnt(8) lgkmcnt(0)
	s_barrier
	v_mfma_f32_16x16x32_bf16 v[60:63], v[128:131], v[188:191], 0
	v_mfma_f32_16x16x32_bf16 v[56:59], v[136:139], v[188:191], 0
	v_mfma_f32_16x16x32_bf16 v[44:47], v[128:131], v[204:207], 0
	v_mfma_f32_16x16x32_bf16 v[40:43], v[136:139], v[204:207], 0
	v_mfma_f32_16x16x32_bf16 v[28:31], v[128:131], v[230:233], 0
	v_mfma_f32_16x16x32_bf16 v[24:27], v[136:139], v[230:233], 0
	v_mfma_f32_16x16x32_bf16 v[12:15], v[128:131], v[238:241], 0
	v_mfma_f32_16x16x32_bf16 v[8:11], v[136:139], v[238:241], 0
	v_mfma_f32_16x16x32_bf16 v[60:63], v[132:135], v[200:203], v[60:63]
	v_mfma_f32_16x16x32_bf16 v[56:59], v[152:155], v[200:203], v[56:59]
	v_mfma_f32_16x16x32_bf16 v[44:47], v[132:135], v[208:211], v[44:47]
	v_mfma_f32_16x16x32_bf16 v[40:43], v[152:155], v[208:211], v[40:43]
	v_mfma_f32_16x16x32_bf16 v[28:31], v[132:135], v[234:237], v[28:31]
	v_mfma_f32_16x16x32_bf16 v[24:27], v[152:155], v[234:237], v[24:27]
	v_mfma_f32_16x16x32_bf16 v[12:15], v[132:135], v[242:245], v[12:15]
	v_mfma_f32_16x16x32_bf16 v[8:11], v[152:155], v[242:245], v[8:11]
	v_mfma_f32_16x16x32_bf16 v[52:55], v[156:159], v[188:191], 0
	v_mfma_f32_16x16x32_bf16 v[48:51], v[164:167], v[188:191], 0
	v_mfma_f32_16x16x32_bf16 v[36:39], v[156:159], v[204:207], 0
	v_mfma_f32_16x16x32_bf16 v[32:35], v[164:167], v[204:207], 0
	v_mfma_f32_16x16x32_bf16 v[20:23], v[156:159], v[230:233], 0
	v_mfma_f32_16x16x32_bf16 v[16:19], v[164:167], v[230:233], 0
	v_mfma_f32_16x16x32_bf16 v[4:7], v[156:159], v[238:241], 0
	v_mfma_f32_16x16x32_bf16 v[0:3], v[164:167], v[238:241], 0
	v_mfma_f32_16x16x32_bf16 v[52:55], v[160:163], v[200:203], v[52:55]
	v_mfma_f32_16x16x32_bf16 v[48:51], v[184:187], v[200:203], v[48:51]
	v_mfma_f32_16x16x32_bf16 v[36:39], v[160:163], v[208:211], v[36:39]
	v_mfma_f32_16x16x32_bf16 v[32:35], v[184:187], v[208:211], v[32:35]
	v_mfma_f32_16x16x32_bf16 v[20:23], v[160:163], v[234:237], v[20:23]
	v_mfma_f32_16x16x32_bf16 v[16:19], v[184:187], v[234:237], v[16:19]
	v_mfma_f32_16x16x32_bf16 v[4:7], v[160:163], v[242:245], v[4:7]
	v_mfma_f32_16x16x32_bf16 v[0:3], v[184:187], v[242:245], v[0:3]
	s_barrier
; #define PG8_STAGE(bufoff, gbase, voff) do { _Pragma("unroll") for (int _i = 0; _i < 2; ++_i) \
;         __builtin_amdgcn_global_load_lds((const unsigned*)((const char*)(gbase) + (voff)[_i]), (LAS unsigned*)(lds + (bufoff) + ldsw + _i * 8192), 16, 0, 0); } while (0)
; #define PG8_LDA(dst, b, h) do { _Pragma("unroll") for (int m = 0; m < 4; ++m) _Pragma("unroll") for (int k = 0; k < 2; ++k) dst[m][k] = *(const LAS bf16x8*)(lds + PG8_SA(b, h) + aoff + m * 2048 + k * 1024); } while (0)
; #define PG8_LDB(dst, b, h) do { _Pragma("unroll") for (int n = 0; n < 2; ++n) _Pragma("unroll") for (int k = 0; k < 2; ++k) dst[n][k] = *(const LAS bf16x8*)(lds + PG8_SB(b, h) + boff + n * 2048 + k * 1024); } while (0)
; #define PG8_MMA(ai, bj, At, Bt) do { __builtin_amdgcn_s_setprio(1); _Pragma("unroll") for (int m = 0; m < 4; ++m) _Pragma("unroll") for (int n = 0; n < 2; ++n) _Pragma("unroll") for (int k = 0; k < 2; ++k) \
;         acc[ai][bj][m][n] = __builtin_amdgcn_mfma_f32_16x16x32_bf16(Bt[n][k], At[m][k], acc[ai][bj][m][n], 0, 0, 0); __builtin_amdgcn_s_setprio(0); } while (0)
; #define PG8_WAIT_V(n) asm volatile("s_waitcnt vmcnt(" #n ")" ::: "memory")
; #define PG8_WAIT_L(n) asm volatile("s_waitcnt lgkmcnt(" #n ")" ::: "memory")
; #define PG8_BAR __builtin_amdgcn_s_barrier()
; #define PG8_SCHED __builtin_amdgcn_sched_barrier(0)
; template <class Epi>
; __device__ __forceinline__ void gemm_phase(LAS unsigned char* lds, const Gemm g, const StaticOrder& S, const Epi& E, const int tid) {
;     ...
;             PG8_LDB(B0, 1, 0); PG8_LDB(B1, 1, 1); PG8_SCHED; PG8_LDA(At, 1, 0); PG8_STAGE(PG8_SA(0, 1), a2 + hsA, voffA);
;             PG8_WAIT_V(8); PG8_WAIT_L(0); PG8_BAR; PG8_MMA(0, 0, At, B0); PG8_MMA(0, 1, At, B1); PG8_BAR; PG8_SCHED;
;             PG8_LDA(At, 1, 1); PG8_STAGE(PG8_SB(1, 0), b3, voffB); PG8_STAGE(PG8_SB(1, 1), b3 + hsB, voffB); PG8_STAGE(PG8_SA(1, 0), a3, voffA);
;             PG8_WAIT_V(8); PG8_WAIT_L(0); PG8_BAR; PG8_MMA(1, 0, At, B0); PG8_MMA(1, 1, At, B1); PG8_BAR; PG8_SCHED;
	s_add_i32 s24, 0, 0x18000
	s_add_i32 s25, 0, 0x1c000
	v_add_u32_e32 v152, s24, v193
	v_add_u32_e32 v170, s25, v193
	ds_read_b128 v[128:131], v152
	ds_read_b128 v[132:135], v152 offset:1024
	ds_read_b128 v[136:139], v152 offset:2048
	ds_read_b128 v[152:155], v152 offset:3072
	ds_read_b128 v[156:159], v170
	ds_read_b128 v[160:163], v170 offset:1024
	ds_read_b128 v[164:167], v170 offset:2048
	ds_read_b128 v[184:187], v170 offset:3072
	s_add_u32 s18, s36, 0x160000
	s_addc_u32 s19, s37, 0
	s_mov_b32 m0, s46
	v_lshl_add_u64 v[170:171], s[18:19], 0, v[146:147]
	ds_read_b128 v[188:191], v198 offset:32768
	ds_read_b128 v[200:203], v198 offset:33792
	ds_read_b128 v[204:207], v198 offset:34816
	ds_read_b128 v[208:211], v198 offset:35840
	ds_read_b128 v[230:233], v198 offset:36864
	ds_read_b128 v[234:237], v198 offset:37888
	ds_read_b128 v[238:241], v198 offset:38912
	ds_read_b128 v[242:245], v198 offset:39936
	global_load_lds_dwordx4 v[170:171], off
	s_mov_b32 m0, s47
	v_lshl_add_u64 v[170:171], s[18:19], 0, v[142:143]
	global_load_lds_dwordx4 v[170:171], off
	s_waitcnt vmcnt(8) lgkmcnt(0)
	s_barrier
	v_mfma_f32_16x16x32_bf16 v[124:127], v[128:131], v[188:191], v[124:127]
	v_mfma_f32_16x16x32_bf16 v[120:123], v[136:139], v[188:191], v[120:123]
	v_mfma_f32_16x16x32_bf16 v[116:119], v[128:131], v[204:207], v[116:119]
	v_mfma_f32_16x16x32_bf16 v[108:111], v[136:139], v[204:207], v[108:111]
	v_mfma_f32_16x16x32_bf16 v[92:95], v[128:131], v[230:233], v[92:95]
	v_mfma_f32_16x16x32_bf16 v[88:91], v[136:139], v[230:233], v[88:91]
	v_mfma_f32_16x16x32_bf16 v[80:83], v[128:131], v[238:241], v[80:83]
	v_mfma_f32_16x16x32_bf16 v[72:75], v[136:139], v[238:241], v[72:75]
	v_mfma_f32_16x16x32_bf16 v[124:127], v[132:135], v[200:203], v[124:127]
	v_mfma_f32_16x16x32_bf16 v[120:123], v[152:155], v[200:203], v[120:123]
	v_mfma_f32_16x16x32_bf16 v[116:119], v[132:135], v[208:211], v[116:119]
	v_mfma_f32_16x16x32_bf16 v[108:111], v[152:155], v[208:211], v[108:111]
	v_mfma_f32_16x16x32_bf16 v[92:95], v[132:135], v[234:237], v[92:95]
	v_mfma_f32_16x16x32_bf16 v[88:91], v[152:155], v[234:237], v[88:91]
	v_mfma_f32_16x16x32_bf16 v[80:83], v[132:135], v[242:245], v[80:83]
	v_mfma_f32_16x16x32_bf16 v[72:75], v[152:155], v[242:245], v[72:75]
	v_mfma_f32_16x16x32_bf16 v[112:115], v[156:159], v[188:191], v[112:115]
	v_mfma_f32_16x16x32_bf16 v[104:107], v[164:167], v[188:191], v[104:107]
	v_mfma_f32_16x16x32_bf16 v[100:103], v[156:159], v[204:207], v[100:103]
	v_mfma_f32_16x16x32_bf16 v[96:99], v[164:167], v[204:207], v[96:99]
	v_mfma_f32_16x16x32_bf16 v[84:87], v[156:159], v[230:233], v[84:87]
	v_mfma_f32_16x16x32_bf16 v[76:79], v[164:167], v[230:233], v[76:79]
	v_mfma_f32_16x16x32_bf16 v[68:71], v[156:159], v[238:241], v[68:71]
	v_mfma_f32_16x16x32_bf16 v[64:67], v[164:167], v[238:241], v[64:67]
	v_mfma_f32_16x16x32_bf16 v[112:115], v[160:163], v[200:203], v[112:115]
	v_mfma_f32_16x16x32_bf16 v[104:107], v[184:187], v[200:203], v[104:107]
	v_mfma_f32_16x16x32_bf16 v[100:103], v[160:163], v[208:211], v[100:103]
	v_mfma_f32_16x16x32_bf16 v[96:99], v[184:187], v[208:211], v[96:99]
	v_mfma_f32_16x16x32_bf16 v[84:87], v[160:163], v[234:237], v[84:87]
	v_mfma_f32_16x16x32_bf16 v[76:79], v[184:187], v[234:237], v[76:79]
	v_mfma_f32_16x16x32_bf16 v[68:71], v[160:163], v[242:245], v[68:71]
	v_mfma_f32_16x16x32_bf16 v[64:67], v[184:187], v[242:245], v[64:67]
	s_barrier
	s_add_i32 s18, s24, s39
	v_lshl_add_u64 v[170:171], v[212:213], 0, s[28:29]
	s_mov_b32 m0, s18
	ds_read_b128 v[188:191], v198 offset:49152
	ds_read_b128 v[200:203], v198 offset:50176
	ds_read_b128 v[204:207], v198 offset:51200
	ds_read_b128 v[208:211], v198 offset:52224
	ds_read_b128 v[230:233], v198 offset:53248
	ds_read_b128 v[234:237], v198 offset:54272
	ds_read_b128 v[238:241], v198 offset:55296
	ds_read_b128 v[242:245], v198 offset:56320
	global_load_lds_dwordx4 v[170:171], off
	s_add_i32 m0, s18, 0x2000
	s_add_u32 s18, s34, 0x160080
	v_lshl_add_u64 v[170:171], v[246:247], 0, s[28:29]
	s_addc_u32 s19, s35, 0
	s_add_i32 s24, s25, s39
	global_load_lds_dwordx4 v[170:171], off
	s_mov_b32 m0, s24
	v_lshl_add_u64 v[170:171], s[18:19], 0, v[144:145]
	global_load_lds_dwordx4 v[170:171], off
	s_add_i32 m0, s24, 0x2000
	v_lshl_add_u64 v[170:171], s[18:19], 0, v[140:141]
	global_load_lds_dwordx4 v[170:171], off
	s_mov_b32 m0, s56
	v_lshl_add_u64 v[170:171], v[248:249], 0, s[28:29]
	global_load_lds_dwordx4 v[170:171], off
	s_mov_b32 m0, s57
	v_lshl_add_u64 v[170:171], v[250:251], 0, s[28:29]
	global_load_lds_dwordx4 v[170:171], off
	s_waitcnt vmcnt(8) lgkmcnt(0)
	s_barrier
	v_mfma_f32_16x16x32_bf16 v[60:63], v[128:131], v[188:191], v[60:63]
	v_mfma_f32_16x16x32_bf16 v[56:59], v[136:139], v[188:191], v[56:59]
	v_mfma_f32_16x16x32_bf16 v[44:47], v[128:131], v[204:207], v[44:47]
	v_mfma_f32_16x16x32_bf16 v[40:43], v[136:139], v[204:207], v[40:43]
	v_mfma_f32_16x16x32_bf16 v[28:31], v[128:131], v[230:233], v[28:31]
	v_mfma_f32_16x16x32_bf16 v[24:27], v[136:139], v[230:233], v[24:27]
	v_mfma_f32_16x16x32_bf16 v[12:15], v[128:131], v[238:241], v[12:15]
	v_mfma_f32_16x16x32_bf16 v[8:11], v[136:139], v[238:241], v[8:11]
	v_mfma_f32_16x16x32_bf16 v[60:63], v[132:135], v[200:203], v[60:63]
	v_mfma_f32_16x16x32_bf16 v[56:59], v[152:155], v[200:203], v[56:59]
	v_mfma_f32_16x16x32_bf16 v[44:47], v[132:135], v[208:211], v[44:47]
	v_mfma_f32_16x16x32_bf16 v[40:43], v[152:155], v[208:211], v[40:43]
	v_mfma_f32_16x16x32_bf16 v[28:31], v[132:135], v[234:237], v[28:31]
	v_mfma_f32_16x16x32_bf16 v[24:27], v[152:155], v[234:237], v[24:27]
	v_mfma_f32_16x16x32_bf16 v[12:15], v[132:135], v[242:245], v[12:15]
	v_mfma_f32_16x16x32_bf16 v[8:11], v[152:155], v[242:245], v[8:11]
	v_mfma_f32_16x16x32_bf16 v[52:55], v[156:159], v[188:191], v[52:55]
	v_mfma_f32_16x16x32_bf16 v[48:51], v[164:167], v[188:191], v[48:51]
	v_mfma_f32_16x16x32_bf16 v[36:39], v[156:159], v[204:207], v[36:39]
	v_mfma_f32_16x16x32_bf16 v[32:35], v[164:167], v[204:207], v[32:35]
	v_mfma_f32_16x16x32_bf16 v[20:23], v[156:159], v[230:233], v[20:23]
	v_mfma_f32_16x16x32_bf16 v[16:19], v[164:167], v[230:233], v[16:19]
	v_mfma_f32_16x16x32_bf16 v[4:7], v[156:159], v[238:241], v[4:7]
	v_mfma_f32_16x16x32_bf16 v[0:3], v[164:167], v[238:241], v[0:3]
	v_mfma_f32_16x16x32_bf16 v[52:55], v[160:163], v[200:203], v[52:55]
	v_mfma_f32_16x16x32_bf16 v[48:51], v[184:187], v[200:203], v[48:51]
	v_mfma_f32_16x16x32_bf16 v[36:39], v[160:163], v[208:211], v[36:39]
	v_mfma_f32_16x16x32_bf16 v[32:35], v[184:187], v[208:211], v[32:35]
	v_mfma_f32_16x16x32_bf16 v[20:23], v[160:163], v[234:237], v[20:23]
	v_mfma_f32_16x16x32_bf16 v[16:19], v[184:187], v[234:237], v[16:19]
	v_mfma_f32_16x16x32_bf16 v[4:7], v[160:163], v[242:245], v[4:7]
	v_mfma_f32_16x16x32_bf16 v[0:3], v[184:187], v[242:245], v[0:3]
	s_barrier
	s_add_i32 s69, s69, 2
	s_add_u32 s42, s42, 0x100
	s_addc_u32 s43, s43, 0
	s_cmpk_gt_u32 s69, 0x55
	s_mov_b64 s[18:19], s[0:1]
; #define PG8_STAGE(bufoff, gbase, voff) do { _Pragma("unroll") for (int _i = 0; _i < 2; ++_i) \
;         __builtin_amdgcn_global_load_lds((const unsigned*)((const char*)(gbase) + (voff)[_i]), (LAS unsigned*)(lds + (bufoff) + ldsw + _i * 8192), 16, 0, 0); } while (0)
; #define PG8_LDA(dst, b, h) do { _Pragma("unroll") for (int m = 0; m < 4; ++m) _Pragma("unroll") for (int k = 0; k < 2; ++k) dst[m][k] = *(const LAS bf16x8*)(lds + PG8_SA(b, h) + aoff + m * 2048 + k * 1024); } while (0)
; #define PG8_LDB(dst, b, h) do { _Pragma("unroll") for (int n = 0; n < 2; ++n) _Pragma("unroll") for (int k = 0; k < 2; ++k) dst[n][k] = *(const LAS bf16x8*)(lds + PG8_SB(b, h) + boff + n * 2048 + k * 1024); } while (0)
; #define PG8_MMA(ai, bj, At, Bt) do { __builtin_amdgcn_s_setprio(1); _Pragma("unroll") for (int m = 0; m < 4; ++m) _Pragma("unroll") for (int n = 0; n < 2; ++n) _Pragma("unroll") for (int k = 0; k < 2; ++k) \
;         acc[ai][bj][m][n] = __builtin_amdgcn_mfma_f32_16x16x32_bf16(Bt[n][k], At[m][k], acc[ai][bj][m][n], 0, 0, 0); __builtin_amdgcn_s_setprio(0); } while (0)
; #define PG8_WAIT_V(n) asm volatile("s_waitcnt vmcnt(" #n ")" ::: "memory")
; #define PG8_WAIT_L(n) asm volatile("s_waitcnt lgkmcnt(" #n ")" ::: "memory")
; #define PG8_BAR __builtin_amdgcn_s_barrier()
; #define PG8_SCHED __builtin_amdgcn_sched_barrier(0)
; template <class Epi>
; __device__ __forceinline__ void gemm_phase(LAS unsigned char* lds, const Gemm g, const StaticOrder& S, const Epi& E, const int tid) {
;     ...
;             const bool last = (t == nt - 2);
;             const char* a1 = cA + (size_t)(t + 1) * kstep;
;             const char* a2 = last ? nA : cA + (size_t)(t + 2) * kstep; const char* b2 = last ? nB : cB + (size_t)(t + 2) * kstep;
;             const char* a3 = a2 + kstep; const char* b3 = b2 + kstep;
;             PG8_LDB(B0, 0, 0); PG8_LDB(B1, 0, 1); PG8_SCHED; PG8_LDA(At, 0, 0); PG8_STAGE(PG8_SA(1, 1), a1 + hsA, voffA);
;             PG8_WAIT_V(8); PG8_WAIT_L(0); PG8_BAR; PG8_MMA(0, 0, At, B0); PG8_MMA(0, 1, At, B1); PG8_BAR; PG8_SCHED;
;             PG8_LDA(At, 0, 1); PG8_STAGE(PG8_SB(0, 0), b2, voffB); PG8_STAGE(PG8_SB(0, 1), b2 + hsB, voffB); PG8_STAGE(PG8_SA(0, 0), a2, voffA);
.LBB0_233:
	s_add_u32 s0, s18, 0x100
	s_addc_u32 s1, s19, 0
	s_add_i32 s24, 0, 0x10000
	s_cmpk_eq_i32 s69, 0x54
	s_cselect_b32 s37, s15, s1
	s_cselect_b32 s36, s14, s0
	s_cselect_b32 s35, s17, s43
	s_cselect_b32 s34, s16, s42
	s_add_i32 s25, 0, 0x14000
	v_add_u32_e32 v152, s24, v193
	v_add_u32_e32 v170, s25, v193
	ds_read_b128 v[128:131], v152
	ds_read_b128 v[132:135], v152 offset:1024
	ds_read_b128 v[136:139], v152 offset:2048
	ds_read_b128 v[152:155], v152 offset:3072
	ds_read_b128 v[156:159], v170
	ds_read_b128 v[160:163], v170 offset:1024
	ds_read_b128 v[164:167], v170 offset:2048
	ds_read_b128 v[184:187], v170 offset:3072
	v_lshl_add_u64 v[212:213], s[18:19], 0, v[148:149]
	s_add_i32 m0, s44, 0xc000
	ds_read_b128 v[188:191], v198
	ds_read_b128 v[200:203], v198 offset:1024
	ds_read_b128 v[204:207], v198 offset:2048
	ds_read_b128 v[208:211], v198 offset:3072
	ds_read_b128 v[230:233], v198 offset:4096
	ds_read_b128 v[234:237], v198 offset:5120
	ds_read_b128 v[238:241], v198 offset:6144
	ds_read_b128 v[242:245], v198 offset:7168
	global_load_lds_dwordx4 v[212:213], off
	s_add_i32 m0, s44, 0xe000
	v_lshl_add_u64 v[212:213], s[18:19], 0, v[150:151]
	global_load_lds_dwordx4 v[212:213], off
	s_waitcnt vmcnt(8) lgkmcnt(0)
	s_barrier
	v_mfma_f32_16x16x32_bf16 v[124:127], v[128:131], v[188:191], v[124:127]
	v_mfma_f32_16x16x32_bf16 v[120:123], v[136:139], v[188:191], v[120:123]
	v_mfma_f32_16x16x32_bf16 v[116:119], v[128:131], v[204:207], v[116:119]
	v_mfma_f32_16x16x32_bf16 v[108:111], v[136:139], v[204:207], v[108:111]
	v_mfma_f32_16x16x32_bf16 v[92:95], v[128:131], v[230:233], v[92:95]
	v_mfma_f32_16x16x32_bf16 v[88:91], v[136:139], v[230:233], v[88:91]
	v_mfma_f32_16x16x32_bf16 v[80:83], v[128:131], v[238:241], v[80:83]
	v_mfma_f32_16x16x32_bf16 v[72:75], v[136:139], v[238:241], v[72:75]
	v_mfma_f32_16x16x32_bf16 v[124:127], v[132:135], v[200:203], v[124:127]
	v_mfma_f32_16x16x32_bf16 v[120:123], v[152:155], v[200:203], v[120:123]
	v_mfma_f32_16x16x32_bf16 v[116:119], v[132:135], v[208:211], v[116:119]
	v_mfma_f32_16x16x32_bf16 v[108:111], v[152:155], v[208:211], v[108:111]
	v_mfma_f32_16x16x32_bf16 v[92:95], v[132:135], v[234:237], v[92:95]
	v_mfma_f32_16x16x32_bf16 v[88:91], v[152:155], v[234:237], v[88:91]
	v_mfma_f32_16x16x32_bf16 v[80:83], v[132:135], v[242:245], v[80:83]
	v_mfma_f32_16x16x32_bf16 v[72:75], v[152:155], v[242:245], v[72:75]
	v_mfma_f32_16x16x32_bf16 v[112:115], v[156:159], v[188:191], v[112:115]
	v_mfma_f32_16x16x32_bf16 v[104:107], v[164:167], v[188:191], v[104:107]
	v_mfma_f32_16x16x32_bf16 v[100:103], v[156:159], v[204:207], v[100:103]
	v_mfma_f32_16x16x32_bf16 v[96:99], v[164:167], v[204:207], v[96:99]
	v_mfma_f32_16x16x32_bf16 v[84:87], v[156:159], v[230:233], v[84:87]
	v_mfma_f32_16x16x32_bf16 v[76:79], v[164:167], v[230:233], v[76:79]
	v_mfma_f32_16x16x32_bf16 v[68:71], v[156:159], v[238:241], v[68:71]
	v_mfma_f32_16x16x32_bf16 v[64:67], v[164:167], v[238:241], v[64:67]
	v_mfma_f32_16x16x32_bf16 v[112:115], v[160:163], v[200:203], v[112:115]
	v_mfma_f32_16x16x32_bf16 v[104:107], v[184:187], v[200:203], v[104:107]
	v_mfma_f32_16x16x32_bf16 v[100:103], v[160:163], v[208:211], v[100:103]
	v_mfma_f32_16x16x32_bf16 v[96:99], v[184:187], v[208:211], v[96:99]
	v_mfma_f32_16x16x32_bf16 v[84:87], v[160:163], v[234:237], v[84:87]
	v_mfma_f32_16x16x32_bf16 v[76:79], v[184:187], v[234:237], v[76:79]
	v_mfma_f32_16x16x32_bf16 v[68:71], v[160:163], v[242:245], v[68:71]
	v_mfma_f32_16x16x32_bf16 v[64:67], v[184:187], v[242:245], v[64:67]
	s_barrier
	s_add_i32 s18, s24, s39
	v_lshl_add_u64 v[212:213], s[34:35], 0, v[144:145]
	s_mov_b32 m0, s18
	ds_read_b128 v[188:191], v198 offset:16384
	ds_read_b128 v[200:203], v198 offset:17408
	ds_read_b128 v[204:207], v198 offset:18432
	ds_read_b128 v[208:211], v198 offset:19456
	ds_read_b128 v[230:233], v198 offset:20480
	ds_read_b128 v[234:237], v198 offset:21504
	ds_read_b128 v[238:241], v198 offset:22528
	ds_read_b128 v[242:245], v198 offset:23552
	global_load_lds_dwordx4 v[212:213], off
	s_add_i32 m0, s18, 0x2000
	s_add_u32 s18, s34, 0x160000
	v_lshl_add_u64 v[246:247], s[34:35], 0, v[140:141]
	s_addc_u32 s19, s35, 0
	s_add_i32 s24, s25, s39
	global_load_lds_dwordx4 v[246:247], off
	v_lshl_add_u64 v[248:249], s[18:19], 0, v[144:145]
	s_mov_b32 m0, s24
	v_lshl_add_u64 v[250:251], s[36:37], 0, v[142:143]
	global_load_lds_dwordx4 v[248:249], off
	s_add_i32 m0, s24, 0x2000
	v_lshl_add_u64 v[248:249], s[18:19], 0, v[140:141]
	global_load_lds_dwordx4 v[248:249], off
	s_mov_b32 m0, s44
	v_lshl_add_u64 v[248:249], s[36:37], 0, v[146:147]
	global_load_lds_dwordx4 v[248:249], off
	s_mov_b32 m0, s45
	s_nop 0
	global_load_lds_dwordx4 v[250:251], off
	s_waitcnt vmcnt(8) lgkmcnt(0)
	s_barrier
; #define PG8_STAGE(bufoff, gbase, voff) do { _Pragma("unroll") for (int _i = 0; _i < 2; ++_i) \
;         __builtin_amdgcn_global_load_lds((const unsigned*)((const char*)(gbase) + (voff)[_i]), (LAS unsigned*)(lds + (bufoff) + ldsw + _i * 8192), 16, 0, 0); } while (0)
; #define PG8_LDA(dst, b, h) do { _Pragma("unroll") for (int m = 0; m < 4; ++m) _Pragma("unroll") for (int k = 0; k < 2; ++k) dst[m][k] = *(const LAS bf16x8*)(lds + PG8_SA(b, h) + aoff + m * 2048 + k * 1024); } while (0)
; #define PG8_LDB(dst, b, h) do { _Pragma("unroll") for (int n = 0; n < 2; ++n) _Pragma("unroll") for (int k = 0; k < 2; ++k) dst[n][k] = *(const LAS bf16x8*)(lds + PG8_SB(b, h) + boff + n * 2048 + k * 1024); } while (0)
; #define PG8_MMA(ai, bj, At, Bt) do { __builtin_amdgcn_s_setprio(1); _Pragma("unroll") for (int m = 0; m < 4; ++m) _Pragma("unroll") for (int n = 0; n < 2; ++n) _Pragma("unroll") for (int k = 0; k < 2; ++k) \
;         acc[ai][bj][m][n] = __builtin_amdgcn_mfma_f32_16x16x32_bf16(Bt[n][k], At[m][k], acc[ai][bj][m][n], 0, 0, 0); __builtin_amdgcn_s_setprio(0); } while (0)
; #define PG8_WAIT_V(n) asm volatile("s_waitcnt vmcnt(" #n ")" ::: "memory")
; #define PG8_WAIT_L(n) asm volatile("s_waitcnt lgkmcnt(" #n ")" ::: "memory")
; #define PG8_BAR __builtin_amdgcn_s_barrier()
; #define PG8_SCHED __builtin_amdgcn_sched_barrier(0)
; template <class Epi>
; __device__ __forceinline__ void gemm_phase(LAS unsigned char* lds, const Gemm g, const StaticOrder& S, const Epi& E, const int tid) {
;     ...
;             PG8_WAIT_V(8); PG8_WAIT_L(0); PG8_BAR; PG8_MMA(1, 0, At, B0); PG8_MMA(1, 1, At, B1); PG8_BAR; PG8_SCHED;
;             PG8_LDB(B0, 1, 0); PG8_LDB(B1, 1, 1); PG8_SCHED; PG8_LDA(At, 1, 0); PG8_STAGE(PG8_SA(0, 1), a2 + hsA, voffA);
;             PG8_WAIT_V(8); PG8_WAIT_L(0); PG8_BAR; PG8_MMA(0, 0, At, B0); PG8_MMA(0, 1, At, B1); PG8_BAR; PG8_SCHED;
	v_mfma_f32_16x16x32_bf16 v[60:63], v[128:131], v[188:191], v[60:63]
	v_mfma_f32_16x16x32_bf16 v[56:59], v[136:139], v[188:191], v[56:59]
	v_mfma_f32_16x16x32_bf16 v[44:47], v[128:131], v[204:207], v[44:47]
	v_mfma_f32_16x16x32_bf16 v[40:43], v[136:139], v[204:207], v[40:43]
	v_mfma_f32_16x16x32_bf16 v[28:31], v[128:131], v[230:233], v[28:31]
	v_mfma_f32_16x16x32_bf16 v[24:27], v[136:139], v[230:233], v[24:27]
	v_mfma_f32_16x16x32_bf16 v[12:15], v[128:131], v[238:241], v[12:15]
	v_mfma_f32_16x16x32_bf16 v[8:11], v[136:139], v[238:241], v[8:11]
	v_mfma_f32_16x16x32_bf16 v[60:63], v[132:135], v[200:203], v[60:63]
	v_mfma_f32_16x16x32_bf16 v[56:59], v[152:155], v[200:203], v[56:59]
	v_mfma_f32_16x16x32_bf16 v[44:47], v[132:135], v[208:211], v[44:47]
	v_mfma_f32_16x16x32_bf16 v[40:43], v[152:155], v[208:211], v[40:43]
	v_mfma_f32_16x16x32_bf16 v[28:31], v[132:135], v[234:237], v[28:31]
	v_mfma_f32_16x16x32_bf16 v[24:27], v[152:155], v[234:237], v[24:27]
	v_mfma_f32_16x16x32_bf16 v[12:15], v[132:135], v[242:245], v[12:15]
	v_mfma_f32_16x16x32_bf16 v[8:11], v[152:155], v[242:245], v[8:11]
	v_mfma_f32_16x16x32_bf16 v[52:55], v[156:159], v[188:191], v[52:55]
	v_mfma_f32_16x16x32_bf16 v[48:51], v[164:167], v[188:191], v[48:51]
	v_mfma_f32_16x16x32_bf16 v[36:39], v[156:159], v[204:207], v[36:39]
	v_mfma_f32_16x16x32_bf16 v[32:35], v[164:167], v[204:207], v[32:35]
	v_mfma_f32_16x16x32_bf16 v[20:23], v[156:159], v[230:233], v[20:23]
	v_mfma_f32_16x16x32_bf16 v[16:19], v[164:167], v[230:233], v[16:19]
	v_mfma_f32_16x16x32_bf16 v[4:7], v[156:159], v[238:241], v[4:7]
	v_mfma_f32_16x16x32_bf16 v[0:3], v[164:167], v[238:241], v[0:3]
	v_mfma_f32_16x16x32_bf16 v[52:55], v[160:163], v[200:203], v[52:55]
	v_mfma_f32_16x16x32_bf16 v[48:51], v[184:187], v[200:203], v[48:51]
	v_mfma_f32_16x16x32_bf16 v[36:39], v[160:163], v[208:211], v[36:39]
	v_mfma_f32_16x16x32_bf16 v[32:35], v[184:187], v[208:211], v[32:35]
	v_mfma_f32_16x16x32_bf16 v[20:23], v[160:163], v[234:237], v[20:23]
	v_mfma_f32_16x16x32_bf16 v[16:19], v[184:187], v[234:237], v[16:19]
	v_mfma_f32_16x16x32_bf16 v[4:7], v[160:163], v[242:245], v[4:7]
	v_mfma_f32_16x16x32_bf16 v[0:3], v[184:187], v[242:245], v[0:3]
	s_barrier
	s_add_i32 s24, 0, 0x18000
	s_add_i32 s25, 0, 0x1c000
	v_add_u32_e32 v152, s24, v193
	v_add_u32_e32 v170, s25, v193
	ds_read_b128 v[128:131], v152
	ds_read_b128 v[132:135], v152 offset:1024
	ds_read_b128 v[136:139], v152 offset:2048
	ds_read_b128 v[152:155], v152 offset:3072
	ds_read_b128 v[156:159], v170
	ds_read_b128 v[160:163], v170 offset:1024
	ds_read_b128 v[164:167], v170 offset:2048
	ds_read_b128 v[184:187], v170 offset:3072
	s_add_u32 s18, s36, 0x160000
	s_addc_u32 s19, s37, 0
	s_mov_b32 m0, s46
	v_lshl_add_u64 v[170:171], s[18:19], 0, v[146:147]
	ds_read_b128 v[188:191], v198 offset:32768
	ds_read_b128 v[200:203], v198 offset:33792
	ds_read_b128 v[204:207], v198 offset:34816
	ds_read_b128 v[208:211], v198 offset:35840
	ds_read_b128 v[230:233], v198 offset:36864
	ds_read_b128 v[234:237], v198 offset:37888
	ds_read_b128 v[238:241], v198 offset:38912
	ds_read_b128 v[242:245], v198 offset:39936
	global_load_lds_dwordx4 v[170:171], off
	s_mov_b32 m0, s47
	v_lshl_add_u64 v[170:171], s[18:19], 0, v[142:143]
	global_load_lds_dwordx4 v[170:171], off
	s_waitcnt vmcnt(8) lgkmcnt(0)
	s_barrier
	v_mfma_f32_16x16x32_bf16 v[124:127], v[128:131], v[188:191], v[124:127]
	v_mfma_f32_16x16x32_bf16 v[120:123], v[136:139], v[188:191], v[120:123]
	v_mfma_f32_16x16x32_bf16 v[116:119], v[128:131], v[204:207], v[116:119]
	v_mfma_f32_16x16x32_bf16 v[108:111], v[136:139], v[204:207], v[108:111]
	v_mfma_f32_16x16x32_bf16 v[92:95], v[128:131], v[230:233], v[92:95]
	v_mfma_f32_16x16x32_bf16 v[88:91], v[136:139], v[230:233], v[88:91]
	v_mfma_f32_16x16x32_bf16 v[80:83], v[128:131], v[238:241], v[80:83]
	v_mfma_f32_16x16x32_bf16 v[72:75], v[136:139], v[238:241], v[72:75]
	v_mfma_f32_16x16x32_bf16 v[124:127], v[132:135], v[200:203], v[124:127]
	v_mfma_f32_16x16x32_bf16 v[120:123], v[152:155], v[200:203], v[120:123]
	v_mfma_f32_16x16x32_bf16 v[116:119], v[132:135], v[208:211], v[116:119]
	v_mfma_f32_16x16x32_bf16 v[108:111], v[152:155], v[208:211], v[108:111]
	v_mfma_f32_16x16x32_bf16 v[92:95], v[132:135], v[234:237], v[92:95]
	v_mfma_f32_16x16x32_bf16 v[88:91], v[152:155], v[234:237], v[88:91]
	v_mfma_f32_16x16x32_bf16 v[80:83], v[132:135], v[242:245], v[80:83]
	v_mfma_f32_16x16x32_bf16 v[72:75], v[152:155], v[242:245], v[72:75]
	v_mfma_f32_16x16x32_bf16 v[112:115], v[156:159], v[188:191], v[112:115]
	v_mfma_f32_16x16x32_bf16 v[104:107], v[164:167], v[188:191], v[104:107]
	v_mfma_f32_16x16x32_bf16 v[100:103], v[156:159], v[204:207], v[100:103]
	v_mfma_f32_16x16x32_bf16 v[96:99], v[164:167], v[204:207], v[96:99]
	v_mfma_f32_16x16x32_bf16 v[84:87], v[156:159], v[230:233], v[84:87]
	v_mfma_f32_16x16x32_bf16 v[76:79], v[164:167], v[230:233], v[76:79]
	v_mfma_f32_16x16x32_bf16 v[68:71], v[156:159], v[238:241], v[68:71]
	v_mfma_f32_16x16x32_bf16 v[64:67], v[164:167], v[238:241], v[64:67]
	v_mfma_f32_16x16x32_bf16 v[112:115], v[160:163], v[200:203], v[112:115]
	v_mfma_f32_16x16x32_bf16 v[104:107], v[184:187], v[200:203], v[104:107]
	v_mfma_f32_16x16x32_bf16 v[100:103], v[160:163], v[208:211], v[100:103]
	v_mfma_f32_16x16x32_bf16 v[96:99], v[184:187], v[208:211], v[96:99]
	v_mfma_f32_16x16x32_bf16 v[84:87], v[160:163], v[234:237], v[84:87]
	v_mfma_f32_16x16x32_bf16 v[76:79], v[184:187], v[234:237], v[76:79]
	v_mfma_f32_16x16x32_bf16 v[68:71], v[160:163], v[242:245], v[68:71]
	v_mfma_f32_16x16x32_bf16 v[64:67], v[184:187], v[242:245], v[64:67]
	s_barrier
; #define PG8_STAGE(bufoff, gbase, voff) do { _Pragma("unroll") for (int _i = 0; _i < 2; ++_i) \
;         __builtin_amdgcn_global_load_lds((const unsigned*)((const char*)(gbase) + (voff)[_i]), (LAS unsigned*)(lds + (bufoff) + ldsw + _i * 8192), 16, 0, 0); } while (0)
; #define PG8_LDA(dst, b, h) do { _Pragma("unroll") for (int m = 0; m < 4; ++m) _Pragma("unroll") for (int k = 0; k < 2; ++k) dst[m][k] = *(const LAS bf16x8*)(lds + PG8_SA(b, h) + aoff + m * 2048 + k * 1024); } while (0)
; #define PG8_MMA(ai, bj, At, Bt) do { __builtin_amdgcn_s_setprio(1); _Pragma("unroll") for (int m = 0; m < 4; ++m) _Pragma("unroll") for (int n = 0; n < 2; ++n) _Pragma("unroll") for (int k = 0; k < 2; ++k) \
;         acc[ai][bj][m][n] = __builtin_amdgcn_mfma_f32_16x16x32_bf16(Bt[n][k], At[m][k], acc[ai][bj][m][n], 0, 0, 0); __builtin_amdgcn_s_setprio(0); } while (0)
; #define PG8_WAIT_V(n) asm volatile("s_waitcnt vmcnt(" #n ")" ::: "memory")
; #define PG8_WAIT_L(n) asm volatile("s_waitcnt lgkmcnt(" #n ")" ::: "memory")
; #define PG8_BAR __builtin_amdgcn_s_barrier()
; #define PG8_SCHED __builtin_amdgcn_sched_barrier(0)
; template <class Epi>
; __device__ __forceinline__ void gemm_phase(LAS unsigned char* lds, const Gemm g, const StaticOrder& S, const Epi& E, const int tid) {
;     ...
;             PG8_LDA(At, 1, 1); PG8_STAGE(PG8_SB(1, 0), b3, voffB); PG8_STAGE(PG8_SB(1, 1), b3 + hsB, voffB); PG8_STAGE(PG8_SA(1, 0), a3, voffA);
;             PG8_WAIT_V(8); PG8_WAIT_L(0); PG8_BAR; PG8_MMA(1, 0, At, B0); PG8_MMA(1, 1, At, B1); PG8_BAR; PG8_SCHED;
;         }
;         if (wr == 0) PG8_BAR;
	s_add_i32 s18, s24, s39
	v_lshl_add_u64 v[170:171], v[212:213], 0, s[28:29]
	s_mov_b32 m0, s18
	ds_read_b128 v[188:191], v198 offset:49152
	ds_read_b128 v[200:203], v198 offset:50176
	ds_read_b128 v[204:207], v198 offset:51200
	ds_read_b128 v[208:211], v198 offset:52224
	ds_read_b128 v[230:233], v198 offset:53248
	ds_read_b128 v[234:237], v198 offset:54272
	ds_read_b128 v[238:241], v198 offset:55296
	ds_read_b128 v[242:245], v198 offset:56320
	global_load_lds_dwordx4 v[170:171], off
	s_add_i32 m0, s18, 0x2000
	s_add_u32 s18, s34, 0x160080
	v_lshl_add_u64 v[170:171], v[246:247], 0, s[28:29]
	s_addc_u32 s19, s35, 0
	s_add_i32 s24, s25, s39
	global_load_lds_dwordx4 v[170:171], off
	s_mov_b32 m0, s24
	v_lshl_add_u64 v[170:171], s[18:19], 0, v[144:145]
	global_load_lds_dwordx4 v[170:171], off
	s_add_i32 m0, s24, 0x2000
	v_lshl_add_u64 v[170:171], s[18:19], 0, v[140:141]
	global_load_lds_dwordx4 v[170:171], off
	s_mov_b32 m0, s56
	v_lshl_add_u64 v[170:171], v[248:249], 0, s[28:29]
	global_load_lds_dwordx4 v[170:171], off
	s_mov_b32 m0, s57
	v_lshl_add_u64 v[170:171], v[250:251], 0, s[28:29]
	global_load_lds_dwordx4 v[170:171], off
	s_waitcnt vmcnt(8) lgkmcnt(0)
	s_barrier
	v_mfma_f32_16x16x32_bf16 v[60:63], v[128:131], v[188:191], v[60:63]
	v_mfma_f32_16x16x32_bf16 v[56:59], v[136:139], v[188:191], v[56:59]
	v_mfma_f32_16x16x32_bf16 v[44:47], v[128:131], v[204:207], v[44:47]
	v_mfma_f32_16x16x32_bf16 v[40:43], v[136:139], v[204:207], v[40:43]
	v_mfma_f32_16x16x32_bf16 v[28:31], v[128:131], v[230:233], v[28:31]
	v_mfma_f32_16x16x32_bf16 v[24:27], v[136:139], v[230:233], v[24:27]
	v_mfma_f32_16x16x32_bf16 v[12:15], v[128:131], v[238:241], v[12:15]
	v_mfma_f32_16x16x32_bf16 v[8:11], v[136:139], v[238:241], v[8:11]
	v_mfma_f32_16x16x32_bf16 v[60:63], v[132:135], v[200:203], v[60:63]
	v_mfma_f32_16x16x32_bf16 v[56:59], v[152:155], v[200:203], v[56:59]
	v_mfma_f32_16x16x32_bf16 v[44:47], v[132:135], v[208:211], v[44:47]
	v_mfma_f32_16x16x32_bf16 v[40:43], v[152:155], v[208:211], v[40:43]
	v_mfma_f32_16x16x32_bf16 v[28:31], v[132:135], v[234:237], v[28:31]
	v_mfma_f32_16x16x32_bf16 v[24:27], v[152:155], v[234:237], v[24:27]
	v_mfma_f32_16x16x32_bf16 v[12:15], v[132:135], v[242:245], v[12:15]
	v_mfma_f32_16x16x32_bf16 v[8:11], v[152:155], v[242:245], v[8:11]
	v_mfma_f32_16x16x32_bf16 v[52:55], v[156:159], v[188:191], v[52:55]
	v_mfma_f32_16x16x32_bf16 v[48:51], v[164:167], v[188:191], v[48:51]
	v_mfma_f32_16x16x32_bf16 v[36:39], v[156:159], v[204:207], v[36:39]
	v_mfma_f32_16x16x32_bf16 v[32:35], v[164:167], v[204:207], v[32:35]
	v_mfma_f32_16x16x32_bf16 v[20:23], v[156:159], v[230:233], v[20:23]
	v_mfma_f32_16x16x32_bf16 v[16:19], v[164:167], v[230:233], v[16:19]
	v_mfma_f32_16x16x32_bf16 v[4:7], v[156:159], v[238:241], v[4:7]
	v_mfma_f32_16x16x32_bf16 v[0:3], v[164:167], v[238:241], v[0:3]
	v_mfma_f32_16x16x32_bf16 v[52:55], v[160:163], v[200:203], v[52:55]
	v_mfma_f32_16x16x32_bf16 v[48:51], v[184:187], v[200:203], v[48:51]
	v_mfma_f32_16x16x32_bf16 v[36:39], v[160:163], v[208:211], v[36:39]
	v_mfma_f32_16x16x32_bf16 v[32:35], v[184:187], v[208:211], v[32:35]
	v_mfma_f32_16x16x32_bf16 v[20:23], v[160:163], v[234:237], v[20:23]
	v_mfma_f32_16x16x32_bf16 v[16:19], v[184:187], v[234:237], v[16:19]
	v_mfma_f32_16x16x32_bf16 v[4:7], v[160:163], v[242:245], v[4:7]
	v_mfma_f32_16x16x32_bf16 v[0:3], v[184:187], v[242:245], v[0:3]
	s_barrier
	s_add_i32 s69, s69, 2
	s_add_u32 s42, s42, 0x100
	s_addc_u32 s43, s43, 0
	s_cmpk_gt_u32 s69, 0x55
	s_mov_b64 s[18:19], s[0:1]
	s_cbranch_scc0 .LBB0_233
	s_and_b64 vcc, exec, s[10:11]
	s_cbranch_vccz .LBB0_236
	s_barrier

; #define PG8_STAGE(bufoff, gbase, voff) do { _Pragma("unroll") for (int _i = 0; _i < 2; ++_i) \
;         __builtin_amdgcn_global_load_lds((const unsigned*)((const char*)(gbase) + (voff)[_i]), (LAS unsigned*)(lds + (bufoff) + ldsw + _i * 8192), 16, 0, 0); } while (0)
; #define PG8_LDA(dst, b, h) do { _Pragma("unroll") for (int m = 0; m < 4; ++m) _Pragma("unroll") for (int k = 0; k < 2; ++k) dst[m][k] = *(const LAS bf16x8*)(lds + PG8_SA(b, h) + aoff + m * 2048 + k * 1024); } while (0)
; #define PG8_LDB(dst, b, h) do { _Pragma("unroll") for (int n = 0; n < 2; ++n) _Pragma("unroll") for (int k = 0; k < 2; ++k) dst[n][k] = *(const LAS bf16x8*)(lds + PG8_SB(b, h) + boff + n * 2048 + k * 1024); } while (0)
; #define PG8_MMA(ai, bj, At, Bt) do { __builtin_amdgcn_s_setprio(1); _Pragma("unroll") for (int m = 0; m < 4; ++m) _Pragma("unroll") for (int n = 0; n < 2; ++n) _Pragma("unroll") for (int k = 0; k < 2; ++k) \
;         acc[ai][bj][m][n] = __builtin_amdgcn_mfma_f32_16x16x32_bf16(Bt[n][k], At[m][k], acc[ai][bj][m][n], 0, 0, 0); __builtin_amdgcn_s_setprio(0); } while (0)
; #define PG8_WAIT_V(n) asm volatile("s_waitcnt vmcnt(" #n ")" ::: "memory")
; #define PG8_WAIT_L(n) asm volatile("s_waitcnt lgkmcnt(" #n ")" ::: "memory")
; #define PG8_BAR __builtin_amdgcn_s_barrier()
; #define PG8_SCHED __builtin_amdgcn_sched_barrier(0)
; template <class Epi>
; __device__ __forceinline__ void gemm_phase(LAS unsigned char* lds, const Gemm g, const StaticOrder& S, const Epi& E, const int tid) {
;     ...
;             const bool last = (t == nt - 2);
;             const char* a1 = cA + (size_t)(t + 1) * kstep;
;             const char* a2 = last ? nA : cA + (size_t)(t + 2) * kstep; const char* b2 = last ? nB : cB + (size_t)(t + 2) * kstep;
;             const char* a3 = a2 + kstep; const char* b3 = b2 + kstep;
;             PG8_LDB(B0, 0, 0); PG8_LDB(B1, 0, 1); PG8_SCHED; PG8_LDA(At, 0, 0); PG8_STAGE(PG8_SA(1, 1), a1 + hsA, voffA);
;             PG8_WAIT_V(8); PG8_WAIT_L(0); PG8_BAR; PG8_MMA(0, 0, At, B0); PG8_MMA(0, 1, At, B1); PG8_BAR; PG8_SCHED;
;             PG8_LDA(At, 0, 1); PG8_STAGE(PG8_SB(0, 0), b2, voffB); PG8_STAGE(PG8_SB(0, 1), b2 + hsB, voffB); PG8_STAGE(PG8_SA(0, 0), a2, voffA);
;             PG8_WAIT_V(8); PG8_WAIT_L(0); PG8_BAR; PG8_MMA(1, 0, At, B0); PG8_MMA(1, 1, At, B1); PG8_BAR; PG8_SCHED;
.Lgprio_c:
	s_add_u32 s0, s36, 0xfff80080
	s_addc_u32 s1, s37, -1
	s_add_i32 s24, 0, 0x10000
	s_cmp_eq_u32 vcc_hi, 28
	s_cselect_b32 s43, s10, s1
	s_cselect_b32 s42, s11, s0
	v_add_u32_e32 v143, s24, v163
	s_cselect_b32 s1, s47, vcc_lo
	s_cselect_b32 s0, s49, s69
	s_add_i32 s55, 0, 0x14000
	ds_read_b128 v[144:147], v143
	ds_read_b128 v[148:151], v143 offset:1024
	ds_read_b128 v[152:155], v143 offset:2048
	ds_read_b128 v[156:159], v143 offset:3072
	v_add_u32_e32 v143, s55, v163
	ds_read_b128 v[184:187], v143
	ds_read_b128 v[188:191], v143 offset:1024
	ds_read_b128 v[192:195], v143 offset:2048
	ds_read_b128 v[196:199], v143 offset:3072
	v_lshl_add_u64 v[160:161], s[36:37], 0, v[138:139]
	s_add_i32 m0, s58, 0xc000
	ds_read_b128 v[200:203], v165
	ds_read_b128 v[204:207], v165 offset:1024
	ds_read_b128 v[208:211], v165 offset:2048
	ds_read_b128 v[232:235], v165 offset:3072
	ds_read_b128 v[236:239], v165 offset:4096
	ds_read_b128 v[240:243], v165 offset:5120
	ds_read_b128 v[244:247], v165 offset:6144
	ds_read_b128 v[248:251], v165 offset:7168
	global_load_lds_dwordx4 v[160:161], off
	s_add_i32 m0, s58, 0xe000
	v_lshl_add_u64 v[160:161], s[36:37], 0, v[140:141]
	global_load_lds_dwordx4 v[160:161], off
	s_waitcnt vmcnt(8) lgkmcnt(0)
	s_barrier
	v_mfma_f32_16x16x32_bf16 v[124:127], v[144:147], v[200:203], 0
	v_mfma_f32_16x16x32_bf16 v[120:123], v[152:155], v[200:203], 0
	v_mfma_f32_16x16x32_bf16 v[108:111], v[144:147], v[208:211], 0
	v_mfma_f32_16x16x32_bf16 v[104:107], v[152:155], v[208:211], 0
	v_mfma_f32_16x16x32_bf16 v[92:95], v[144:147], v[236:239], 0
	v_mfma_f32_16x16x32_bf16 v[88:91], v[152:155], v[236:239], 0
	v_mfma_f32_16x16x32_bf16 v[76:79], v[144:147], v[244:247], 0
	v_mfma_f32_16x16x32_bf16 v[72:75], v[152:155], v[244:247], 0
	v_mfma_f32_16x16x32_bf16 v[124:127], v[148:151], v[204:207], v[124:127]
	v_mfma_f32_16x16x32_bf16 v[120:123], v[156:159], v[204:207], v[120:123]
	v_mfma_f32_16x16x32_bf16 v[108:111], v[148:151], v[232:235], v[108:111]
	v_mfma_f32_16x16x32_bf16 v[104:107], v[156:159], v[232:235], v[104:107]
	v_mfma_f32_16x16x32_bf16 v[92:95], v[148:151], v[240:243], v[92:95]
	v_mfma_f32_16x16x32_bf16 v[88:91], v[156:159], v[240:243], v[88:91]
	v_mfma_f32_16x16x32_bf16 v[76:79], v[148:151], v[248:251], v[76:79]
	v_mfma_f32_16x16x32_bf16 v[72:75], v[156:159], v[248:251], v[72:75]
	v_mfma_f32_16x16x32_bf16 v[116:119], v[184:187], v[200:203], 0
	v_mfma_f32_16x16x32_bf16 v[112:115], v[192:195], v[200:203], 0
	v_mfma_f32_16x16x32_bf16 v[100:103], v[184:187], v[208:211], 0
	v_mfma_f32_16x16x32_bf16 v[96:99], v[192:195], v[208:211], 0
	v_mfma_f32_16x16x32_bf16 v[84:87], v[184:187], v[236:239], 0
	v_mfma_f32_16x16x32_bf16 v[80:83], v[192:195], v[236:239], 0
	v_mfma_f32_16x16x32_bf16 v[68:71], v[184:187], v[244:247], 0
	v_mfma_f32_16x16x32_bf16 v[64:67], v[192:195], v[244:247], 0
	v_mfma_f32_16x16x32_bf16 v[116:119], v[188:191], v[204:207], v[116:119]
	v_mfma_f32_16x16x32_bf16 v[112:115], v[196:199], v[204:207], v[112:115]
	v_mfma_f32_16x16x32_bf16 v[100:103], v[188:191], v[232:235], v[100:103]
	v_mfma_f32_16x16x32_bf16 v[96:99], v[196:199], v[232:235], v[96:99]
	v_mfma_f32_16x16x32_bf16 v[84:87], v[188:191], v[240:243], v[84:87]
	v_mfma_f32_16x16x32_bf16 v[80:83], v[196:199], v[240:243], v[80:83]
	v_mfma_f32_16x16x32_bf16 v[68:71], v[188:191], v[248:251], v[68:71]
	v_mfma_f32_16x16x32_bf16 v[64:67], v[196:199], v[248:251], v[64:67]
	s_barrier
	s_add_i32 s24, s24, s57
	v_lshl_add_u64 v[160:161], s[0:1], 0, v[132:133]
	s_mov_b32 m0, s24
	ds_read_b128 v[200:203], v165 offset:16384
	ds_read_b128 v[204:207], v165 offset:17408
	ds_read_b128 v[208:211], v165 offset:18432
	ds_read_b128 v[232:235], v165 offset:19456
	ds_read_b128 v[236:239], v165 offset:20480
	ds_read_b128 v[240:243], v165 offset:21504
	ds_read_b128 v[244:247], v165 offset:22528
	ds_read_b128 v[248:251], v165 offset:23552
	global_load_lds_dwordx4 v[160:161], off
	s_add_i32 m0, s24, 0x2000
	s_add_u32 s24, s0, 0x80000
	v_lshl_add_u64 v[166:167], s[0:1], 0, v[128:129]
	s_addc_u32 s25, s1, 0
	s_add_i32 s55, s55, s57
	global_load_lds_dwordx4 v[166:167], off
	v_lshl_add_u64 v[170:171], s[24:25], 0, v[132:133]
	s_mov_b32 m0, s55
	v_lshl_add_u64 v[212:213], s[42:43], 0, v[130:131]
	global_load_lds_dwordx4 v[170:171], off
	s_add_i32 m0, s55, 0x2000
	v_lshl_add_u64 v[170:171], s[24:25], 0, v[128:129]
	global_load_lds_dwordx4 v[170:171], off
	s_mov_b32 m0, s58
	v_lshl_add_u64 v[170:171], s[42:43], 0, v[134:135]
	global_load_lds_dwordx4 v[170:171], off
	s_mov_b32 m0, s59
	s_nop 0
	global_load_lds_dwordx4 v[212:213], off
	s_waitcnt vmcnt(8) lgkmcnt(0)
	s_barrier
	v_mfma_f32_16x16x32_bf16 v[60:63], v[144:147], v[200:203], 0
	v_mfma_f32_16x16x32_bf16 v[56:59], v[152:155], v[200:203], 0
	v_mfma_f32_16x16x32_bf16 v[44:47], v[144:147], v[208:211], 0
	v_mfma_f32_16x16x32_bf16 v[40:43], v[152:155], v[208:211], 0
	v_mfma_f32_16x16x32_bf16 v[28:31], v[144:147], v[236:239], 0
	v_mfma_f32_16x16x32_bf16 v[24:27], v[152:155], v[236:239], 0
	v_mfma_f32_16x16x32_bf16 v[12:15], v[144:147], v[244:247], 0
	v_mfma_f32_16x16x32_bf16 v[8:11], v[152:155], v[244:247], 0
	v_mfma_f32_16x16x32_bf16 v[60:63], v[148:151], v[204:207], v[60:63]
	v_mfma_f32_16x16x32_bf16 v[56:59], v[156:159], v[204:207], v[56:59]
	v_mfma_f32_16x16x32_bf16 v[44:47], v[148:151], v[232:235], v[44:47]
	v_mfma_f32_16x16x32_bf16 v[40:43], v[156:159], v[232:235], v[40:43]
	v_mfma_f32_16x16x32_bf16 v[28:31], v[148:151], v[240:243], v[28:31]
	v_mfma_f32_16x16x32_bf16 v[24:27], v[156:159], v[240:243], v[24:27]
	v_mfma_f32_16x16x32_bf16 v[12:15], v[148:151], v[248:251], v[12:15]
	v_mfma_f32_16x16x32_bf16 v[8:11], v[156:159], v[248:251], v[8:11]
	v_mfma_f32_16x16x32_bf16 v[52:55], v[184:187], v[200:203], 0
	v_mfma_f32_16x16x32_bf16 v[48:51], v[192:195], v[200:203], 0
	v_mfma_f32_16x16x32_bf16 v[36:39], v[184:187], v[208:211], 0
	v_mfma_f32_16x16x32_bf16 v[32:35], v[192:195], v[208:211], 0
	v_mfma_f32_16x16x32_bf16 v[20:23], v[184:187], v[236:239], 0
	v_mfma_f32_16x16x32_bf16 v[16:19], v[192:195], v[236:239], 0
	v_mfma_f32_16x16x32_bf16 v[4:7], v[184:187], v[244:247], 0
	v_mfma_f32_16x16x32_bf16 v[0:3], v[192:195], v[244:247], 0
	v_mfma_f32_16x16x32_bf16 v[52:55], v[188:191], v[204:207], v[52:55]
	v_mfma_f32_16x16x32_bf16 v[48:51], v[196:199], v[204:207], v[48:51]
	v_mfma_f32_16x16x32_bf16 v[36:39], v[188:191], v[232:235], v[36:39]
	v_mfma_f32_16x16x32_bf16 v[32:35], v[196:199], v[232:235], v[32:35]
	v_mfma_f32_16x16x32_bf16 v[20:23], v[188:191], v[240:243], v[20:23]
	v_mfma_f32_16x16x32_bf16 v[16:19], v[196:199], v[240:243], v[16:19]
	v_mfma_f32_16x16x32_bf16 v[4:7], v[188:191], v[248:251], v[4:7]
	v_mfma_f32_16x16x32_bf16 v[0:3], v[196:199], v[248:251], v[0:3]
	s_barrier
; #define PG8_STAGE(bufoff, gbase, voff) do { _Pragma("unroll") for (int _i = 0; _i < 2; ++_i) \
;         __builtin_amdgcn_global_load_lds((const unsigned*)((const char*)(gbase) + (voff)[_i]), (LAS unsigned*)(lds + (bufoff) + ldsw + _i * 8192), 16, 0, 0); } while (0)
; #define PG8_LDA(dst, b, h) do { _Pragma("unroll") for (int m = 0; m < 4; ++m) _Pragma("unroll") for (int k = 0; k < 2; ++k) dst[m][k] = *(const LAS bf16x8*)(lds + PG8_SA(b, h) + aoff + m * 2048 + k * 1024); } while (0)
; #define PG8_LDB(dst, b, h) do { _Pragma("unroll") for (int n = 0; n < 2; ++n) _Pragma("unroll") for (int k = 0; k < 2; ++k) dst[n][k] = *(const LAS bf16x8*)(lds + PG8_SB(b, h) + boff + n * 2048 + k * 1024); } while (0)
; #define PG8_MMA(ai, bj, At, Bt) do { __builtin_amdgcn_s_setprio(1); _Pragma("unroll") for (int m = 0; m < 4; ++m) _Pragma("unroll") for (int n = 0; n < 2; ++n) _Pragma("unroll") for (int k = 0; k < 2; ++k) \
;         acc[ai][bj][m][n] = __builtin_amdgcn_mfma_f32_16x16x32_bf16(Bt[n][k], At[m][k], acc[ai][bj][m][n], 0, 0, 0); __builtin_amdgcn_s_setprio(0); } while (0)
; #define PG8_WAIT_V(n) asm volatile("s_waitcnt vmcnt(" #n ")" ::: "memory")
; #define PG8_WAIT_L(n) asm volatile("s_waitcnt lgkmcnt(" #n ")" ::: "memory")
; #define PG8_BAR __builtin_amdgcn_s_barrier()
; #define PG8_SCHED __builtin_amdgcn_sched_barrier(0)
; template <class Epi>
; __device__ __forceinline__ void gemm_phase(LAS unsigned char* lds, const Gemm g, const StaticOrder& S, const Epi& E, const int tid) {
;     ...
;             PG8_LDB(B0, 1, 0); PG8_LDB(B1, 1, 1); PG8_SCHED; PG8_LDA(At, 1, 0); PG8_STAGE(PG8_SA(0, 1), a2 + hsA, voffA);
;             PG8_WAIT_V(8); PG8_WAIT_L(0); PG8_BAR; PG8_MMA(0, 0, At, B0); PG8_MMA(0, 1, At, B1); PG8_BAR; PG8_SCHED;
;             PG8_LDA(At, 1, 1); PG8_STAGE(PG8_SB(1, 0), b3, voffB); PG8_STAGE(PG8_SB(1, 1), b3 + hsB, voffB); PG8_STAGE(PG8_SA(1, 0), a3, voffA);
;             PG8_WAIT_V(8); PG8_WAIT_L(0); PG8_BAR; PG8_MMA(1, 0, At, B0); PG8_MMA(1, 1, At, B1); PG8_BAR; PG8_SCHED;
	s_add_i32 s55, 0, 0x18000
	v_add_u32_e32 v143, s55, v163
	s_add_i32 s67, 0, 0x1c000
	ds_read_b128 v[144:147], v143
	ds_read_b128 v[148:151], v143 offset:1024
	ds_read_b128 v[152:155], v143 offset:2048
	ds_read_b128 v[156:159], v143 offset:3072
	v_add_u32_e32 v143, s67, v163
	ds_read_b128 v[184:187], v143
	ds_read_b128 v[188:191], v143 offset:1024
	ds_read_b128 v[192:195], v143 offset:2048
	ds_read_b128 v[196:199], v143 offset:3072
	s_add_u32 s24, s42, 0x80000
	s_addc_u32 s25, s43, 0
	s_mov_b32 m0, s27
	v_lshl_add_u64 v[172:173], s[24:25], 0, v[134:135]
	ds_read_b128 v[200:203], v165 offset:32768
	ds_read_b128 v[204:207], v165 offset:33792
	ds_read_b128 v[208:211], v165 offset:34816
	ds_read_b128 v[232:235], v165 offset:35840
	ds_read_b128 v[236:239], v165 offset:36864
	ds_read_b128 v[240:243], v165 offset:37888
	ds_read_b128 v[244:247], v165 offset:38912
	ds_read_b128 v[248:251], v165 offset:39936
	global_load_lds_dwordx4 v[172:173], off
	s_mov_b32 m0, s96
	v_lshl_add_u64 v[172:173], s[24:25], 0, v[130:131]
	global_load_lds_dwordx4 v[172:173], off
	s_waitcnt vmcnt(8) lgkmcnt(0)
	s_barrier
	v_mfma_f32_16x16x32_bf16 v[124:127], v[144:147], v[200:203], v[124:127]
	v_mfma_f32_16x16x32_bf16 v[120:123], v[152:155], v[200:203], v[120:123]
	v_mfma_f32_16x16x32_bf16 v[108:111], v[144:147], v[208:211], v[108:111]
	v_mfma_f32_16x16x32_bf16 v[104:107], v[152:155], v[208:211], v[104:107]
	v_mfma_f32_16x16x32_bf16 v[92:95], v[144:147], v[236:239], v[92:95]
	v_mfma_f32_16x16x32_bf16 v[88:91], v[152:155], v[236:239], v[88:91]
	v_mfma_f32_16x16x32_bf16 v[76:79], v[144:147], v[244:247], v[76:79]
	v_mfma_f32_16x16x32_bf16 v[72:75], v[152:155], v[244:247], v[72:75]
	v_mfma_f32_16x16x32_bf16 v[124:127], v[148:151], v[204:207], v[124:127]
	v_mfma_f32_16x16x32_bf16 v[120:123], v[156:159], v[204:207], v[120:123]
	v_mfma_f32_16x16x32_bf16 v[108:111], v[148:151], v[232:235], v[108:111]
	v_mfma_f32_16x16x32_bf16 v[104:107], v[156:159], v[232:235], v[104:107]
	v_mfma_f32_16x16x32_bf16 v[92:95], v[148:151], v[240:243], v[92:95]
	v_mfma_f32_16x16x32_bf16 v[88:91], v[156:159], v[240:243], v[88:91]
	v_mfma_f32_16x16x32_bf16 v[76:79], v[148:151], v[248:251], v[76:79]
	v_mfma_f32_16x16x32_bf16 v[72:75], v[156:159], v[248:251], v[72:75]
	v_mfma_f32_16x16x32_bf16 v[116:119], v[184:187], v[200:203], v[116:119]
	v_mfma_f32_16x16x32_bf16 v[112:115], v[192:195], v[200:203], v[112:115]
	v_mfma_f32_16x16x32_bf16 v[100:103], v[184:187], v[208:211], v[100:103]
	v_mfma_f32_16x16x32_bf16 v[96:99], v[192:195], v[208:211], v[96:99]
	v_mfma_f32_16x16x32_bf16 v[84:87], v[184:187], v[236:239], v[84:87]
	v_mfma_f32_16x16x32_bf16 v[80:83], v[192:195], v[236:239], v[80:83]
	v_mfma_f32_16x16x32_bf16 v[68:71], v[184:187], v[244:247], v[68:71]
	v_mfma_f32_16x16x32_bf16 v[64:67], v[192:195], v[244:247], v[64:67]
	v_mfma_f32_16x16x32_bf16 v[116:119], v[188:191], v[204:207], v[116:119]
	v_mfma_f32_16x16x32_bf16 v[112:115], v[196:199], v[204:207], v[112:115]
	v_mfma_f32_16x16x32_bf16 v[100:103], v[188:191], v[232:235], v[100:103]
	v_mfma_f32_16x16x32_bf16 v[96:99], v[196:199], v[232:235], v[96:99]
	v_mfma_f32_16x16x32_bf16 v[84:87], v[188:191], v[240:243], v[84:87]
	v_mfma_f32_16x16x32_bf16 v[80:83], v[196:199], v[240:243], v[80:83]
	v_mfma_f32_16x16x32_bf16 v[68:71], v[188:191], v[248:251], v[68:71]
	v_mfma_f32_16x16x32_bf16 v[64:67], v[196:199], v[248:251], v[64:67]
	s_barrier
	s_add_i32 s24, s55, s57
	v_lshl_add_u64 v[160:161], v[160:161], 0, s[28:29]
	s_mov_b32 m0, s24
	ds_read_b128 v[200:203], v165 offset:49152
	ds_read_b128 v[204:207], v165 offset:50176
	ds_read_b128 v[208:211], v165 offset:51200
	ds_read_b128 v[232:235], v165 offset:52224
	ds_read_b128 v[236:239], v165 offset:53248
	ds_read_b128 v[240:243], v165 offset:54272
	ds_read_b128 v[244:247], v165 offset:55296
	ds_read_b128 v[248:251], v165 offset:56320
	global_load_lds_dwordx4 v[160:161], off
	s_add_i32 m0, s24, 0x2000
	s_add_u32 s0, s0, 0x80080
	v_lshl_add_u64 v[160:161], v[166:167], 0, s[28:29]
	s_addc_u32 s1, s1, 0
	s_add_i32 s24, s67, s57
	global_load_lds_dwordx4 v[160:161], off
	s_mov_b32 m0, s24
	v_lshl_add_u64 v[160:161], s[0:1], 0, v[132:133]
	global_load_lds_dwordx4 v[160:161], off
	s_add_i32 m0, s24, 0x2000
	v_lshl_add_u64 v[160:161], s[0:1], 0, v[128:129]
	global_load_lds_dwordx4 v[160:161], off
	s_mov_b32 m0, s6
	v_lshl_add_u64 v[160:161], v[170:171], 0, s[28:29]
	global_load_lds_dwordx4 v[160:161], off
	s_mov_b32 m0, s7
	v_lshl_add_u64 v[160:161], v[212:213], 0, s[28:29]
	global_load_lds_dwordx4 v[160:161], off
	s_waitcnt vmcnt(8) lgkmcnt(0)
	s_barrier
	v_mfma_f32_16x16x32_bf16 v[60:63], v[144:147], v[200:203], v[60:63]
	v_mfma_f32_16x16x32_bf16 v[56:59], v[152:155], v[200:203], v[56:59]
	v_mfma_f32_16x16x32_bf16 v[44:47], v[144:147], v[208:211], v[44:47]
	v_mfma_f32_16x16x32_bf16 v[40:43], v[152:155], v[208:211], v[40:43]
	v_mfma_f32_16x16x32_bf16 v[28:31], v[144:147], v[236:239], v[28:31]
	v_mfma_f32_16x16x32_bf16 v[24:27], v[152:155], v[236:239], v[24:27]
	v_mfma_f32_16x16x32_bf16 v[12:15], v[144:147], v[244:247], v[12:15]
	v_mfma_f32_16x16x32_bf16 v[8:11], v[152:155], v[244:247], v[8:11]
	v_mfma_f32_16x16x32_bf16 v[60:63], v[148:151], v[204:207], v[60:63]
	v_mfma_f32_16x16x32_bf16 v[56:59], v[156:159], v[204:207], v[56:59]
	v_mfma_f32_16x16x32_bf16 v[44:47], v[148:151], v[232:235], v[44:47]
	v_mfma_f32_16x16x32_bf16 v[40:43], v[156:159], v[232:235], v[40:43]
	v_mfma_f32_16x16x32_bf16 v[28:31], v[148:151], v[240:243], v[28:31]
	v_mfma_f32_16x16x32_bf16 v[24:27], v[156:159], v[240:243], v[24:27]
	v_mfma_f32_16x16x32_bf16 v[12:15], v[148:151], v[248:251], v[12:15]
	v_mfma_f32_16x16x32_bf16 v[8:11], v[156:159], v[248:251], v[8:11]
	v_mfma_f32_16x16x32_bf16 v[52:55], v[184:187], v[200:203], v[52:55]
	v_mfma_f32_16x16x32_bf16 v[48:51], v[192:195], v[200:203], v[48:51]
	v_mfma_f32_16x16x32_bf16 v[36:39], v[184:187], v[208:211], v[36:39]
	v_mfma_f32_16x16x32_bf16 v[32:35], v[192:195], v[208:211], v[32:35]
	v_mfma_f32_16x16x32_bf16 v[20:23], v[184:187], v[236:239], v[20:23]
	v_mfma_f32_16x16x32_bf16 v[16:19], v[192:195], v[236:239], v[16:19]
	v_mfma_f32_16x16x32_bf16 v[4:7], v[184:187], v[244:247], v[4:7]
	v_mfma_f32_16x16x32_bf16 v[0:3], v[192:195], v[244:247], v[0:3]
	v_mfma_f32_16x16x32_bf16 v[52:55], v[188:191], v[204:207], v[52:55]
	v_mfma_f32_16x16x32_bf16 v[48:51], v[196:199], v[204:207], v[48:51]
	v_mfma_f32_16x16x32_bf16 v[36:39], v[188:191], v[232:235], v[36:39]
	v_mfma_f32_16x16x32_bf16 v[32:35], v[196:199], v[232:235], v[32:35]
	v_mfma_f32_16x16x32_bf16 v[20:23], v[188:191], v[240:243], v[20:23]
	v_mfma_f32_16x16x32_bf16 v[16:19], v[196:199], v[240:243], v[16:19]
	v_mfma_f32_16x16x32_bf16 v[4:7], v[188:191], v[248:251], v[4:7]
	v_mfma_f32_16x16x32_bf16 v[0:3], v[196:199], v[248:251], v[0:3]
	s_barrier
	s_add_i32 vcc_hi, vcc_hi, 2
	s_add_u32 s36, s36, 0x100
	s_addc_u32 s37, s37, 0
	s_add_u32 s69, s69, 0x100
	s_addc_u32 vcc_lo, vcc_lo, 0
	s_cmp_gt_u32 vcc_hi, 29
; #define PG8_STAGE(bufoff, gbase, voff) do { _Pragma("unroll") for (int _i = 0; _i < 2; ++_i) \
;         __builtin_amdgcn_global_load_lds((const unsigned*)((const char*)(gbase) + (voff)[_i]), (LAS unsigned*)(lds + (bufoff) + ldsw + _i * 8192), 16, 0, 0); } while (0)
; #define PG8_LDA(dst, b, h) do { _Pragma("unroll") for (int m = 0; m < 4; ++m) _Pragma("unroll") for (int k = 0; k < 2; ++k) dst[m][k] = *(const LAS bf16x8*)(lds + PG8_SA(b, h) + aoff + m * 2048 + k * 1024); } while (0)
; #define PG8_LDB(dst, b, h) do { _Pragma("unroll") for (int n = 0; n < 2; ++n) _Pragma("unroll") for (int k = 0; k < 2; ++k) dst[n][k] = *(const LAS bf16x8*)(lds + PG8_SB(b, h) + boff + n * 2048 + k * 1024); } while (0)
; #define PG8_MMA(ai, bj, At, Bt) do { __builtin_amdgcn_s_setprio(1); _Pragma("unroll") for (int m = 0; m < 4; ++m) _Pragma("unroll") for (int n = 0; n < 2; ++n) _Pragma("unroll") for (int k = 0; k < 2; ++k) \
;         acc[ai][bj][m][n] = __builtin_amdgcn_mfma_f32_16x16x32_bf16(Bt[n][k], At[m][k], acc[ai][bj][m][n], 0, 0, 0); __builtin_amdgcn_s_setprio(0); } while (0)
; #define PG8_WAIT_V(n) asm volatile("s_waitcnt vmcnt(" #n ")" ::: "memory")
; #define PG8_WAIT_L(n) asm volatile("s_waitcnt lgkmcnt(" #n ")" ::: "memory")
; #define PG8_BAR __builtin_amdgcn_s_barrier()
; #define PG8_SCHED __builtin_amdgcn_sched_barrier(0)
; template <class Epi>
; __device__ __forceinline__ void gemm_phase(LAS unsigned char* lds, const Gemm g, const StaticOrder& S, const Epi& E, const int tid) {
;     ...
;             const bool last = (t == nt - 2);
;             const char* a1 = cA + (size_t)(t + 1) * kstep;
;             const char* a2 = last ? nA : cA + (size_t)(t + 2) * kstep; const char* b2 = last ? nB : cB + (size_t)(t + 2) * kstep;
;             const char* a3 = a2 + kstep; const char* b3 = b2 + kstep;
;             PG8_LDB(B0, 0, 0); PG8_LDB(B1, 0, 1); PG8_SCHED; PG8_LDA(At, 0, 0); PG8_STAGE(PG8_SA(1, 1), a1 + hsA, voffA);
;             PG8_WAIT_V(8); PG8_WAIT_L(0); PG8_BAR; PG8_MMA(0, 0, At, B0); PG8_MMA(0, 1, At, B1); PG8_BAR; PG8_SCHED;
;             PG8_LDA(At, 0, 1); PG8_STAGE(PG8_SB(0, 0), b2, voffB); PG8_STAGE(PG8_SB(0, 1), b2 + hsB, voffB); PG8_STAGE(PG8_SA(0, 0), a2, voffA);
.LBB0_354:
	s_add_u32 s0, s36, 0xfff80080
	s_addc_u32 s1, s37, -1
	s_add_i32 s24, 0, 0x10000
	s_cmp_eq_u32 vcc_hi, 28
	s_cselect_b32 s43, s10, s1
	s_cselect_b32 s42, s11, s0
	v_add_u32_e32 v143, s24, v163
	s_cselect_b32 s1, s47, vcc_lo
	s_cselect_b32 s0, s49, s69
	s_add_i32 s55, 0, 0x14000
	ds_read_b128 v[144:147], v143
	ds_read_b128 v[148:151], v143 offset:1024
	ds_read_b128 v[152:155], v143 offset:2048
	ds_read_b128 v[156:159], v143 offset:3072
	v_add_u32_e32 v143, s55, v163
	ds_read_b128 v[184:187], v143
	ds_read_b128 v[188:191], v143 offset:1024
	ds_read_b128 v[192:195], v143 offset:2048
	ds_read_b128 v[196:199], v143 offset:3072
	v_lshl_add_u64 v[160:161], s[36:37], 0, v[138:139]
	s_add_i32 m0, s58, 0xc000
	ds_read_b128 v[200:203], v165
	ds_read_b128 v[204:207], v165 offset:1024
	ds_read_b128 v[208:211], v165 offset:2048
	ds_read_b128 v[232:235], v165 offset:3072
	ds_read_b128 v[236:239], v165 offset:4096
	ds_read_b128 v[240:243], v165 offset:5120
	ds_read_b128 v[244:247], v165 offset:6144
	ds_read_b128 v[248:251], v165 offset:7168
	global_load_lds_dwordx4 v[160:161], off
	s_add_i32 m0, s58, 0xe000
	v_lshl_add_u64 v[160:161], s[36:37], 0, v[140:141]
	global_load_lds_dwordx4 v[160:161], off
	s_waitcnt vmcnt(8) lgkmcnt(0)
	s_barrier
	v_mfma_f32_16x16x32_bf16 v[124:127], v[144:147], v[200:203], v[124:127]
	v_mfma_f32_16x16x32_bf16 v[120:123], v[152:155], v[200:203], v[120:123]
	v_mfma_f32_16x16x32_bf16 v[108:111], v[144:147], v[208:211], v[108:111]
	v_mfma_f32_16x16x32_bf16 v[104:107], v[152:155], v[208:211], v[104:107]
	v_mfma_f32_16x16x32_bf16 v[92:95], v[144:147], v[236:239], v[92:95]
	v_mfma_f32_16x16x32_bf16 v[88:91], v[152:155], v[236:239], v[88:91]
	v_mfma_f32_16x16x32_bf16 v[76:79], v[144:147], v[244:247], v[76:79]
	v_mfma_f32_16x16x32_bf16 v[72:75], v[152:155], v[244:247], v[72:75]
	v_mfma_f32_16x16x32_bf16 v[124:127], v[148:151], v[204:207], v[124:127]
	v_mfma_f32_16x16x32_bf16 v[120:123], v[156:159], v[204:207], v[120:123]
	v_mfma_f32_16x16x32_bf16 v[108:111], v[148:151], v[232:235], v[108:111]
	v_mfma_f32_16x16x32_bf16 v[104:107], v[156:159], v[232:235], v[104:107]
	v_mfma_f32_16x16x32_bf16 v[92:95], v[148:151], v[240:243], v[92:95]
	v_mfma_f32_16x16x32_bf16 v[88:91], v[156:159], v[240:243], v[88:91]
	v_mfma_f32_16x16x32_bf16 v[76:79], v[148:151], v[248:251], v[76:79]
	v_mfma_f32_16x16x32_bf16 v[72:75], v[156:159], v[248:251], v[72:75]
	v_mfma_f32_16x16x32_bf16 v[116:119], v[184:187], v[200:203], v[116:119]
	v_mfma_f32_16x16x32_bf16 v[112:115], v[192:195], v[200:203], v[112:115]
	v_mfma_f32_16x16x32_bf16 v[100:103], v[184:187], v[208:211], v[100:103]
	v_mfma_f32_16x16x32_bf16 v[96:99], v[192:195], v[208:211], v[96:99]
	v_mfma_f32_16x16x32_bf16 v[84:87], v[184:187], v[236:239], v[84:87]
	v_mfma_f32_16x16x32_bf16 v[80:83], v[192:195], v[236:239], v[80:83]
	v_mfma_f32_16x16x32_bf16 v[68:71], v[184:187], v[244:247], v[68:71]
	v_mfma_f32_16x16x32_bf16 v[64:67], v[192:195], v[244:247], v[64:67]
	v_mfma_f32_16x16x32_bf16 v[116:119], v[188:191], v[204:207], v[116:119]
	v_mfma_f32_16x16x32_bf16 v[112:115], v[196:199], v[204:207], v[112:115]
	v_mfma_f32_16x16x32_bf16 v[100:103], v[188:191], v[232:235], v[100:103]
	v_mfma_f32_16x16x32_bf16 v[96:99], v[196:199], v[232:235], v[96:99]
	v_mfma_f32_16x16x32_bf16 v[84:87], v[188:191], v[240:243], v[84:87]
	v_mfma_f32_16x16x32_bf16 v[80:83], v[196:199], v[240:243], v[80:83]
	v_mfma_f32_16x16x32_bf16 v[68:71], v[188:191], v[248:251], v[68:71]
	v_mfma_f32_16x16x32_bf16 v[64:67], v[196:199], v[248:251], v[64:67]
	s_barrier
	s_add_i32 s24, s24, s57
	v_lshl_add_u64 v[160:161], s[0:1], 0, v[132:133]
	s_mov_b32 m0, s24
	ds_read_b128 v[200:203], v165 offset:16384
	ds_read_b128 v[204:207], v165 offset:17408
	ds_read_b128 v[208:211], v165 offset:18432
	ds_read_b128 v[232:235], v165 offset:19456
	ds_read_b128 v[236:239], v165 offset:20480
	ds_read_b128 v[240:243], v165 offset:21504
	ds_read_b128 v[244:247], v165 offset:22528
	ds_read_b128 v[248:251], v165 offset:23552
	global_load_lds_dwordx4 v[160:161], off
	s_add_i32 m0, s24, 0x2000
	s_add_u32 s24, s0, 0x80000
	v_lshl_add_u64 v[166:167], s[0:1], 0, v[128:129]
	s_addc_u32 s25, s1, 0
	s_add_i32 s55, s55, s57
	global_load_lds_dwordx4 v[166:167], off
	v_lshl_add_u64 v[170:171], s[24:25], 0, v[132:133]
	s_mov_b32 m0, s55
	v_lshl_add_u64 v[212:213], s[42:43], 0, v[130:131]
	global_load_lds_dwordx4 v[170:171], off
	s_add_i32 m0, s55, 0x2000
	v_lshl_add_u64 v[170:171], s[24:25], 0, v[128:129]
	global_load_lds_dwordx4 v[170:171], off
	s_mov_b32 m0, s58
	v_lshl_add_u64 v[170:171], s[42:43], 0, v[134:135]
	global_load_lds_dwordx4 v[170:171], off
	s_mov_b32 m0, s59
	s_nop 0
	global_load_lds_dwordx4 v[212:213], off
	s_waitcnt vmcnt(8) lgkmcnt(0)
	s_barrier
; #define PG8_STAGE(bufoff, gbase, voff) do { _Pragma("unroll") for (int _i = 0; _i < 2; ++_i) \
;         __builtin_amdgcn_global_load_lds((const unsigned*)((const char*)(gbase) + (voff)[_i]), (LAS unsigned*)(lds + (bufoff) + ldsw + _i * 8192), 16, 0, 0); } while (0)
; #define PG8_LDA(dst, b, h) do { _Pragma("unroll") for (int m = 0; m < 4; ++m) _Pragma("unroll") for (int k = 0; k < 2; ++k) dst[m][k] = *(const LAS bf16x8*)(lds + PG8_SA(b, h) + aoff + m * 2048 + k * 1024); } while (0)
; #define PG8_LDB(dst, b, h) do { _Pragma("unroll") for (int n = 0; n < 2; ++n) _Pragma("unroll") for (int k = 0; k < 2; ++k) dst[n][k] = *(const LAS bf16x8*)(lds + PG8_SB(b, h) + boff + n * 2048 + k * 1024); } while (0)
; #define PG8_MMA(ai, bj, At, Bt) do { __builtin_amdgcn_s_setprio(1); _Pragma("unroll") for (int m = 0; m < 4; ++m) _Pragma("unroll") for (int n = 0; n < 2; ++n) _Pragma("unroll") for (int k = 0; k < 2; ++k) \
;         acc[ai][bj][m][n] = __builtin_amdgcn_mfma_f32_16x16x32_bf16(Bt[n][k], At[m][k], acc[ai][bj][m][n], 0, 0, 0); __builtin_amdgcn_s_setprio(0); } while (0)
; #define PG8_WAIT_V(n) asm volatile("s_waitcnt vmcnt(" #n ")" ::: "memory")
; #define PG8_WAIT_L(n) asm volatile("s_waitcnt lgkmcnt(" #n ")" ::: "memory")
; #define PG8_BAR __builtin_amdgcn_s_barrier()
; #define PG8_SCHED __builtin_amdgcn_sched_barrier(0)
; template <class Epi>
; __device__ __forceinline__ void gemm_phase(LAS unsigned char* lds, const Gemm g, const StaticOrder& S, const Epi& E, const int tid) {
;     ...
;             PG8_WAIT_V(8); PG8_WAIT_L(0); PG8_BAR; PG8_MMA(1, 0, At, B0); PG8_MMA(1, 1, At, B1); PG8_BAR; PG8_SCHED;
;             PG8_LDB(B0, 1, 0); PG8_LDB(B1, 1, 1); PG8_SCHED; PG8_LDA(At, 1, 0); PG8_STAGE(PG8_SA(0, 1), a2 + hsA, voffA);
;             PG8_WAIT_V(8); PG8_WAIT_L(0); PG8_BAR; PG8_MMA(0, 0, At, B0); PG8_MMA(0, 1, At, B1); PG8_BAR; PG8_SCHED;
	v_mfma_f32_16x16x32_bf16 v[60:63], v[144:147], v[200:203], v[60:63]
	v_mfma_f32_16x16x32_bf16 v[56:59], v[152:155], v[200:203], v[56:59]
	v_mfma_f32_16x16x32_bf16 v[44:47], v[144:147], v[208:211], v[44:47]
	v_mfma_f32_16x16x32_bf16 v[40:43], v[152:155], v[208:211], v[40:43]
	v_mfma_f32_16x16x32_bf16 v[28:31], v[144:147], v[236:239], v[28:31]
	v_mfma_f32_16x16x32_bf16 v[24:27], v[152:155], v[236:239], v[24:27]
	v_mfma_f32_16x16x32_bf16 v[12:15], v[144:147], v[244:247], v[12:15]
	v_mfma_f32_16x16x32_bf16 v[8:11], v[152:155], v[244:247], v[8:11]
	v_mfma_f32_16x16x32_bf16 v[60:63], v[148:151], v[204:207], v[60:63]
	v_mfma_f32_16x16x32_bf16 v[56:59], v[156:159], v[204:207], v[56:59]
	v_mfma_f32_16x16x32_bf16 v[44:47], v[148:151], v[232:235], v[44:47]
	v_mfma_f32_16x16x32_bf16 v[40:43], v[156:159], v[232:235], v[40:43]
	v_mfma_f32_16x16x32_bf16 v[28:31], v[148:151], v[240:243], v[28:31]
	v_mfma_f32_16x16x32_bf16 v[24:27], v[156:159], v[240:243], v[24:27]
	v_mfma_f32_16x16x32_bf16 v[12:15], v[148:151], v[248:251], v[12:15]
	v_mfma_f32_16x16x32_bf16 v[8:11], v[156:159], v[248:251], v[8:11]
	v_mfma_f32_16x16x32_bf16 v[52:55], v[184:187], v[200:203], v[52:55]
	v_mfma_f32_16x16x32_bf16 v[48:51], v[192:195], v[200:203], v[48:51]
	v_mfma_f32_16x16x32_bf16 v[36:39], v[184:187], v[208:211], v[36:39]
	v_mfma_f32_16x16x32_bf16 v[32:35], v[192:195], v[208:211], v[32:35]
	v_mfma_f32_16x16x32_bf16 v[20:23], v[184:187], v[236:239], v[20:23]
	v_mfma_f32_16x16x32_bf16 v[16:19], v[192:195], v[236:239], v[16:19]
	v_mfma_f32_16x16x32_bf16 v[4:7], v[184:187], v[244:247], v[4:7]
	v_mfma_f32_16x16x32_bf16 v[0:3], v[192:195], v[244:247], v[0:3]
	v_mfma_f32_16x16x32_bf16 v[52:55], v[188:191], v[204:207], v[52:55]
	v_mfma_f32_16x16x32_bf16 v[48:51], v[196:199], v[204:207], v[48:51]
	v_mfma_f32_16x16x32_bf16 v[36:39], v[188:191], v[232:235], v[36:39]
	v_mfma_f32_16x16x32_bf16 v[32:35], v[196:199], v[232:235], v[32:35]
	v_mfma_f32_16x16x32_bf16 v[20:23], v[188:191], v[240:243], v[20:23]
	v_mfma_f32_16x16x32_bf16 v[16:19], v[196:199], v[240:243], v[16:19]
	v_mfma_f32_16x16x32_bf16 v[4:7], v[188:191], v[248:251], v[4:7]
	v_mfma_f32_16x16x32_bf16 v[0:3], v[196:199], v[248:251], v[0:3]
	s_barrier
	s_add_i32 s55, 0, 0x18000
	v_add_u32_e32 v143, s55, v163
	s_add_i32 s67, 0, 0x1c000
	ds_read_b128 v[144:147], v143
	ds_read_b128 v[148:151], v143 offset:1024
	ds_read_b128 v[152:155], v143 offset:2048
	ds_read_b128 v[156:159], v143 offset:3072
	v_add_u32_e32 v143, s67, v163
	ds_read_b128 v[184:187], v143
	ds_read_b128 v[188:191], v143 offset:1024
	ds_read_b128 v[192:195], v143 offset:2048
	ds_read_b128 v[196:199], v143 offset:3072
	s_add_u32 s24, s42, 0x80000
	s_addc_u32 s25, s43, 0
	s_mov_b32 m0, s27
	v_lshl_add_u64 v[172:173], s[24:25], 0, v[134:135]
	ds_read_b128 v[200:203], v165 offset:32768
	ds_read_b128 v[204:207], v165 offset:33792
	ds_read_b128 v[208:211], v165 offset:34816
	ds_read_b128 v[232:235], v165 offset:35840
	ds_read_b128 v[236:239], v165 offset:36864
	ds_read_b128 v[240:243], v165 offset:37888
	ds_read_b128 v[244:247], v165 offset:38912
	ds_read_b128 v[248:251], v165 offset:39936
	global_load_lds_dwordx4 v[172:173], off
	s_mov_b32 m0, s96
	v_lshl_add_u64 v[172:173], s[24:25], 0, v[130:131]
	global_load_lds_dwordx4 v[172:173], off
	s_waitcnt vmcnt(8) lgkmcnt(0)
	s_barrier
	v_mfma_f32_16x16x32_bf16 v[124:127], v[144:147], v[200:203], v[124:127]
	v_mfma_f32_16x16x32_bf16 v[120:123], v[152:155], v[200:203], v[120:123]
	v_mfma_f32_16x16x32_bf16 v[108:111], v[144:147], v[208:211], v[108:111]
	v_mfma_f32_16x16x32_bf16 v[104:107], v[152:155], v[208:211], v[104:107]
	v_mfma_f32_16x16x32_bf16 v[92:95], v[144:147], v[236:239], v[92:95]
	v_mfma_f32_16x16x32_bf16 v[88:91], v[152:155], v[236:239], v[88:91]
	v_mfma_f32_16x16x32_bf16 v[76:79], v[144:147], v[244:247], v[76:79]
	v_mfma_f32_16x16x32_bf16 v[72:75], v[152:155], v[244:247], v[72:75]
	v_mfma_f32_16x16x32_bf16 v[124:127], v[148:151], v[204:207], v[124:127]
	v_mfma_f32_16x16x32_bf16 v[120:123], v[156:159], v[204:207], v[120:123]
	v_mfma_f32_16x16x32_bf16 v[108:111], v[148:151], v[232:235], v[108:111]
	v_mfma_f32_16x16x32_bf16 v[104:107], v[156:159], v[232:235], v[104:107]
	v_mfma_f32_16x16x32_bf16 v[92:95], v[148:151], v[240:243], v[92:95]
	v_mfma_f32_16x16x32_bf16 v[88:91], v[156:159], v[240:243], v[88:91]
	v_mfma_f32_16x16x32_bf16 v[76:79], v[148:151], v[248:251], v[76:79]
	v_mfma_f32_16x16x32_bf16 v[72:75], v[156:159], v[248:251], v[72:75]
	v_mfma_f32_16x16x32_bf16 v[116:119], v[184:187], v[200:203], v[116:119]
	v_mfma_f32_16x16x32_bf16 v[112:115], v[192:195], v[200:203], v[112:115]
	v_mfma_f32_16x16x32_bf16 v[100:103], v[184:187], v[208:211], v[100:103]
	v_mfma_f32_16x16x32_bf16 v[96:99], v[192:195], v[208:211], v[96:99]
	v_mfma_f32_16x16x32_bf16 v[84:87], v[184:187], v[236:239], v[84:87]
	v_mfma_f32_16x16x32_bf16 v[80:83], v[192:195], v[236:239], v[80:83]
	v_mfma_f32_16x16x32_bf16 v[68:71], v[184:187], v[244:247], v[68:71]
	v_mfma_f32_16x16x32_bf16 v[64:67], v[192:195], v[244:247], v[64:67]
	v_mfma_f32_16x16x32_bf16 v[116:119], v[188:191], v[204:207], v[116:119]
	v_mfma_f32_16x16x32_bf16 v[112:115], v[196:199], v[204:207], v[112:115]
	v_mfma_f32_16x16x32_bf16 v[100:103], v[188:191], v[232:235], v[100:103]
	v_mfma_f32_16x16x32_bf16 v[96:99], v[196:199], v[232:235], v[96:99]
	v_mfma_f32_16x16x32_bf16 v[84:87], v[188:191], v[240:243], v[84:87]
	v_mfma_f32_16x16x32_bf16 v[80:83], v[196:199], v[240:243], v[80:83]
	v_mfma_f32_16x16x32_bf16 v[68:71], v[188:191], v[248:251], v[68:71]
	v_mfma_f32_16x16x32_bf16 v[64:67], v[196:199], v[248:251], v[64:67]
	s_barrier
; #define PG8_STAGE(bufoff, gbase, voff) do { _Pragma("unroll") for (int _i = 0; _i < 2; ++_i) \
;         __builtin_amdgcn_global_load_lds((const unsigned*)((const char*)(gbase) + (voff)[_i]), (LAS unsigned*)(lds + (bufoff) + ldsw + _i * 8192), 16, 0, 0); } while (0)
; #define PG8_LDA(dst, b, h) do { _Pragma("unroll") for (int m = 0; m < 4; ++m) _Pragma("unroll") for (int k = 0; k < 2; ++k) dst[m][k] = *(const LAS bf16x8*)(lds + PG8_SA(b, h) + aoff + m * 2048 + k * 1024); } while (0)
; #define PG8_MMA(ai, bj, At, Bt) do { __builtin_amdgcn_s_setprio(1); _Pragma("unroll") for (int m = 0; m < 4; ++m) _Pragma("unroll") for (int n = 0; n < 2; ++n) _Pragma("unroll") for (int k = 0; k < 2; ++k) \
;         acc[ai][bj][m][n] = __builtin_amdgcn_mfma_f32_16x16x32_bf16(Bt[n][k], At[m][k], acc[ai][bj][m][n], 0, 0, 0); __builtin_amdgcn_s_setprio(0); } while (0)
; #define PG8_WAIT_V(n) asm volatile("s_waitcnt vmcnt(" #n ")" ::: "memory")
; #define PG8_WAIT_L(n) asm volatile("s_waitcnt lgkmcnt(" #n ")" ::: "memory")
; #define PG8_BAR __builtin_amdgcn_s_barrier()
; #define PG8_SCHED __builtin_amdgcn_sched_barrier(0)
; template <class Epi>
; __device__ __forceinline__ void gemm_phase(LAS unsigned char* lds, const Gemm g, const StaticOrder& S, const Epi& E, const int tid) {
;     ...
;             PG8_LDA(At, 1, 1); PG8_STAGE(PG8_SB(1, 0), b3, voffB); PG8_STAGE(PG8_SB(1, 1), b3 + hsB, voffB); PG8_STAGE(PG8_SA(1, 0), a3, voffA);
;             PG8_WAIT_V(8); PG8_WAIT_L(0); PG8_BAR; PG8_MMA(1, 0, At, B0); PG8_MMA(1, 1, At, B1); PG8_BAR; PG8_SCHED;
;         }
;         if (wr == 0) PG8_BAR;
	s_add_i32 s24, s55, s57
	v_lshl_add_u64 v[160:161], v[160:161], 0, s[28:29]
	s_mov_b32 m0, s24
	ds_read_b128 v[200:203], v165 offset:49152
	ds_read_b128 v[204:207], v165 offset:50176
	ds_read_b128 v[208:211], v165 offset:51200
	ds_read_b128 v[232:235], v165 offset:52224
	ds_read_b128 v[236:239], v165 offset:53248
	ds_read_b128 v[240:243], v165 offset:54272
	ds_read_b128 v[244:247], v165 offset:55296
	ds_read_b128 v[248:251], v165 offset:56320
	global_load_lds_dwordx4 v[160:161], off
	s_add_i32 m0, s24, 0x2000
	s_add_u32 s0, s0, 0x80080
	v_lshl_add_u64 v[160:161], v[166:167], 0, s[28:29]
	s_addc_u32 s1, s1, 0
	s_add_i32 s24, s67, s57
	global_load_lds_dwordx4 v[160:161], off
	s_mov_b32 m0, s24
	v_lshl_add_u64 v[160:161], s[0:1], 0, v[132:133]
	global_load_lds_dwordx4 v[160:161], off
	s_add_i32 m0, s24, 0x2000
	v_lshl_add_u64 v[160:161], s[0:1], 0, v[128:129]
	global_load_lds_dwordx4 v[160:161], off
	s_mov_b32 m0, s6
	v_lshl_add_u64 v[160:161], v[170:171], 0, s[28:29]
	global_load_lds_dwordx4 v[160:161], off
	s_mov_b32 m0, s7
	v_lshl_add_u64 v[160:161], v[212:213], 0, s[28:29]
	global_load_lds_dwordx4 v[160:161], off
	s_waitcnt vmcnt(8) lgkmcnt(0)
	s_barrier
	v_mfma_f32_16x16x32_bf16 v[60:63], v[144:147], v[200:203], v[60:63]
	v_mfma_f32_16x16x32_bf16 v[56:59], v[152:155], v[200:203], v[56:59]
	v_mfma_f32_16x16x32_bf16 v[44:47], v[144:147], v[208:211], v[44:47]
	v_mfma_f32_16x16x32_bf16 v[40:43], v[152:155], v[208:211], v[40:43]
	v_mfma_f32_16x16x32_bf16 v[28:31], v[144:147], v[236:239], v[28:31]
	v_mfma_f32_16x16x32_bf16 v[24:27], v[152:155], v[236:239], v[24:27]
	v_mfma_f32_16x16x32_bf16 v[12:15], v[144:147], v[244:247], v[12:15]
	v_mfma_f32_16x16x32_bf16 v[8:11], v[152:155], v[244:247], v[8:11]
	v_mfma_f32_16x16x32_bf16 v[60:63], v[148:151], v[204:207], v[60:63]
	v_mfma_f32_16x16x32_bf16 v[56:59], v[156:159], v[204:207], v[56:59]
	v_mfma_f32_16x16x32_bf16 v[44:47], v[148:151], v[232:235], v[44:47]
	v_mfma_f32_16x16x32_bf16 v[40:43], v[156:159], v[232:235], v[40:43]
	v_mfma_f32_16x16x32_bf16 v[28:31], v[148:151], v[240:243], v[28:31]
	v_mfma_f32_16x16x32_bf16 v[24:27], v[156:159], v[240:243], v[24:27]
	v_mfma_f32_16x16x32_bf16 v[12:15], v[148:151], v[248:251], v[12:15]
	v_mfma_f32_16x16x32_bf16 v[8:11], v[156:159], v[248:251], v[8:11]
	v_mfma_f32_16x16x32_bf16 v[52:55], v[184:187], v[200:203], v[52:55]
	v_mfma_f32_16x16x32_bf16 v[48:51], v[192:195], v[200:203], v[48:51]
	v_mfma_f32_16x16x32_bf16 v[36:39], v[184:187], v[208:211], v[36:39]
	v_mfma_f32_16x16x32_bf16 v[32:35], v[192:195], v[208:211], v[32:35]
	v_mfma_f32_16x16x32_bf16 v[20:23], v[184:187], v[236:239], v[20:23]
	v_mfma_f32_16x16x32_bf16 v[16:19], v[192:195], v[236:239], v[16:19]
	v_mfma_f32_16x16x32_bf16 v[4:7], v[184:187], v[244:247], v[4:7]
	v_mfma_f32_16x16x32_bf16 v[0:3], v[192:195], v[244:247], v[0:3]
	v_mfma_f32_16x16x32_bf16 v[52:55], v[188:191], v[204:207], v[52:55]
	v_mfma_f32_16x16x32_bf16 v[48:51], v[196:199], v[204:207], v[48:51]
	v_mfma_f32_16x16x32_bf16 v[36:39], v[188:191], v[232:235], v[36:39]
	v_mfma_f32_16x16x32_bf16 v[32:35], v[196:199], v[232:235], v[32:35]
	v_mfma_f32_16x16x32_bf16 v[20:23], v[188:191], v[240:243], v[20:23]
	v_mfma_f32_16x16x32_bf16 v[16:19], v[196:199], v[240:243], v[16:19]
	v_mfma_f32_16x16x32_bf16 v[4:7], v[188:191], v[248:251], v[4:7]
	v_mfma_f32_16x16x32_bf16 v[0:3], v[196:199], v[248:251], v[0:3]
	s_barrier
	s_add_i32 vcc_hi, vcc_hi, 2
	s_add_u32 s36, s36, 0x100
	s_addc_u32 s37, s37, 0
	s_add_u32 s69, s69, 0x100
	s_addc_u32 vcc_lo, vcc_lo, 0
	s_cmp_gt_u32 vcc_hi, 29
	s_cbranch_scc0 .LBB0_354
	s_and_b64 vcc, exec, s[34:35]
	s_cbranch_vccz .LBB0_357
	s_barrier

; #define PG8_STAGE(bufoff, gbase, voff) do { _Pragma("unroll") for (int _i = 0; _i < 2; ++_i) \
;         __builtin_amdgcn_global_load_lds((const unsigned*)((const char*)(gbase) + (voff)[_i]), (LAS unsigned*)(lds + (bufoff) + ldsw + _i * 8192), 16, 0, 0); } while (0)
; #define PG8_LDA(dst, b, h) do { _Pragma("unroll") for (int m = 0; m < 4; ++m) _Pragma("unroll") for (int k = 0; k < 2; ++k) dst[m][k] = *(const LAS bf16x8*)(lds + PG8_SA(b, h) + aoff + m * 2048 + k * 1024); } while (0)
; #define PG8_LDB(dst, b, h) do { _Pragma("unroll") for (int n = 0; n < 2; ++n) _Pragma("unroll") for (int k = 0; k < 2; ++k) dst[n][k] = *(const LAS bf16x8*)(lds + PG8_SB(b, h) + boff + n * 2048 + k * 1024); } while (0)
; #define PG8_MMA(ai, bj, At, Bt) do { __builtin_amdgcn_s_setprio(1); _Pragma("unroll") for (int m = 0; m < 4; ++m) _Pragma("unroll") for (int n = 0; n < 2; ++n) _Pragma("unroll") for (int k = 0; k < 2; ++k) \
;         acc[ai][bj][m][n] = __builtin_amdgcn_mfma_f32_16x16x32_bf16(Bt[n][k], At[m][k], acc[ai][bj][m][n], 0, 0, 0); __builtin_amdgcn_s_setprio(0); } while (0)
; #define PG8_WAIT_V(n) asm volatile("s_waitcnt vmcnt(" #n ")" ::: "memory")
; #define PG8_WAIT_L(n) asm volatile("s_waitcnt lgkmcnt(" #n ")" ::: "memory")
; #define PG8_BAR __builtin_amdgcn_s_barrier()
; #define PG8_SCHED __builtin_amdgcn_sched_barrier(0)
; template <class Epi>
; __device__ __forceinline__ void gemm_phase(LAS unsigned char* lds, const Gemm g, const StaticOrder& S, const Epi& E, const int tid) {
;     ...
;             const bool last = (t == nt - 2);
;             const char* a1 = cA + (size_t)(t + 1) * kstep;
;             const char* a2 = last ? nA : cA + (size_t)(t + 2) * kstep; const char* b2 = last ? nB : cB + (size_t)(t + 2) * kstep;
;             const char* a3 = a2 + kstep; const char* b3 = b2 + kstep;
;             PG8_LDB(B0, 0, 0); PG8_LDB(B1, 0, 1); PG8_SCHED; PG8_LDA(At, 0, 0); PG8_STAGE(PG8_SA(1, 1), a1 + hsA, voffA);
;             PG8_WAIT_V(8); PG8_WAIT_L(0); PG8_BAR; PG8_MMA(0, 0, At, B0); PG8_MMA(0, 1, At, B1); PG8_BAR; PG8_SCHED;
;             PG8_LDA(At, 0, 1); PG8_STAGE(PG8_SB(0, 0), b2, voffB); PG8_STAGE(PG8_SB(0, 1), b2 + hsB, voffB); PG8_STAGE(PG8_SA(0, 0), a2, voffA);
.Lgprio_d:
.LBB0_823:
	s_add_u32 s42, s36, 0x100
	s_addc_u32 s43, s37, 0
	s_add_i32 s24, 0, 0x10000
	s_cmp_eq_u32 s96, 12
	s_cselect_b32 vcc_hi, s47, s43
	s_cselect_b32 vcc_lo, s46, s42
	s_cselect_b32 s49, s35, s69
	s_cselect_b32 s48, s45, s68
	s_add_i32 s55, 0, 0x14000
	v_add_u32_e32 v150, s24, v232
	v_add_u32_e32 v166, s55, v232
	ds_read_b128 v[138:141], v150
	ds_read_b128 v[142:145], v150 offset:1024
	ds_read_b128 v[146:149], v150 offset:2048
	ds_read_b128 v[150:153], v150 offset:3072
	ds_read_b128 v[154:157], v166
	ds_read_b128 v[158:161], v166 offset:1024
	ds_read_b128 v[162:165], v166 offset:2048
	ds_read_b128 v[184:187], v166 offset:3072
	v_lshl_add_u64 v[166:167], s[36:37], 0, v[134:135]
	s_add_i32 m0, s7, 0xc000
	ds_read_b128 v[188:191], v234
	ds_read_b128 v[192:195], v234 offset:1024
	ds_read_b128 v[196:199], v234 offset:2048
	ds_read_b128 v[200:203], v234 offset:3072
	ds_read_b128 v[204:207], v234 offset:4096
	ds_read_b128 v[208:211], v234 offset:5120
	ds_read_b128 v[236:239], v234 offset:6144
	ds_read_b128 v[240:243], v234 offset:7168
	global_load_lds_dwordx4 v[166:167], off
	s_add_i32 m0, s7, 0xe000
	v_lshl_add_u64 v[166:167], s[36:37], 0, v[136:137]
	global_load_lds_dwordx4 v[166:167], off
	s_waitcnt vmcnt(8) lgkmcnt(0)
	s_barrier
	v_mfma_f32_16x16x32_bf16 v[124:127], v[138:141], v[188:191], v[124:127]
	v_mfma_f32_16x16x32_bf16 v[120:123], v[146:149], v[188:191], v[120:123]
	v_mfma_f32_16x16x32_bf16 v[116:119], v[138:141], v[196:199], v[116:119]
	v_mfma_f32_16x16x32_bf16 v[112:115], v[146:149], v[196:199], v[112:115]
	v_mfma_f32_16x16x32_bf16 v[108:111], v[138:141], v[204:207], v[108:111]
	v_mfma_f32_16x16x32_bf16 v[104:107], v[146:149], v[204:207], v[104:107]
	v_mfma_f32_16x16x32_bf16 v[100:103], v[138:141], v[236:239], v[100:103]
	v_mfma_f32_16x16x32_bf16 v[96:99], v[146:149], v[236:239], v[96:99]
	v_mfma_f32_16x16x32_bf16 v[124:127], v[142:145], v[192:195], v[124:127]
	v_mfma_f32_16x16x32_bf16 v[120:123], v[150:153], v[192:195], v[120:123]
	v_mfma_f32_16x16x32_bf16 v[116:119], v[142:145], v[200:203], v[116:119]
	v_mfma_f32_16x16x32_bf16 v[112:115], v[150:153], v[200:203], v[112:115]
	v_mfma_f32_16x16x32_bf16 v[108:111], v[142:145], v[208:211], v[108:111]
	v_mfma_f32_16x16x32_bf16 v[104:107], v[150:153], v[208:211], v[104:107]
	v_mfma_f32_16x16x32_bf16 v[100:103], v[142:145], v[240:243], v[100:103]
	v_mfma_f32_16x16x32_bf16 v[96:99], v[150:153], v[240:243], v[96:99]
	v_mfma_f32_16x16x32_bf16 v[92:95], v[154:157], v[188:191], v[92:95]
	v_mfma_f32_16x16x32_bf16 v[88:91], v[162:165], v[188:191], v[88:91]
	v_mfma_f32_16x16x32_bf16 v[84:87], v[154:157], v[196:199], v[84:87]
	v_mfma_f32_16x16x32_bf16 v[80:83], v[162:165], v[196:199], v[80:83]
	v_mfma_f32_16x16x32_bf16 v[76:79], v[154:157], v[204:207], v[76:79]
	v_mfma_f32_16x16x32_bf16 v[72:75], v[162:165], v[204:207], v[72:75]
	v_mfma_f32_16x16x32_bf16 v[68:71], v[154:157], v[236:239], v[68:71]
	v_mfma_f32_16x16x32_bf16 v[64:67], v[162:165], v[236:239], v[64:67]
	v_mfma_f32_16x16x32_bf16 v[92:95], v[158:161], v[192:195], v[92:95]
	v_mfma_f32_16x16x32_bf16 v[88:91], v[184:187], v[192:195], v[88:91]
	v_mfma_f32_16x16x32_bf16 v[84:87], v[158:161], v[200:203], v[84:87]
	v_mfma_f32_16x16x32_bf16 v[80:83], v[184:187], v[200:203], v[80:83]
	v_mfma_f32_16x16x32_bf16 v[76:79], v[158:161], v[208:211], v[76:79]
	v_mfma_f32_16x16x32_bf16 v[72:75], v[184:187], v[208:211], v[72:75]
	v_mfma_f32_16x16x32_bf16 v[68:71], v[158:161], v[240:243], v[68:71]
	v_mfma_f32_16x16x32_bf16 v[64:67], v[184:187], v[240:243], v[64:67]
	s_barrier
	s_add_i32 s24, s24, s6
	v_lshl_add_u64 v[166:167], s[48:49], 0, v[168:169]
	s_mov_b32 m0, s24
	ds_read_b128 v[188:191], v234 offset:16384
	ds_read_b128 v[192:195], v234 offset:17408
	ds_read_b128 v[196:199], v234 offset:18432
	ds_read_b128 v[200:203], v234 offset:19456
	ds_read_b128 v[204:207], v234 offset:20480
	ds_read_b128 v[208:211], v234 offset:21504
	ds_read_b128 v[236:239], v234 offset:22528
	ds_read_b128 v[240:243], v234 offset:23552
	global_load_lds_dwordx4 v[166:167], off
	s_add_i32 m0, s24, 0x2000
	s_add_u32 s24, s48, 0x40000
	v_lshl_add_u64 v[170:171], s[48:49], 0, v[128:129]
	s_addc_u32 s25, s49, 0
	s_add_i32 s36, s55, s6
	global_load_lds_dwordx4 v[170:171], off
	v_lshl_add_u64 v[172:173], s[24:25], 0, v[168:169]
	s_mov_b32 m0, s36
	v_lshl_add_u64 v[212:213], vcc, 0, v[130:131]
	global_load_lds_dwordx4 v[172:173], off
	s_add_i32 m0, s36, 0x2000
	v_lshl_add_u64 v[172:173], s[24:25], 0, v[128:129]
	global_load_lds_dwordx4 v[172:173], off
	s_mov_b32 m0, s7
	v_lshl_add_u64 v[172:173], vcc, 0, v[132:133]
	global_load_lds_dwordx4 v[172:173], off
	s_mov_b32 m0, s10
	s_nop 0
	global_load_lds_dwordx4 v[212:213], off
	s_waitcnt vmcnt(8) lgkmcnt(0)
	s_barrier
; #define PG8_STAGE(bufoff, gbase, voff) do { _Pragma("unroll") for (int _i = 0; _i < 2; ++_i) \
;         __builtin_amdgcn_global_load_lds((const unsigned*)((const char*)(gbase) + (voff)[_i]), (LAS unsigned*)(lds + (bufoff) + ldsw + _i * 8192), 16, 0, 0); } while (0)
; #define PG8_LDA(dst, b, h) do { _Pragma("unroll") for (int m = 0; m < 4; ++m) _Pragma("unroll") for (int k = 0; k < 2; ++k) dst[m][k] = *(const LAS bf16x8*)(lds + PG8_SA(b, h) + aoff + m * 2048 + k * 1024); } while (0)
; #define PG8_LDB(dst, b, h) do { _Pragma("unroll") for (int n = 0; n < 2; ++n) _Pragma("unroll") for (int k = 0; k < 2; ++k) dst[n][k] = *(const LAS bf16x8*)(lds + PG8_SB(b, h) + boff + n * 2048 + k * 1024); } while (0)
; #define PG8_MMA(ai, bj, At, Bt) do { __builtin_amdgcn_s_setprio(1); _Pragma("unroll") for (int m = 0; m < 4; ++m) _Pragma("unroll") for (int n = 0; n < 2; ++n) _Pragma("unroll") for (int k = 0; k < 2; ++k) \
;         acc[ai][bj][m][n] = __builtin_amdgcn_mfma_f32_16x16x32_bf16(Bt[n][k], At[m][k], acc[ai][bj][m][n], 0, 0, 0); __builtin_amdgcn_s_setprio(0); } while (0)
; #define PG8_WAIT_V(n) asm volatile("s_waitcnt vmcnt(" #n ")" ::: "memory")
; #define PG8_WAIT_L(n) asm volatile("s_waitcnt lgkmcnt(" #n ")" ::: "memory")
; #define PG8_BAR __builtin_amdgcn_s_barrier()
; #define PG8_SCHED __builtin_amdgcn_sched_barrier(0)
; template <class Epi>
; __device__ __forceinline__ void gemm_phase(LAS unsigned char* lds, const Gemm g, const StaticOrder& S, const Epi& E, const int tid) {
;     ...
;             PG8_WAIT_V(8); PG8_WAIT_L(0); PG8_BAR; PG8_MMA(1, 0, At, B0); PG8_MMA(1, 1, At, B1); PG8_BAR; PG8_SCHED;
;             PG8_LDB(B0, 1, 0); PG8_LDB(B1, 1, 1); PG8_SCHED; PG8_LDA(At, 1, 0); PG8_STAGE(PG8_SA(0, 1), a2 + hsA, voffA);
;             PG8_WAIT_V(8); PG8_WAIT_L(0); PG8_BAR; PG8_MMA(0, 0, At, B0); PG8_MMA(0, 1, At, B1); PG8_BAR; PG8_SCHED;
	v_mfma_f32_16x16x32_bf16 v[60:63], v[138:141], v[188:191], v[60:63]
	v_mfma_f32_16x16x32_bf16 v[56:59], v[146:149], v[188:191], v[56:59]
	v_mfma_f32_16x16x32_bf16 v[52:55], v[138:141], v[196:199], v[52:55]
	v_mfma_f32_16x16x32_bf16 v[48:51], v[146:149], v[196:199], v[48:51]
	v_mfma_f32_16x16x32_bf16 v[44:47], v[138:141], v[204:207], v[44:47]
	v_mfma_f32_16x16x32_bf16 v[40:43], v[146:149], v[204:207], v[40:43]
	v_mfma_f32_16x16x32_bf16 v[36:39], v[138:141], v[236:239], v[36:39]
	v_mfma_f32_16x16x32_bf16 v[32:35], v[146:149], v[236:239], v[32:35]
	v_mfma_f32_16x16x32_bf16 v[60:63], v[142:145], v[192:195], v[60:63]
	v_mfma_f32_16x16x32_bf16 v[56:59], v[150:153], v[192:195], v[56:59]
	v_mfma_f32_16x16x32_bf16 v[52:55], v[142:145], v[200:203], v[52:55]
	v_mfma_f32_16x16x32_bf16 v[48:51], v[150:153], v[200:203], v[48:51]
	v_mfma_f32_16x16x32_bf16 v[44:47], v[142:145], v[208:211], v[44:47]
	v_mfma_f32_16x16x32_bf16 v[40:43], v[150:153], v[208:211], v[40:43]
	v_mfma_f32_16x16x32_bf16 v[36:39], v[142:145], v[240:243], v[36:39]
	v_mfma_f32_16x16x32_bf16 v[32:35], v[150:153], v[240:243], v[32:35]
	v_mfma_f32_16x16x32_bf16 v[28:31], v[154:157], v[188:191], v[28:31]
	v_mfma_f32_16x16x32_bf16 v[24:27], v[162:165], v[188:191], v[24:27]
	v_mfma_f32_16x16x32_bf16 v[20:23], v[154:157], v[196:199], v[20:23]
	v_mfma_f32_16x16x32_bf16 v[16:19], v[162:165], v[196:199], v[16:19]
	v_mfma_f32_16x16x32_bf16 v[12:15], v[154:157], v[204:207], v[12:15]
	v_mfma_f32_16x16x32_bf16 v[8:11], v[162:165], v[204:207], v[8:11]
	v_mfma_f32_16x16x32_bf16 v[4:7], v[154:157], v[236:239], v[4:7]
	v_mfma_f32_16x16x32_bf16 v[0:3], v[162:165], v[236:239], v[0:3]
	v_mfma_f32_16x16x32_bf16 v[28:31], v[158:161], v[192:195], v[28:31]
	v_mfma_f32_16x16x32_bf16 v[24:27], v[184:187], v[192:195], v[24:27]
	v_mfma_f32_16x16x32_bf16 v[20:23], v[158:161], v[200:203], v[20:23]
	v_mfma_f32_16x16x32_bf16 v[16:19], v[184:187], v[200:203], v[16:19]
	v_mfma_f32_16x16x32_bf16 v[12:15], v[158:161], v[208:211], v[12:15]
	v_mfma_f32_16x16x32_bf16 v[8:11], v[184:187], v[208:211], v[8:11]
	v_mfma_f32_16x16x32_bf16 v[4:7], v[158:161], v[240:243], v[4:7]
	v_mfma_f32_16x16x32_bf16 v[0:3], v[184:187], v[240:243], v[0:3]
	s_barrier
	s_add_i32 s36, 0, 0x18000
	s_add_i32 s37, 0, 0x1c000
	v_add_u32_e32 v150, s36, v232
	v_add_u32_e32 v184, s37, v232
	ds_read_b128 v[138:141], v150
	ds_read_b128 v[142:145], v150 offset:1024
	ds_read_b128 v[146:149], v150 offset:2048
	ds_read_b128 v[150:153], v150 offset:3072
	ds_read_b128 v[154:157], v184
	ds_read_b128 v[158:161], v184 offset:1024
	ds_read_b128 v[162:165], v184 offset:2048
	ds_read_b128 v[184:187], v184 offset:3072
	s_add_u32 s24, vcc_lo, 0xc0000
	s_addc_u32 s25, vcc_hi, 0
	s_mov_b32 m0, s11
	v_lshl_add_u64 v[244:245], s[24:25], 0, v[132:133]
	ds_read_b128 v[188:191], v234 offset:32768
	ds_read_b128 v[192:195], v234 offset:33792
	ds_read_b128 v[196:199], v234 offset:34816
	ds_read_b128 v[200:203], v234 offset:35840
	ds_read_b128 v[204:207], v234 offset:36864
	ds_read_b128 v[208:211], v234 offset:37888
	ds_read_b128 v[236:239], v234 offset:38912
	ds_read_b128 v[240:243], v234 offset:39936
	global_load_lds_dwordx4 v[244:245], off
	s_mov_b32 m0, s27
	v_lshl_add_u64 v[244:245], s[24:25], 0, v[130:131]
	global_load_lds_dwordx4 v[244:245], off
	s_waitcnt vmcnt(8) lgkmcnt(0)
	s_barrier
	v_mfma_f32_16x16x32_bf16 v[124:127], v[138:141], v[188:191], v[124:127]
	v_mfma_f32_16x16x32_bf16 v[120:123], v[146:149], v[188:191], v[120:123]
	v_mfma_f32_16x16x32_bf16 v[116:119], v[138:141], v[196:199], v[116:119]
	v_mfma_f32_16x16x32_bf16 v[112:115], v[146:149], v[196:199], v[112:115]
	v_mfma_f32_16x16x32_bf16 v[108:111], v[138:141], v[204:207], v[108:111]
	v_mfma_f32_16x16x32_bf16 v[104:107], v[146:149], v[204:207], v[104:107]
	v_mfma_f32_16x16x32_bf16 v[100:103], v[138:141], v[236:239], v[100:103]
	v_mfma_f32_16x16x32_bf16 v[96:99], v[146:149], v[236:239], v[96:99]
	v_mfma_f32_16x16x32_bf16 v[124:127], v[142:145], v[192:195], v[124:127]
	v_mfma_f32_16x16x32_bf16 v[120:123], v[150:153], v[192:195], v[120:123]
	v_mfma_f32_16x16x32_bf16 v[116:119], v[142:145], v[200:203], v[116:119]
	v_mfma_f32_16x16x32_bf16 v[112:115], v[150:153], v[200:203], v[112:115]
	v_mfma_f32_16x16x32_bf16 v[108:111], v[142:145], v[208:211], v[108:111]
	v_mfma_f32_16x16x32_bf16 v[104:107], v[150:153], v[208:211], v[104:107]
	v_mfma_f32_16x16x32_bf16 v[100:103], v[142:145], v[240:243], v[100:103]
	v_mfma_f32_16x16x32_bf16 v[96:99], v[150:153], v[240:243], v[96:99]
	v_mfma_f32_16x16x32_bf16 v[92:95], v[154:157], v[188:191], v[92:95]
	v_mfma_f32_16x16x32_bf16 v[88:91], v[162:165], v[188:191], v[88:91]
	v_mfma_f32_16x16x32_bf16 v[84:87], v[154:157], v[196:199], v[84:87]
	v_mfma_f32_16x16x32_bf16 v[80:83], v[162:165], v[196:199], v[80:83]
	v_mfma_f32_16x16x32_bf16 v[76:79], v[154:157], v[204:207], v[76:79]
	v_mfma_f32_16x16x32_bf16 v[72:75], v[162:165], v[204:207], v[72:75]
	v_mfma_f32_16x16x32_bf16 v[68:71], v[154:157], v[236:239], v[68:71]
	v_mfma_f32_16x16x32_bf16 v[64:67], v[162:165], v[236:239], v[64:67]
	v_mfma_f32_16x16x32_bf16 v[92:95], v[158:161], v[192:195], v[92:95]
	v_mfma_f32_16x16x32_bf16 v[88:91], v[184:187], v[192:195], v[88:91]
	v_mfma_f32_16x16x32_bf16 v[84:87], v[158:161], v[200:203], v[84:87]
	v_mfma_f32_16x16x32_bf16 v[80:83], v[184:187], v[200:203], v[80:83]
	v_mfma_f32_16x16x32_bf16 v[76:79], v[158:161], v[208:211], v[76:79]
	v_mfma_f32_16x16x32_bf16 v[72:75], v[184:187], v[208:211], v[72:75]
	v_mfma_f32_16x16x32_bf16 v[68:71], v[158:161], v[240:243], v[68:71]
	v_mfma_f32_16x16x32_bf16 v[64:67], v[184:187], v[240:243], v[64:67]
	s_barrier
; #define PG8_STAGE(bufoff, gbase, voff) do { _Pragma("unroll") for (int _i = 0; _i < 2; ++_i) \
;         __builtin_amdgcn_global_load_lds((const unsigned*)((const char*)(gbase) + (voff)[_i]), (LAS unsigned*)(lds + (bufoff) + ldsw + _i * 8192), 16, 0, 0); } while (0)
; #define PG8_LDA(dst, b, h) do { _Pragma("unroll") for (int m = 0; m < 4; ++m) _Pragma("unroll") for (int k = 0; k < 2; ++k) dst[m][k] = *(const LAS bf16x8*)(lds + PG8_SA(b, h) + aoff + m * 2048 + k * 1024); } while (0)
; #define PG8_MMA(ai, bj, At, Bt) do { __builtin_amdgcn_s_setprio(1); _Pragma("unroll") for (int m = 0; m < 4; ++m) _Pragma("unroll") for (int n = 0; n < 2; ++n) _Pragma("unroll") for (int k = 0; k < 2; ++k) \
;         acc[ai][bj][m][n] = __builtin_amdgcn_mfma_f32_16x16x32_bf16(Bt[n][k], At[m][k], acc[ai][bj][m][n], 0, 0, 0); __builtin_amdgcn_s_setprio(0); } while (0)
; #define PG8_WAIT_V(n) asm volatile("s_waitcnt vmcnt(" #n ")" ::: "memory")
; #define PG8_WAIT_L(n) asm volatile("s_waitcnt lgkmcnt(" #n ")" ::: "memory")
; #define PG8_BAR __builtin_amdgcn_s_barrier()
; #define PG8_SCHED __builtin_amdgcn_sched_barrier(0)
; template <class Epi>
; __device__ __forceinline__ void gemm_phase(LAS unsigned char* lds, const Gemm g, const StaticOrder& S, const Epi& E, const int tid) {
;     ...
;             PG8_LDA(At, 1, 1); PG8_STAGE(PG8_SB(1, 0), b3, voffB); PG8_STAGE(PG8_SB(1, 1), b3 + hsB, voffB); PG8_STAGE(PG8_SA(1, 0), a3, voffA);
;             PG8_WAIT_V(8); PG8_WAIT_L(0); PG8_BAR; PG8_MMA(1, 0, At, B0); PG8_MMA(1, 1, At, B1); PG8_BAR; PG8_SCHED;
;         }
;         if (wr == 0) PG8_BAR;
	s_add_i32 s24, s36, s6
	v_lshl_add_u64 v[166:167], v[166:167], 0, s[28:29]
	s_mov_b32 m0, s24
	ds_read_b128 v[188:191], v234 offset:49152
	ds_read_b128 v[192:195], v234 offset:50176
	ds_read_b128 v[196:199], v234 offset:51200
	ds_read_b128 v[200:203], v234 offset:52224
	ds_read_b128 v[204:207], v234 offset:53248
	ds_read_b128 v[208:211], v234 offset:54272
	ds_read_b128 v[236:239], v234 offset:55296
	ds_read_b128 v[240:243], v234 offset:56320
	global_load_lds_dwordx4 v[166:167], off
	s_add_i32 m0, s24, 0x2000
	s_add_u32 s24, s48, 0x40080
	v_lshl_add_u64 v[166:167], v[170:171], 0, s[28:29]
	s_addc_u32 s25, s49, 0
	s_add_i32 s36, s37, s6
	global_load_lds_dwordx4 v[166:167], off
	s_mov_b32 m0, s36
	v_lshl_add_u64 v[166:167], s[24:25], 0, v[168:169]
	global_load_lds_dwordx4 v[166:167], off
	s_add_i32 m0, s36, 0x2000
	v_lshl_add_u64 v[166:167], s[24:25], 0, v[128:129]
	global_load_lds_dwordx4 v[166:167], off
	s_mov_b32 m0, s56
	v_lshl_add_u64 v[166:167], v[172:173], 0, s[28:29]
	global_load_lds_dwordx4 v[166:167], off
	s_mov_b32 m0, s57
	v_lshl_add_u64 v[166:167], v[212:213], 0, s[28:29]
	global_load_lds_dwordx4 v[166:167], off
	s_waitcnt vmcnt(8) lgkmcnt(0)
	s_barrier
	v_mfma_f32_16x16x32_bf16 v[60:63], v[138:141], v[188:191], v[60:63]
	v_mfma_f32_16x16x32_bf16 v[56:59], v[146:149], v[188:191], v[56:59]
	v_mfma_f32_16x16x32_bf16 v[52:55], v[138:141], v[196:199], v[52:55]
	v_mfma_f32_16x16x32_bf16 v[48:51], v[146:149], v[196:199], v[48:51]
	v_mfma_f32_16x16x32_bf16 v[44:47], v[138:141], v[204:207], v[44:47]
	v_mfma_f32_16x16x32_bf16 v[40:43], v[146:149], v[204:207], v[40:43]
	v_mfma_f32_16x16x32_bf16 v[36:39], v[138:141], v[236:239], v[36:39]
	v_mfma_f32_16x16x32_bf16 v[32:35], v[146:149], v[236:239], v[32:35]
	v_mfma_f32_16x16x32_bf16 v[60:63], v[142:145], v[192:195], v[60:63]
	v_mfma_f32_16x16x32_bf16 v[56:59], v[150:153], v[192:195], v[56:59]
	v_mfma_f32_16x16x32_bf16 v[52:55], v[142:145], v[200:203], v[52:55]
	v_mfma_f32_16x16x32_bf16 v[48:51], v[150:153], v[200:203], v[48:51]
	v_mfma_f32_16x16x32_bf16 v[44:47], v[142:145], v[208:211], v[44:47]
	v_mfma_f32_16x16x32_bf16 v[40:43], v[150:153], v[208:211], v[40:43]
	v_mfma_f32_16x16x32_bf16 v[36:39], v[142:145], v[240:243], v[36:39]
	v_mfma_f32_16x16x32_bf16 v[32:35], v[150:153], v[240:243], v[32:35]
	v_mfma_f32_16x16x32_bf16 v[28:31], v[154:157], v[188:191], v[28:31]
	v_mfma_f32_16x16x32_bf16 v[24:27], v[162:165], v[188:191], v[24:27]
	v_mfma_f32_16x16x32_bf16 v[20:23], v[154:157], v[196:199], v[20:23]
	v_mfma_f32_16x16x32_bf16 v[16:19], v[162:165], v[196:199], v[16:19]
	v_mfma_f32_16x16x32_bf16 v[12:15], v[154:157], v[204:207], v[12:15]
	v_mfma_f32_16x16x32_bf16 v[8:11], v[162:165], v[204:207], v[8:11]
	v_mfma_f32_16x16x32_bf16 v[4:7], v[154:157], v[236:239], v[4:7]
	v_mfma_f32_16x16x32_bf16 v[0:3], v[162:165], v[236:239], v[0:3]
	v_mfma_f32_16x16x32_bf16 v[28:31], v[158:161], v[192:195], v[28:31]
	v_mfma_f32_16x16x32_bf16 v[24:27], v[184:187], v[192:195], v[24:27]
	v_mfma_f32_16x16x32_bf16 v[20:23], v[158:161], v[200:203], v[20:23]
	v_mfma_f32_16x16x32_bf16 v[16:19], v[184:187], v[200:203], v[16:19]
	v_mfma_f32_16x16x32_bf16 v[12:15], v[158:161], v[208:211], v[12:15]
	v_mfma_f32_16x16x32_bf16 v[8:11], v[184:187], v[208:211], v[8:11]
	v_mfma_f32_16x16x32_bf16 v[4:7], v[158:161], v[240:243], v[4:7]
	v_mfma_f32_16x16x32_bf16 v[0:3], v[184:187], v[240:243], v[0:3]
	s_barrier
	s_add_i32 s96, s96, 2
	s_add_u32 s68, s68, 0x100
	s_addc_u32 s69, s69, 0
	s_cmp_gt_u32 s96, 13
	s_mov_b64 s[36:37], s[42:43]
	s_cbranch_scc0 .LBB0_823
	s_and_b64 vcc, exec, s[12:13]
	s_cbranch_vccz .LBB0_826
	s_barrier

; #define PG8_STAGE(bufoff, gbase, voff) do { _Pragma("unroll") for (int _i = 0; _i < 2; ++_i) \
;         __builtin_amdgcn_global_load_lds((const unsigned*)((const char*)(gbase) + (voff)[_i]), (LAS unsigned*)(lds + (bufoff) + ldsw + _i * 8192), 16, 0, 0); } while (0)
; #define PG8_LDA(dst, b, h) do { _Pragma("unroll") for (int m = 0; m < 4; ++m) _Pragma("unroll") for (int k = 0; k < 2; ++k) dst[m][k] = *(const LAS bf16x8*)(lds + PG8_SA(b, h) + aoff + m * 2048 + k * 1024); } while (0)
; #define PG8_LDB(dst, b, h) do { _Pragma("unroll") for (int n = 0; n < 2; ++n) _Pragma("unroll") for (int k = 0; k < 2; ++k) dst[n][k] = *(const LAS bf16x8*)(lds + PG8_SB(b, h) + boff + n * 2048 + k * 1024); } while (0)
; #define PG8_MMA(ai, bj, At, Bt) do { __builtin_amdgcn_s_setprio(1); _Pragma("unroll") for (int m = 0; m < 4; ++m) _Pragma("unroll") for (int n = 0; n < 2; ++n) _Pragma("unroll") for (int k = 0; k < 2; ++k) \
;         acc[ai][bj][m][n] = __builtin_amdgcn_mfma_f32_16x16x32_bf16(Bt[n][k], At[m][k], acc[ai][bj][m][n], 0, 0, 0); __builtin_amdgcn_s_setprio(0); } while (0)
; #define PG8_WAIT_V(n) asm volatile("s_waitcnt vmcnt(" #n ")" ::: "memory")
; #define PG8_WAIT_L(n) asm volatile("s_waitcnt lgkmcnt(" #n ")" ::: "memory")
; #define PG8_BAR __builtin_amdgcn_s_barrier()
; #define PG8_SCHED __builtin_amdgcn_sched_barrier(0)
; template <class Epi>
; __device__ __forceinline__ void gemm_phase(LAS unsigned char* lds, const Gemm g, const StaticOrder& S, const Epi& E, const int tid) {
;     ...
;             const bool last = (t == nt - 2);
;             const char* a1 = cA + (size_t)(t + 1) * kstep;
;             const char* a2 = last ? nA : cA + (size_t)(t + 2) * kstep; const char* b2 = last ? nB : cB + (size_t)(t + 2) * kstep;
;             const char* a3 = a2 + kstep; const char* b3 = b2 + kstep;
;             PG8_LDB(B0, 0, 0); PG8_LDB(B1, 0, 1); PG8_SCHED; PG8_LDA(At, 0, 0); PG8_STAGE(PG8_SA(1, 1), a1 + hsA, voffA);
;             PG8_WAIT_V(8); PG8_WAIT_L(0); PG8_BAR; PG8_MMA(0, 0, At, B0); PG8_MMA(0, 1, At, B1); PG8_BAR; PG8_SCHED;
;             PG8_LDA(At, 0, 1); PG8_STAGE(PG8_SB(0, 0), b2, voffB); PG8_STAGE(PG8_SB(0, 1), b2 + hsB, voffB); PG8_STAGE(PG8_SA(0, 0), a2, voffA);
.Lgprio_e:
.LBB0_893:
	s_add_u32 s0, s16, 0xfff80080
	s_addc_u32 s1, s17, -1
	s_add_i32 s2, 0, 0x10000
	s_cmp_eq_u32 s57, 28
	s_cselect_b32 s19, s11, s1
	s_cselect_b32 s18, s49, s0
	s_cselect_b32 s1, s9, s56
	s_cselect_b32 s0, s52, s53
	s_add_i32 s55, 0, 0x14000
	v_add_u32_e32 v76, s2, v204
	v_add_u32_e32 v156, s55, v204
	ds_read_b128 v[64:67], v76
	ds_read_b128 v[68:71], v76 offset:1024
	ds_read_b128 v[72:75], v76 offset:2048
	ds_read_b128 v[76:79], v76 offset:3072
	ds_read_b128 v[144:147], v156
	ds_read_b128 v[148:151], v156 offset:1024
	ds_read_b128 v[152:155], v156 offset:2048
	ds_read_b128 v[156:159], v156 offset:3072
	v_lshl_add_u64 v[170:171], s[16:17], 0, v[192:193]
	s_add_i32 m0, s36, 0xc000
	ds_read_b128 v[160:163], v209
	ds_read_b128 v[164:167], v209 offset:1024
	ds_read_b128 v[196:199], v209 offset:2048
	ds_read_b128 v[200:203], v209 offset:3072
	ds_read_b128 v[210:213], v209 offset:4096
	ds_read_b128 v[230:233], v209 offset:5120
	ds_read_b128 v[234:237], v209 offset:6144
	ds_read_b128 v[238:241], v209 offset:7168
	global_load_lds_dwordx4 v[170:171], off
	s_add_i32 m0, s36, 0xe000
	v_lshl_add_u64 v[170:171], s[16:17], 0, v[194:195]
	global_load_lds_dwordx4 v[170:171], off
	s_waitcnt vmcnt(8) lgkmcnt(0)
	s_barrier
	v_mfma_f32_16x16x32_bf16 v[140:143], v[64:67], v[160:163], v[140:143]
	v_mfma_f32_16x16x32_bf16 v[136:139], v[72:75], v[160:163], v[136:139]
	v_mfma_f32_16x16x32_bf16 v[124:127], v[64:67], v[196:199], v[124:127]
	v_mfma_f32_16x16x32_bf16 v[120:123], v[72:75], v[196:199], v[120:123]
	v_mfma_f32_16x16x32_bf16 v[108:111], v[64:67], v[210:213], v[108:111]
	v_mfma_f32_16x16x32_bf16 v[104:107], v[72:75], v[210:213], v[104:107]
	v_mfma_f32_16x16x32_bf16 v[96:99], v[64:67], v[234:237], v[96:99]
	v_mfma_f32_16x16x32_bf16 v[88:91], v[72:75], v[234:237], v[88:91]
	v_mfma_f32_16x16x32_bf16 v[140:143], v[68:71], v[164:167], v[140:143]
	v_mfma_f32_16x16x32_bf16 v[136:139], v[76:79], v[164:167], v[136:139]
	v_mfma_f32_16x16x32_bf16 v[124:127], v[68:71], v[200:203], v[124:127]
	v_mfma_f32_16x16x32_bf16 v[120:123], v[76:79], v[200:203], v[120:123]
	v_mfma_f32_16x16x32_bf16 v[108:111], v[68:71], v[230:233], v[108:111]
	v_mfma_f32_16x16x32_bf16 v[104:107], v[76:79], v[230:233], v[104:107]
	v_mfma_f32_16x16x32_bf16 v[96:99], v[68:71], v[238:241], v[96:99]
	v_mfma_f32_16x16x32_bf16 v[88:91], v[76:79], v[238:241], v[88:91]
	v_mfma_f32_16x16x32_bf16 v[132:135], v[144:147], v[160:163], v[132:135]
	v_mfma_f32_16x16x32_bf16 v[128:131], v[152:155], v[160:163], v[128:131]
	v_mfma_f32_16x16x32_bf16 v[116:119], v[144:147], v[196:199], v[116:119]
	v_mfma_f32_16x16x32_bf16 v[112:115], v[152:155], v[196:199], v[112:115]
	v_mfma_f32_16x16x32_bf16 v[100:103], v[144:147], v[210:213], v[100:103]
	v_mfma_f32_16x16x32_bf16 v[92:95], v[152:155], v[210:213], v[92:95]
	v_mfma_f32_16x16x32_bf16 v[84:87], v[144:147], v[234:237], v[84:87]
	v_mfma_f32_16x16x32_bf16 v[80:83], v[152:155], v[234:237], v[80:83]
	v_mfma_f32_16x16x32_bf16 v[132:135], v[148:151], v[164:167], v[132:135]
	v_mfma_f32_16x16x32_bf16 v[128:131], v[156:159], v[164:167], v[128:131]
	v_mfma_f32_16x16x32_bf16 v[116:119], v[148:151], v[200:203], v[116:119]
	v_mfma_f32_16x16x32_bf16 v[112:115], v[156:159], v[200:203], v[112:115]
	v_mfma_f32_16x16x32_bf16 v[100:103], v[148:151], v[230:233], v[100:103]
	v_mfma_f32_16x16x32_bf16 v[92:95], v[156:159], v[230:233], v[92:95]
	v_mfma_f32_16x16x32_bf16 v[84:87], v[148:151], v[238:241], v[84:87]
	v_mfma_f32_16x16x32_bf16 v[80:83], v[156:159], v[238:241], v[80:83]
	s_barrier
	s_add_i32 s2, s2, s35
	v_lshl_add_u64 v[170:171], s[0:1], 0, v[188:189]
	s_mov_b32 m0, s2
	ds_read_b128 v[160:163], v209 offset:16384
	ds_read_b128 v[164:167], v209 offset:17408
	ds_read_b128 v[196:199], v209 offset:18432
	ds_read_b128 v[200:203], v209 offset:19456
	ds_read_b128 v[210:213], v209 offset:20480
	ds_read_b128 v[230:233], v209 offset:21504
	ds_read_b128 v[234:237], v209 offset:22528
	ds_read_b128 v[238:241], v209 offset:23552
	global_load_lds_dwordx4 v[170:171], off
	s_add_i32 m0, s2, 0x2000
	s_add_u32 s24, s0, 0x80000
	v_lshl_add_u64 v[172:173], s[0:1], 0, v[184:185]
	s_addc_u32 s25, s1, 0
	s_add_i32 s2, s55, s35
	global_load_lds_dwordx4 v[172:173], off
	v_lshl_add_u64 v[242:243], s[24:25], 0, v[188:189]
	s_mov_b32 m0, s2
	v_lshl_add_u64 v[244:245], s[18:19], 0, v[186:187]
	global_load_lds_dwordx4 v[242:243], off
	s_add_i32 m0, s2, 0x2000
	v_lshl_add_u64 v[242:243], s[24:25], 0, v[184:185]
	global_load_lds_dwordx4 v[242:243], off
	s_mov_b32 m0, s36
	v_lshl_add_u64 v[242:243], s[18:19], 0, v[190:191]
	global_load_lds_dwordx4 v[242:243], off
	s_mov_b32 m0, s37
	s_nop 0
	global_load_lds_dwordx4 v[244:245], off
	s_waitcnt vmcnt(8) lgkmcnt(0)
	s_barrier
; #define PG8_STAGE(bufoff, gbase, voff) do { _Pragma("unroll") for (int _i = 0; _i < 2; ++_i) \
;         __builtin_amdgcn_global_load_lds((const unsigned*)((const char*)(gbase) + (voff)[_i]), (LAS unsigned*)(lds + (bufoff) + ldsw + _i * 8192), 16, 0, 0); } while (0)
; #define PG8_LDA(dst, b, h) do { _Pragma("unroll") for (int m = 0; m < 4; ++m) _Pragma("unroll") for (int k = 0; k < 2; ++k) dst[m][k] = *(const LAS bf16x8*)(lds + PG8_SA(b, h) + aoff + m * 2048 + k * 1024); } while (0)
; #define PG8_LDB(dst, b, h) do { _Pragma("unroll") for (int n = 0; n < 2; ++n) _Pragma("unroll") for (int k = 0; k < 2; ++k) dst[n][k] = *(const LAS bf16x8*)(lds + PG8_SB(b, h) + boff + n * 2048 + k * 1024); } while (0)
; #define PG8_MMA(ai, bj, At, Bt) do { __builtin_amdgcn_s_setprio(1); _Pragma("unroll") for (int m = 0; m < 4; ++m) _Pragma("unroll") for (int n = 0; n < 2; ++n) _Pragma("unroll") for (int k = 0; k < 2; ++k) \
;         acc[ai][bj][m][n] = __builtin_amdgcn_mfma_f32_16x16x32_bf16(Bt[n][k], At[m][k], acc[ai][bj][m][n], 0, 0, 0); __builtin_amdgcn_s_setprio(0); } while (0)
; #define PG8_WAIT_V(n) asm volatile("s_waitcnt vmcnt(" #n ")" ::: "memory")
; #define PG8_WAIT_L(n) asm volatile("s_waitcnt lgkmcnt(" #n ")" ::: "memory")
; #define PG8_BAR __builtin_amdgcn_s_barrier()
; #define PG8_SCHED __builtin_amdgcn_sched_barrier(0)
; template <class Epi>
; __device__ __forceinline__ void gemm_phase(LAS unsigned char* lds, const Gemm g, const StaticOrder& S, const Epi& E, const int tid) {
;     ...
;             PG8_WAIT_V(8); PG8_WAIT_L(0); PG8_BAR; PG8_MMA(1, 0, At, B0); PG8_MMA(1, 1, At, B1); PG8_BAR; PG8_SCHED;
;             PG8_LDB(B0, 1, 0); PG8_LDB(B1, 1, 1); PG8_SCHED; PG8_LDA(At, 1, 0); PG8_STAGE(PG8_SA(0, 1), a2 + hsA, voffA);
;             PG8_WAIT_V(8); PG8_WAIT_L(0); PG8_BAR; PG8_MMA(0, 0, At, B0); PG8_MMA(0, 1, At, B1); PG8_BAR; PG8_SCHED;
	v_mfma_f32_16x16x32_bf16 v[60:63], v[64:67], v[160:163], v[60:63]
	v_mfma_f32_16x16x32_bf16 v[56:59], v[72:75], v[160:163], v[56:59]
	v_mfma_f32_16x16x32_bf16 v[44:47], v[64:67], v[196:199], v[44:47]
	v_mfma_f32_16x16x32_bf16 v[40:43], v[72:75], v[196:199], v[40:43]
	v_mfma_f32_16x16x32_bf16 v[28:31], v[64:67], v[210:213], v[28:31]
	v_mfma_f32_16x16x32_bf16 v[24:27], v[72:75], v[210:213], v[24:27]
	v_mfma_f32_16x16x32_bf16 v[12:15], v[64:67], v[234:237], v[12:15]
	v_mfma_f32_16x16x32_bf16 v[8:11], v[72:75], v[234:237], v[8:11]
	v_mfma_f32_16x16x32_bf16 v[60:63], v[68:71], v[164:167], v[60:63]
	v_mfma_f32_16x16x32_bf16 v[56:59], v[76:79], v[164:167], v[56:59]
	v_mfma_f32_16x16x32_bf16 v[44:47], v[68:71], v[200:203], v[44:47]
	v_mfma_f32_16x16x32_bf16 v[40:43], v[76:79], v[200:203], v[40:43]
	v_mfma_f32_16x16x32_bf16 v[28:31], v[68:71], v[230:233], v[28:31]
	v_mfma_f32_16x16x32_bf16 v[24:27], v[76:79], v[230:233], v[24:27]
	v_mfma_f32_16x16x32_bf16 v[12:15], v[68:71], v[238:241], v[12:15]
	v_mfma_f32_16x16x32_bf16 v[8:11], v[76:79], v[238:241], v[8:11]
	v_mfma_f32_16x16x32_bf16 v[52:55], v[144:147], v[160:163], v[52:55]
	v_mfma_f32_16x16x32_bf16 v[48:51], v[152:155], v[160:163], v[48:51]
	v_mfma_f32_16x16x32_bf16 v[36:39], v[144:147], v[196:199], v[36:39]
	v_mfma_f32_16x16x32_bf16 v[32:35], v[152:155], v[196:199], v[32:35]
	v_mfma_f32_16x16x32_bf16 v[20:23], v[144:147], v[210:213], v[20:23]
	v_mfma_f32_16x16x32_bf16 v[16:19], v[152:155], v[210:213], v[16:19]
	v_mfma_f32_16x16x32_bf16 v[4:7], v[144:147], v[234:237], v[4:7]
	v_mfma_f32_16x16x32_bf16 v[0:3], v[152:155], v[234:237], v[0:3]
	v_mfma_f32_16x16x32_bf16 v[52:55], v[148:151], v[164:167], v[52:55]
	v_mfma_f32_16x16x32_bf16 v[48:51], v[156:159], v[164:167], v[48:51]
	v_mfma_f32_16x16x32_bf16 v[36:39], v[148:151], v[200:203], v[36:39]
	v_mfma_f32_16x16x32_bf16 v[32:35], v[156:159], v[200:203], v[32:35]
	v_mfma_f32_16x16x32_bf16 v[20:23], v[148:151], v[230:233], v[20:23]
	v_mfma_f32_16x16x32_bf16 v[16:19], v[156:159], v[230:233], v[16:19]
	v_mfma_f32_16x16x32_bf16 v[4:7], v[148:151], v[238:241], v[4:7]
	v_mfma_f32_16x16x32_bf16 v[0:3], v[156:159], v[238:241], v[0:3]
	s_barrier
	s_add_i32 s2, 0, 0x18000
	s_add_i32 s24, 0, 0x1c000
	v_add_u32_e32 v76, s2, v204
	v_add_u32_e32 v156, s24, v204
	ds_read_b128 v[64:67], v76
	ds_read_b128 v[68:71], v76 offset:1024
	ds_read_b128 v[72:75], v76 offset:2048
	ds_read_b128 v[76:79], v76 offset:3072
	ds_read_b128 v[144:147], v156
	ds_read_b128 v[148:151], v156 offset:1024
	ds_read_b128 v[152:155], v156 offset:2048
	ds_read_b128 v[156:159], v156 offset:3072
	s_add_u32 s18, s18, 0x80000
	s_addc_u32 s19, s19, 0
	s_mov_b32 m0, s38
	v_lshl_add_u64 v[246:247], s[18:19], 0, v[190:191]
	ds_read_b128 v[160:163], v209 offset:32768
	ds_read_b128 v[164:167], v209 offset:33792
	ds_read_b128 v[196:199], v209 offset:34816
	ds_read_b128 v[200:203], v209 offset:35840
	ds_read_b128 v[210:213], v209 offset:36864
	ds_read_b128 v[230:233], v209 offset:37888
	ds_read_b128 v[234:237], v209 offset:38912
	ds_read_b128 v[238:241], v209 offset:39936
	global_load_lds_dwordx4 v[246:247], off
	s_mov_b32 m0, s39
	v_lshl_add_u64 v[246:247], s[18:19], 0, v[186:187]
	global_load_lds_dwordx4 v[246:247], off
	s_waitcnt vmcnt(8) lgkmcnt(0)
	s_barrier
	v_mfma_f32_16x16x32_bf16 v[140:143], v[64:67], v[160:163], v[140:143]
	v_mfma_f32_16x16x32_bf16 v[136:139], v[72:75], v[160:163], v[136:139]
	v_mfma_f32_16x16x32_bf16 v[124:127], v[64:67], v[196:199], v[124:127]
	v_mfma_f32_16x16x32_bf16 v[120:123], v[72:75], v[196:199], v[120:123]
	v_mfma_f32_16x16x32_bf16 v[108:111], v[64:67], v[210:213], v[108:111]
	v_mfma_f32_16x16x32_bf16 v[104:107], v[72:75], v[210:213], v[104:107]
	v_mfma_f32_16x16x32_bf16 v[96:99], v[64:67], v[234:237], v[96:99]
	v_mfma_f32_16x16x32_bf16 v[88:91], v[72:75], v[234:237], v[88:91]
	v_mfma_f32_16x16x32_bf16 v[140:143], v[68:71], v[164:167], v[140:143]
	v_mfma_f32_16x16x32_bf16 v[136:139], v[76:79], v[164:167], v[136:139]
	v_mfma_f32_16x16x32_bf16 v[124:127], v[68:71], v[200:203], v[124:127]
	v_mfma_f32_16x16x32_bf16 v[120:123], v[76:79], v[200:203], v[120:123]
	v_mfma_f32_16x16x32_bf16 v[108:111], v[68:71], v[230:233], v[108:111]
	v_mfma_f32_16x16x32_bf16 v[104:107], v[76:79], v[230:233], v[104:107]
	v_mfma_f32_16x16x32_bf16 v[96:99], v[68:71], v[238:241], v[96:99]
	v_mfma_f32_16x16x32_bf16 v[88:91], v[76:79], v[238:241], v[88:91]
	v_mfma_f32_16x16x32_bf16 v[132:135], v[144:147], v[160:163], v[132:135]
	v_mfma_f32_16x16x32_bf16 v[128:131], v[152:155], v[160:163], v[128:131]
	v_mfma_f32_16x16x32_bf16 v[116:119], v[144:147], v[196:199], v[116:119]
	v_mfma_f32_16x16x32_bf16 v[112:115], v[152:155], v[196:199], v[112:115]
	v_mfma_f32_16x16x32_bf16 v[100:103], v[144:147], v[210:213], v[100:103]
	v_mfma_f32_16x16x32_bf16 v[92:95], v[152:155], v[210:213], v[92:95]
	v_mfma_f32_16x16x32_bf16 v[84:87], v[144:147], v[234:237], v[84:87]
	v_mfma_f32_16x16x32_bf16 v[80:83], v[152:155], v[234:237], v[80:83]
	v_mfma_f32_16x16x32_bf16 v[132:135], v[148:151], v[164:167], v[132:135]
	v_mfma_f32_16x16x32_bf16 v[128:131], v[156:159], v[164:167], v[128:131]
	v_mfma_f32_16x16x32_bf16 v[116:119], v[148:151], v[200:203], v[116:119]
	v_mfma_f32_16x16x32_bf16 v[112:115], v[156:159], v[200:203], v[112:115]
	v_mfma_f32_16x16x32_bf16 v[100:103], v[148:151], v[230:233], v[100:103]
	v_mfma_f32_16x16x32_bf16 v[92:95], v[156:159], v[230:233], v[92:95]
	v_mfma_f32_16x16x32_bf16 v[84:87], v[148:151], v[238:241], v[84:87]
	v_mfma_f32_16x16x32_bf16 v[80:83], v[156:159], v[238:241], v[80:83]
	s_barrier
; #define PG8_STAGE(bufoff, gbase, voff) do { _Pragma("unroll") for (int _i = 0; _i < 2; ++_i) \
;         __builtin_amdgcn_global_load_lds((const unsigned*)((const char*)(gbase) + (voff)[_i]), (LAS unsigned*)(lds + (bufoff) + ldsw + _i * 8192), 16, 0, 0); } while (0)
; #define PG8_LDA(dst, b, h) do { _Pragma("unroll") for (int m = 0; m < 4; ++m) _Pragma("unroll") for (int k = 0; k < 2; ++k) dst[m][k] = *(const LAS bf16x8*)(lds + PG8_SA(b, h) + aoff + m * 2048 + k * 1024); } while (0)
; #define PG8_MMA(ai, bj, At, Bt) do { __builtin_amdgcn_s_setprio(1); _Pragma("unroll") for (int m = 0; m < 4; ++m) _Pragma("unroll") for (int n = 0; n < 2; ++n) _Pragma("unroll") for (int k = 0; k < 2; ++k) \
;         acc[ai][bj][m][n] = __builtin_amdgcn_mfma_f32_16x16x32_bf16(Bt[n][k], At[m][k], acc[ai][bj][m][n], 0, 0, 0); __builtin_amdgcn_s_setprio(0); } while (0)
; #define PG8_WAIT_V(n) asm volatile("s_waitcnt vmcnt(" #n ")" ::: "memory")
; #define PG8_WAIT_L(n) asm volatile("s_waitcnt lgkmcnt(" #n ")" ::: "memory")
; #define PG8_BAR __builtin_amdgcn_s_barrier()
; #define PG8_SCHED __builtin_amdgcn_sched_barrier(0)
; template <class Epi>
; __device__ __forceinline__ void gemm_phase(LAS unsigned char* lds, const Gemm g, const StaticOrder& S, const Epi& E, const int tid) {
;     ...
;             PG8_LDA(At, 1, 1); PG8_STAGE(PG8_SB(1, 0), b3, voffB); PG8_STAGE(PG8_SB(1, 1), b3 + hsB, voffB); PG8_STAGE(PG8_SA(1, 0), a3, voffA);
;             PG8_WAIT_V(8); PG8_WAIT_L(0); PG8_BAR; PG8_MMA(1, 0, At, B0); PG8_MMA(1, 1, At, B1); PG8_BAR; PG8_SCHED;
;         }
;         if (wr == 0) PG8_BAR;
	s_add_i32 s2, s2, s35
	v_lshl_add_u64 v[170:171], v[170:171], 0, s[28:29]
	s_mov_b32 m0, s2
	ds_read_b128 v[160:163], v209 offset:49152
	ds_read_b128 v[164:167], v209 offset:50176
	ds_read_b128 v[196:199], v209 offset:51200
	ds_read_b128 v[200:203], v209 offset:52224
	ds_read_b128 v[210:213], v209 offset:53248
	ds_read_b128 v[230:233], v209 offset:54272
	ds_read_b128 v[234:237], v209 offset:55296
	ds_read_b128 v[238:241], v209 offset:56320
	global_load_lds_dwordx4 v[170:171], off
	s_add_i32 m0, s2, 0x2000
	s_add_u32 s0, s0, 0x80080
	v_lshl_add_u64 v[170:171], v[172:173], 0, s[28:29]
	s_addc_u32 s1, s1, 0
	s_add_i32 s2, s24, s35
	global_load_lds_dwordx4 v[170:171], off
	s_mov_b32 m0, s2
	v_lshl_add_u64 v[170:171], s[0:1], 0, v[188:189]
	global_load_lds_dwordx4 v[170:171], off
	s_add_i32 m0, s2, 0x2000
	v_lshl_add_u64 v[170:171], s[0:1], 0, v[184:185]
	global_load_lds_dwordx4 v[170:171], off
	s_mov_b32 m0, s44
	v_lshl_add_u64 v[170:171], v[242:243], 0, s[28:29]
	global_load_lds_dwordx4 v[170:171], off
	s_mov_b32 m0, s45
	v_lshl_add_u64 v[170:171], v[244:245], 0, s[28:29]
	global_load_lds_dwordx4 v[170:171], off
	s_waitcnt vmcnt(8) lgkmcnt(0)
	s_barrier
	v_mfma_f32_16x16x32_bf16 v[60:63], v[64:67], v[160:163], v[60:63]
	v_mfma_f32_16x16x32_bf16 v[56:59], v[72:75], v[160:163], v[56:59]
	v_mfma_f32_16x16x32_bf16 v[44:47], v[64:67], v[196:199], v[44:47]
	v_mfma_f32_16x16x32_bf16 v[40:43], v[72:75], v[196:199], v[40:43]
	v_mfma_f32_16x16x32_bf16 v[28:31], v[64:67], v[210:213], v[28:31]
	v_mfma_f32_16x16x32_bf16 v[24:27], v[72:75], v[210:213], v[24:27]
	v_mfma_f32_16x16x32_bf16 v[12:15], v[64:67], v[234:237], v[12:15]
	v_mfma_f32_16x16x32_bf16 v[8:11], v[72:75], v[234:237], v[8:11]
	v_mfma_f32_16x16x32_bf16 v[60:63], v[68:71], v[164:167], v[60:63]
	v_mfma_f32_16x16x32_bf16 v[56:59], v[76:79], v[164:167], v[56:59]
	v_mfma_f32_16x16x32_bf16 v[44:47], v[68:71], v[200:203], v[44:47]
	v_mfma_f32_16x16x32_bf16 v[40:43], v[76:79], v[200:203], v[40:43]
	v_mfma_f32_16x16x32_bf16 v[28:31], v[68:71], v[230:233], v[28:31]
	v_mfma_f32_16x16x32_bf16 v[24:27], v[76:79], v[230:233], v[24:27]
	v_mfma_f32_16x16x32_bf16 v[12:15], v[68:71], v[238:241], v[12:15]
	v_mfma_f32_16x16x32_bf16 v[8:11], v[76:79], v[238:241], v[8:11]
	v_mfma_f32_16x16x32_bf16 v[52:55], v[144:147], v[160:163], v[52:55]
	v_mfma_f32_16x16x32_bf16 v[48:51], v[152:155], v[160:163], v[48:51]
	v_mfma_f32_16x16x32_bf16 v[36:39], v[144:147], v[196:199], v[36:39]
	v_mfma_f32_16x16x32_bf16 v[32:35], v[152:155], v[196:199], v[32:35]
	v_mfma_f32_16x16x32_bf16 v[20:23], v[144:147], v[210:213], v[20:23]
	v_mfma_f32_16x16x32_bf16 v[16:19], v[152:155], v[210:213], v[16:19]
	v_mfma_f32_16x16x32_bf16 v[4:7], v[144:147], v[234:237], v[4:7]
	v_mfma_f32_16x16x32_bf16 v[0:3], v[152:155], v[234:237], v[0:3]
	v_mfma_f32_16x16x32_bf16 v[52:55], v[148:151], v[164:167], v[52:55]
	v_mfma_f32_16x16x32_bf16 v[48:51], v[156:159], v[164:167], v[48:51]
	v_mfma_f32_16x16x32_bf16 v[36:39], v[148:151], v[200:203], v[36:39]
	v_mfma_f32_16x16x32_bf16 v[32:35], v[156:159], v[200:203], v[32:35]
	v_mfma_f32_16x16x32_bf16 v[20:23], v[148:151], v[230:233], v[20:23]
	v_mfma_f32_16x16x32_bf16 v[16:19], v[156:159], v[230:233], v[16:19]
	v_mfma_f32_16x16x32_bf16 v[4:7], v[148:151], v[238:241], v[4:7]
	v_mfma_f32_16x16x32_bf16 v[0:3], v[156:159], v[238:241], v[0:3]
	s_barrier
	s_add_i32 s57, s57, 2
	s_add_u32 s16, s16, 0x100
	s_addc_u32 s17, s17, 0
	s_add_u32 s53, s53, 0x100
	s_addc_u32 s56, s56, 0
	s_cmp_gt_u32 s57, 29
	s_cbranch_scc0 .LBB0_893
	s_and_b64 vcc, exec, s[6:7]
	s_movk_i32 s49, 0x300
	s_mov_b64 s[52:53], 0x60000
	s_cbranch_vccz .LBB0_896
	s_barrier

; #define PG8_STAGE(bufoff, gbase, voff) do { _Pragma("unroll") for (int _i = 0; _i < 2; ++_i) \
;         __builtin_amdgcn_global_load_lds((const unsigned*)((const char*)(gbase) + (voff)[_i]), (LAS unsigned*)(lds + (bufoff) + ldsw + _i * 8192), 16, 0, 0); } while (0)
; #define PG8_LDA(dst, b, h) do { _Pragma("unroll") for (int m = 0; m < 4; ++m) _Pragma("unroll") for (int k = 0; k < 2; ++k) dst[m][k] = *(const LAS bf16x8*)(lds + PG8_SA(b, h) + aoff + m * 2048 + k * 1024); } while (0)
; #define PG8_LDB(dst, b, h) do { _Pragma("unroll") for (int n = 0; n < 2; ++n) _Pragma("unroll") for (int k = 0; k < 2; ++k) dst[n][k] = *(const LAS bf16x8*)(lds + PG8_SB(b, h) + boff + n * 2048 + k * 1024); } while (0)
; #define PG8_MMA(ai, bj, At, Bt) do { __builtin_amdgcn_s_setprio(1); _Pragma("unroll") for (int m = 0; m < 4; ++m) _Pragma("unroll") for (int n = 0; n < 2; ++n) _Pragma("unroll") for (int k = 0; k < 2; ++k) \
;         acc[ai][bj][m][n] = __builtin_amdgcn_mfma_f32_16x16x32_bf16(Bt[n][k], At[m][k], acc[ai][bj][m][n], 0, 0, 0); __builtin_amdgcn_s_setprio(0); } while (0)
; #define PG8_WAIT_V(n) asm volatile("s_waitcnt vmcnt(" #n ")" ::: "memory")
; #define PG8_WAIT_L(n) asm volatile("s_waitcnt lgkmcnt(" #n ")" ::: "memory")
; #define PG8_BAR __builtin_amdgcn_s_barrier()
; #define PG8_SCHED __builtin_amdgcn_sched_barrier(0)
; template <class Epi>
; __device__ __forceinline__ void gemm_phase(LAS unsigned char* lds, const Gemm g, const StaticOrder& S, const Epi& E, const int tid) {
;     ...
;             const bool last = (t == nt - 2);
;             const char* a1 = cA + (size_t)(t + 1) * kstep;
;             const char* a2 = last ? nA : cA + (size_t)(t + 2) * kstep; const char* b2 = last ? nB : cB + (size_t)(t + 2) * kstep;
;             const char* a3 = a2 + kstep; const char* b3 = b2 + kstep;
;             PG8_LDB(B0, 0, 0); PG8_LDB(B1, 0, 1); PG8_SCHED; PG8_LDA(At, 0, 0); PG8_STAGE(PG8_SA(1, 1), a1 + hsA, voffA);
;             PG8_WAIT_V(8); PG8_WAIT_L(0); PG8_BAR; PG8_MMA(0, 0, At, B0); PG8_MMA(0, 1, At, B1); PG8_BAR; PG8_SCHED;
;             PG8_LDA(At, 0, 1); PG8_STAGE(PG8_SB(0, 0), b2, voffB); PG8_STAGE(PG8_SB(0, 1), b2 + hsB, voffB); PG8_STAGE(PG8_SA(0, 0), a2, voffA);
;             PG8_WAIT_V(8); PG8_WAIT_L(0); PG8_BAR; PG8_MMA(1, 0, At, B0); PG8_MMA(1, 1, At, B1); PG8_BAR; PG8_SCHED;
.Lgprio_f:
	s_add_u32 s0, s18, 0xfff80080
	s_addc_u32 s1, s19, -1
	s_add_i32 s2, 0, 0x10000
	s_cmp_eq_u32 s57, 28
	s_cselect_b32 s35, s13, s1
	s_cselect_b32 s34, s49, s0
	s_cselect_b32 s1, s11, s56
	s_cselect_b32 s0, s52, s53
	s_add_i32 s55, 0, 0x14000
	v_add_u32_e32 v154, s2, v143
	v_add_u32_e32 v166, s55, v143
	ds_read_b128 v[138:141], v154
	ds_read_b128 v[146:149], v154 offset:1024
	ds_read_b128 v[150:153], v154 offset:2048
	ds_read_b128 v[154:157], v154 offset:3072
	ds_read_b128 v[158:161], v166
	ds_read_b128 v[162:165], v166 offset:1024
	ds_read_b128 v[184:187], v166 offset:2048
	ds_read_b128 v[188:191], v166 offset:3072
	v_lshl_add_u64 v[166:167], s[18:19], 0, v[134:135]
	s_add_i32 m0, s40, 0xc000
	ds_read_b128 v[192:195], v145
	ds_read_b128 v[196:199], v145 offset:1024
	ds_read_b128 v[200:203], v145 offset:2048
	ds_read_b128 v[204:207], v145 offset:3072
	ds_read_b128 v[208:211], v145 offset:4096
	ds_read_b128 v[230:233], v145 offset:5120
	ds_read_b128 v[234:237], v145 offset:6144
	ds_read_b128 v[238:241], v145 offset:7168
	global_load_lds_dwordx4 v[166:167], off
	s_add_i32 m0, s40, 0xe000
	v_lshl_add_u64 v[166:167], s[18:19], 0, v[136:137]
	global_load_lds_dwordx4 v[166:167], off
	s_waitcnt vmcnt(8) lgkmcnt(0)
	s_barrier
	v_mfma_f32_16x16x32_bf16 v[124:127], v[138:141], v[192:195], 0
	v_mfma_f32_16x16x32_bf16 v[116:119], v[150:153], v[192:195], 0
	v_mfma_f32_16x16x32_bf16 v[108:111], v[138:141], v[200:203], 0
	v_mfma_f32_16x16x32_bf16 v[100:103], v[150:153], v[200:203], 0
	v_mfma_f32_16x16x32_bf16 v[92:95], v[138:141], v[208:211], 0
	v_mfma_f32_16x16x32_bf16 v[84:87], v[150:153], v[208:211], 0
	v_mfma_f32_16x16x32_bf16 v[76:79], v[138:141], v[234:237], 0
	v_mfma_f32_16x16x32_bf16 v[68:71], v[150:153], v[234:237], 0
	v_mfma_f32_16x16x32_bf16 v[124:127], v[146:149], v[196:199], v[124:127]
	v_mfma_f32_16x16x32_bf16 v[116:119], v[154:157], v[196:199], v[116:119]
	v_mfma_f32_16x16x32_bf16 v[108:111], v[146:149], v[204:207], v[108:111]
	v_mfma_f32_16x16x32_bf16 v[100:103], v[154:157], v[204:207], v[100:103]
	v_mfma_f32_16x16x32_bf16 v[92:95], v[146:149], v[230:233], v[92:95]
	v_mfma_f32_16x16x32_bf16 v[84:87], v[154:157], v[230:233], v[84:87]
	v_mfma_f32_16x16x32_bf16 v[76:79], v[146:149], v[238:241], v[76:79]
	v_mfma_f32_16x16x32_bf16 v[68:71], v[154:157], v[238:241], v[68:71]
	v_mfma_f32_16x16x32_bf16 v[120:123], v[158:161], v[192:195], 0
	v_mfma_f32_16x16x32_bf16 v[112:115], v[184:187], v[192:195], 0
	v_mfma_f32_16x16x32_bf16 v[104:107], v[158:161], v[200:203], 0
	v_mfma_f32_16x16x32_bf16 v[96:99], v[184:187], v[200:203], 0
	v_mfma_f32_16x16x32_bf16 v[88:91], v[158:161], v[208:211], 0
	v_mfma_f32_16x16x32_bf16 v[80:83], v[184:187], v[208:211], 0
	v_mfma_f32_16x16x32_bf16 v[72:75], v[158:161], v[234:237], 0
	v_mfma_f32_16x16x32_bf16 v[64:67], v[184:187], v[234:237], 0
	v_mfma_f32_16x16x32_bf16 v[120:123], v[162:165], v[196:199], v[120:123]
	v_mfma_f32_16x16x32_bf16 v[112:115], v[188:191], v[196:199], v[112:115]
	v_mfma_f32_16x16x32_bf16 v[104:107], v[162:165], v[204:207], v[104:107]
	v_mfma_f32_16x16x32_bf16 v[96:99], v[188:191], v[204:207], v[96:99]
	v_mfma_f32_16x16x32_bf16 v[88:91], v[162:165], v[230:233], v[88:91]
	v_mfma_f32_16x16x32_bf16 v[80:83], v[188:191], v[230:233], v[80:83]
	v_mfma_f32_16x16x32_bf16 v[72:75], v[162:165], v[238:241], v[72:75]
	v_mfma_f32_16x16x32_bf16 v[64:67], v[188:191], v[238:241], v[64:67]
	s_barrier
	s_add_i32 s2, s2, s27
	v_lshl_add_u64 v[166:167], s[0:1], 0, v[168:169]
	s_mov_b32 m0, s2
	ds_read_b128 v[192:195], v145 offset:16384
	ds_read_b128 v[196:199], v145 offset:17408
	ds_read_b128 v[200:203], v145 offset:18432
	ds_read_b128 v[204:207], v145 offset:19456
	ds_read_b128 v[208:211], v145 offset:20480
	ds_read_b128 v[230:233], v145 offset:21504
	ds_read_b128 v[234:237], v145 offset:22528
	ds_read_b128 v[238:241], v145 offset:23552
	global_load_lds_dwordx4 v[166:167], off
	s_add_i32 m0, s2, 0x2000
	s_add_u32 s24, s0, 0x80000
	v_lshl_add_u64 v[170:171], s[0:1], 0, v[132:133]
	s_addc_u32 s25, s1, 0
	s_add_i32 s2, s55, s27
	global_load_lds_dwordx4 v[170:171], off
	v_lshl_add_u64 v[172:173], s[24:25], 0, v[168:169]
	s_mov_b32 m0, s2
	v_lshl_add_u64 v[212:213], s[34:35], 0, v[130:131]
	global_load_lds_dwordx4 v[172:173], off
	s_add_i32 m0, s2, 0x2000
	v_lshl_add_u64 v[172:173], s[24:25], 0, v[132:133]
	global_load_lds_dwordx4 v[172:173], off
	s_mov_b32 m0, s40
	v_lshl_add_u64 v[172:173], s[34:35], 0, v[128:129]
	global_load_lds_dwordx4 v[172:173], off
	s_mov_b32 m0, s41
	s_nop 0
	global_load_lds_dwordx4 v[212:213], off
	s_waitcnt vmcnt(8) lgkmcnt(0)
	s_barrier
	v_mfma_f32_16x16x32_bf16 v[60:63], v[138:141], v[192:195], 0
	v_mfma_f32_16x16x32_bf16 v[52:55], v[150:153], v[192:195], 0
	v_mfma_f32_16x16x32_bf16 v[44:47], v[138:141], v[200:203], 0
	v_mfma_f32_16x16x32_bf16 v[36:39], v[150:153], v[200:203], 0
	v_mfma_f32_16x16x32_bf16 v[28:31], v[138:141], v[208:211], 0
	v_mfma_f32_16x16x32_bf16 v[20:23], v[150:153], v[208:211], 0
	v_mfma_f32_16x16x32_bf16 v[12:15], v[138:141], v[234:237], 0
	v_mfma_f32_16x16x32_bf16 v[4:7], v[150:153], v[234:237], 0
	v_mfma_f32_16x16x32_bf16 v[60:63], v[146:149], v[196:199], v[60:63]
	v_mfma_f32_16x16x32_bf16 v[52:55], v[154:157], v[196:199], v[52:55]
	v_mfma_f32_16x16x32_bf16 v[44:47], v[146:149], v[204:207], v[44:47]
	v_mfma_f32_16x16x32_bf16 v[36:39], v[154:157], v[204:207], v[36:39]
	v_mfma_f32_16x16x32_bf16 v[28:31], v[146:149], v[230:233], v[28:31]
	v_mfma_f32_16x16x32_bf16 v[20:23], v[154:157], v[230:233], v[20:23]
	v_mfma_f32_16x16x32_bf16 v[12:15], v[146:149], v[238:241], v[12:15]
	v_mfma_f32_16x16x32_bf16 v[4:7], v[154:157], v[238:241], v[4:7]
	v_mfma_f32_16x16x32_bf16 v[56:59], v[158:161], v[192:195], 0
	v_mfma_f32_16x16x32_bf16 v[48:51], v[184:187], v[192:195], 0
	v_mfma_f32_16x16x32_bf16 v[40:43], v[158:161], v[200:203], 0
	v_mfma_f32_16x16x32_bf16 v[32:35], v[184:187], v[200:203], 0
	v_mfma_f32_16x16x32_bf16 v[24:27], v[158:161], v[208:211], 0
	v_mfma_f32_16x16x32_bf16 v[16:19], v[184:187], v[208:211], 0
	v_mfma_f32_16x16x32_bf16 v[8:11], v[158:161], v[234:237], 0
	v_mfma_f32_16x16x32_bf16 v[0:3], v[184:187], v[234:237], 0
	v_mfma_f32_16x16x32_bf16 v[56:59], v[162:165], v[196:199], v[56:59]
	v_mfma_f32_16x16x32_bf16 v[48:51], v[188:191], v[196:199], v[48:51]
	v_mfma_f32_16x16x32_bf16 v[40:43], v[162:165], v[204:207], v[40:43]
	v_mfma_f32_16x16x32_bf16 v[32:35], v[188:191], v[204:207], v[32:35]
	v_mfma_f32_16x16x32_bf16 v[24:27], v[162:165], v[230:233], v[24:27]
	v_mfma_f32_16x16x32_bf16 v[16:19], v[188:191], v[230:233], v[16:19]
	v_mfma_f32_16x16x32_bf16 v[8:11], v[162:165], v[238:241], v[8:11]
	v_mfma_f32_16x16x32_bf16 v[0:3], v[188:191], v[238:241], v[0:3]
	s_barrier
; #define PG8_STAGE(bufoff, gbase, voff) do { _Pragma("unroll") for (int _i = 0; _i < 2; ++_i) \
;         __builtin_amdgcn_global_load_lds((const unsigned*)((const char*)(gbase) + (voff)[_i]), (LAS unsigned*)(lds + (bufoff) + ldsw + _i * 8192), 16, 0, 0); } while (0)
; #define PG8_LDA(dst, b, h) do { _Pragma("unroll") for (int m = 0; m < 4; ++m) _Pragma("unroll") for (int k = 0; k < 2; ++k) dst[m][k] = *(const LAS bf16x8*)(lds + PG8_SA(b, h) + aoff + m * 2048 + k * 1024); } while (0)
; #define PG8_LDB(dst, b, h) do { _Pragma("unroll") for (int n = 0; n < 2; ++n) _Pragma("unroll") for (int k = 0; k < 2; ++k) dst[n][k] = *(const LAS bf16x8*)(lds + PG8_SB(b, h) + boff + n * 2048 + k * 1024); } while (0)
; #define PG8_MMA(ai, bj, At, Bt) do { __builtin_amdgcn_s_setprio(1); _Pragma("unroll") for (int m = 0; m < 4; ++m) _Pragma("unroll") for (int n = 0; n < 2; ++n) _Pragma("unroll") for (int k = 0; k < 2; ++k) \
;         acc[ai][bj][m][n] = __builtin_amdgcn_mfma_f32_16x16x32_bf16(Bt[n][k], At[m][k], acc[ai][bj][m][n], 0, 0, 0); __builtin_amdgcn_s_setprio(0); } while (0)
; #define PG8_WAIT_V(n) asm volatile("s_waitcnt vmcnt(" #n ")" ::: "memory")
; #define PG8_WAIT_L(n) asm volatile("s_waitcnt lgkmcnt(" #n ")" ::: "memory")
; #define PG8_BAR __builtin_amdgcn_s_barrier()
; #define PG8_SCHED __builtin_amdgcn_sched_barrier(0)
; template <class Epi>
; __device__ __forceinline__ void gemm_phase(LAS unsigned char* lds, const Gemm g, const StaticOrder& S, const Epi& E, const int tid) {
;     ...
;             PG8_LDB(B0, 1, 0); PG8_LDB(B1, 1, 1); PG8_SCHED; PG8_LDA(At, 1, 0); PG8_STAGE(PG8_SA(0, 1), a2 + hsA, voffA);
;             PG8_WAIT_V(8); PG8_WAIT_L(0); PG8_BAR; PG8_MMA(0, 0, At, B0); PG8_MMA(0, 1, At, B1); PG8_BAR; PG8_SCHED;
;             PG8_LDA(At, 1, 1); PG8_STAGE(PG8_SB(1, 0), b3, voffB); PG8_STAGE(PG8_SB(1, 1), b3 + hsB, voffB); PG8_STAGE(PG8_SA(1, 0), a3, voffA);
;             PG8_WAIT_V(8); PG8_WAIT_L(0); PG8_BAR; PG8_MMA(1, 0, At, B0); PG8_MMA(1, 1, At, B1); PG8_BAR; PG8_SCHED;
	s_add_i32 s2, 0, 0x18000
	s_add_i32 s55, 0, 0x1c000
	v_add_u32_e32 v154, s2, v143
	v_add_u32_e32 v188, s55, v143
	ds_read_b128 v[138:141], v154
	ds_read_b128 v[146:149], v154 offset:1024
	ds_read_b128 v[150:153], v154 offset:2048
	ds_read_b128 v[154:157], v154 offset:3072
	ds_read_b128 v[158:161], v188
	ds_read_b128 v[162:165], v188 offset:1024
	ds_read_b128 v[184:187], v188 offset:2048
	ds_read_b128 v[188:191], v188 offset:3072
	s_add_u32 s24, s34, 0x80000
	s_addc_u32 s25, s35, 0
	s_mov_b32 m0, s42
	v_lshl_add_u64 v[242:243], s[24:25], 0, v[128:129]
	ds_read_b128 v[192:195], v145 offset:32768
	ds_read_b128 v[196:199], v145 offset:33792
	ds_read_b128 v[200:203], v145 offset:34816
	ds_read_b128 v[204:207], v145 offset:35840
	ds_read_b128 v[208:211], v145 offset:36864
	ds_read_b128 v[230:233], v145 offset:37888
	ds_read_b128 v[234:237], v145 offset:38912
	ds_read_b128 v[238:241], v145 offset:39936
	global_load_lds_dwordx4 v[242:243], off
	s_mov_b32 m0, s43
	v_lshl_add_u64 v[242:243], s[24:25], 0, v[130:131]
	global_load_lds_dwordx4 v[242:243], off
	s_waitcnt vmcnt(8) lgkmcnt(0)
	s_barrier
	v_mfma_f32_16x16x32_bf16 v[124:127], v[138:141], v[192:195], v[124:127]
	v_mfma_f32_16x16x32_bf16 v[116:119], v[150:153], v[192:195], v[116:119]
	v_mfma_f32_16x16x32_bf16 v[108:111], v[138:141], v[200:203], v[108:111]
	v_mfma_f32_16x16x32_bf16 v[100:103], v[150:153], v[200:203], v[100:103]
	v_mfma_f32_16x16x32_bf16 v[92:95], v[138:141], v[208:211], v[92:95]
	v_mfma_f32_16x16x32_bf16 v[84:87], v[150:153], v[208:211], v[84:87]
	v_mfma_f32_16x16x32_bf16 v[76:79], v[138:141], v[234:237], v[76:79]
	v_mfma_f32_16x16x32_bf16 v[68:71], v[150:153], v[234:237], v[68:71]
	v_mfma_f32_16x16x32_bf16 v[124:127], v[146:149], v[196:199], v[124:127]
	v_mfma_f32_16x16x32_bf16 v[116:119], v[154:157], v[196:199], v[116:119]
	v_mfma_f32_16x16x32_bf16 v[108:111], v[146:149], v[204:207], v[108:111]
	v_mfma_f32_16x16x32_bf16 v[100:103], v[154:157], v[204:207], v[100:103]
	v_mfma_f32_16x16x32_bf16 v[92:95], v[146:149], v[230:233], v[92:95]
	v_mfma_f32_16x16x32_bf16 v[84:87], v[154:157], v[230:233], v[84:87]
	v_mfma_f32_16x16x32_bf16 v[76:79], v[146:149], v[238:241], v[76:79]
	v_mfma_f32_16x16x32_bf16 v[68:71], v[154:157], v[238:241], v[68:71]
	v_mfma_f32_16x16x32_bf16 v[120:123], v[158:161], v[192:195], v[120:123]
	v_mfma_f32_16x16x32_bf16 v[112:115], v[184:187], v[192:195], v[112:115]
	v_mfma_f32_16x16x32_bf16 v[104:107], v[158:161], v[200:203], v[104:107]
	v_mfma_f32_16x16x32_bf16 v[96:99], v[184:187], v[200:203], v[96:99]
	v_mfma_f32_16x16x32_bf16 v[88:91], v[158:161], v[208:211], v[88:91]
	v_mfma_f32_16x16x32_bf16 v[80:83], v[184:187], v[208:211], v[80:83]
	v_mfma_f32_16x16x32_bf16 v[72:75], v[158:161], v[234:237], v[72:75]
	v_mfma_f32_16x16x32_bf16 v[64:67], v[184:187], v[234:237], v[64:67]
	v_mfma_f32_16x16x32_bf16 v[120:123], v[162:165], v[196:199], v[120:123]
	v_mfma_f32_16x16x32_bf16 v[112:115], v[188:191], v[196:199], v[112:115]
	v_mfma_f32_16x16x32_bf16 v[104:107], v[162:165], v[204:207], v[104:107]
	v_mfma_f32_16x16x32_bf16 v[96:99], v[188:191], v[204:207], v[96:99]
	v_mfma_f32_16x16x32_bf16 v[88:91], v[162:165], v[230:233], v[88:91]
	v_mfma_f32_16x16x32_bf16 v[80:83], v[188:191], v[230:233], v[80:83]
	v_mfma_f32_16x16x32_bf16 v[72:75], v[162:165], v[238:241], v[72:75]
	v_mfma_f32_16x16x32_bf16 v[64:67], v[188:191], v[238:241], v[64:67]
	s_barrier
	s_add_i32 s2, s2, s27
	v_lshl_add_u64 v[166:167], v[166:167], 0, s[28:29]
	s_mov_b32 m0, s2
	ds_read_b128 v[192:195], v145 offset:49152
	ds_read_b128 v[196:199], v145 offset:50176
	ds_read_b128 v[200:203], v145 offset:51200
	ds_read_b128 v[204:207], v145 offset:52224
	ds_read_b128 v[208:211], v145 offset:53248
	ds_read_b128 v[230:233], v145 offset:54272
	ds_read_b128 v[234:237], v145 offset:55296
	ds_read_b128 v[238:241], v145 offset:56320
	global_load_lds_dwordx4 v[166:167], off
	s_add_i32 m0, s2, 0x2000
	s_add_u32 s0, s0, 0x80080
	v_lshl_add_u64 v[166:167], v[170:171], 0, s[28:29]
	s_addc_u32 s1, s1, 0
	s_add_i32 s2, s55, s27
	global_load_lds_dwordx4 v[166:167], off
	s_mov_b32 m0, s2
	v_lshl_add_u64 v[166:167], s[0:1], 0, v[168:169]
	global_load_lds_dwordx4 v[166:167], off
	s_add_i32 m0, s2, 0x2000
	v_lshl_add_u64 v[166:167], s[0:1], 0, v[132:133]
	global_load_lds_dwordx4 v[166:167], off
	s_mov_b32 m0, s44
	v_lshl_add_u64 v[166:167], v[172:173], 0, s[28:29]
	global_load_lds_dwordx4 v[166:167], off
	s_mov_b32 m0, s45
	v_lshl_add_u64 v[166:167], v[212:213], 0, s[28:29]
	global_load_lds_dwordx4 v[166:167], off
	s_waitcnt vmcnt(8) lgkmcnt(0)
	s_barrier
	v_mfma_f32_16x16x32_bf16 v[60:63], v[138:141], v[192:195], v[60:63]
	v_mfma_f32_16x16x32_bf16 v[52:55], v[150:153], v[192:195], v[52:55]
	v_mfma_f32_16x16x32_bf16 v[44:47], v[138:141], v[200:203], v[44:47]
	v_mfma_f32_16x16x32_bf16 v[36:39], v[150:153], v[200:203], v[36:39]
	v_mfma_f32_16x16x32_bf16 v[28:31], v[138:141], v[208:211], v[28:31]
	v_mfma_f32_16x16x32_bf16 v[20:23], v[150:153], v[208:211], v[20:23]
	v_mfma_f32_16x16x32_bf16 v[12:15], v[138:141], v[234:237], v[12:15]
	v_mfma_f32_16x16x32_bf16 v[4:7], v[150:153], v[234:237], v[4:7]
	v_mfma_f32_16x16x32_bf16 v[60:63], v[146:149], v[196:199], v[60:63]
	v_mfma_f32_16x16x32_bf16 v[52:55], v[154:157], v[196:199], v[52:55]
	v_mfma_f32_16x16x32_bf16 v[44:47], v[146:149], v[204:207], v[44:47]
	v_mfma_f32_16x16x32_bf16 v[36:39], v[154:157], v[204:207], v[36:39]
	v_mfma_f32_16x16x32_bf16 v[28:31], v[146:149], v[230:233], v[28:31]
	v_mfma_f32_16x16x32_bf16 v[20:23], v[154:157], v[230:233], v[20:23]
	v_mfma_f32_16x16x32_bf16 v[12:15], v[146:149], v[238:241], v[12:15]
	v_mfma_f32_16x16x32_bf16 v[4:7], v[154:157], v[238:241], v[4:7]
	v_mfma_f32_16x16x32_bf16 v[56:59], v[158:161], v[192:195], v[56:59]
	v_mfma_f32_16x16x32_bf16 v[48:51], v[184:187], v[192:195], v[48:51]
	v_mfma_f32_16x16x32_bf16 v[40:43], v[158:161], v[200:203], v[40:43]
	v_mfma_f32_16x16x32_bf16 v[32:35], v[184:187], v[200:203], v[32:35]
	v_mfma_f32_16x16x32_bf16 v[24:27], v[158:161], v[208:211], v[24:27]
	v_mfma_f32_16x16x32_bf16 v[16:19], v[184:187], v[208:211], v[16:19]
	v_mfma_f32_16x16x32_bf16 v[8:11], v[158:161], v[234:237], v[8:11]
	v_mfma_f32_16x16x32_bf16 v[0:3], v[184:187], v[234:237], v[0:3]
	v_mfma_f32_16x16x32_bf16 v[56:59], v[162:165], v[196:199], v[56:59]
	v_mfma_f32_16x16x32_bf16 v[48:51], v[188:191], v[196:199], v[48:51]
	v_mfma_f32_16x16x32_bf16 v[40:43], v[162:165], v[204:207], v[40:43]
	v_mfma_f32_16x16x32_bf16 v[32:35], v[188:191], v[204:207], v[32:35]
	v_mfma_f32_16x16x32_bf16 v[24:27], v[162:165], v[230:233], v[24:27]
	v_mfma_f32_16x16x32_bf16 v[16:19], v[188:191], v[230:233], v[16:19]
	v_mfma_f32_16x16x32_bf16 v[8:11], v[162:165], v[238:241], v[8:11]
	v_mfma_f32_16x16x32_bf16 v[0:3], v[188:191], v[238:241], v[0:3]
	s_barrier
	s_add_i32 s57, s57, 2
	s_add_u32 s18, s18, 0x100
	s_addc_u32 s19, s19, 0
	s_add_u32 s53, s53, 0x100
	s_addc_u32 s56, s56, 0
	s_cmp_gt_u32 s57, 29
; #define PG8_STAGE(bufoff, gbase, voff) do { _Pragma("unroll") for (int _i = 0; _i < 2; ++_i) \
;         __builtin_amdgcn_global_load_lds((const unsigned*)((const char*)(gbase) + (voff)[_i]), (LAS unsigned*)(lds + (bufoff) + ldsw + _i * 8192), 16, 0, 0); } while (0)
; #define PG8_LDA(dst, b, h) do { _Pragma("unroll") for (int m = 0; m < 4; ++m) _Pragma("unroll") for (int k = 0; k < 2; ++k) dst[m][k] = *(const LAS bf16x8*)(lds + PG8_SA(b, h) + aoff + m * 2048 + k * 1024); } while (0)
; #define PG8_LDB(dst, b, h) do { _Pragma("unroll") for (int n = 0; n < 2; ++n) _Pragma("unroll") for (int k = 0; k < 2; ++k) dst[n][k] = *(const LAS bf16x8*)(lds + PG8_SB(b, h) + boff + n * 2048 + k * 1024); } while (0)
; #define PG8_MMA(ai, bj, At, Bt) do { __builtin_amdgcn_s_setprio(1); _Pragma("unroll") for (int m = 0; m < 4; ++m) _Pragma("unroll") for (int n = 0; n < 2; ++n) _Pragma("unroll") for (int k = 0; k < 2; ++k) \
;         acc[ai][bj][m][n] = __builtin_amdgcn_mfma_f32_16x16x32_bf16(Bt[n][k], At[m][k], acc[ai][bj][m][n], 0, 0, 0); __builtin_amdgcn_s_setprio(0); } while (0)
; #define PG8_WAIT_V(n) asm volatile("s_waitcnt vmcnt(" #n ")" ::: "memory")
; #define PG8_WAIT_L(n) asm volatile("s_waitcnt lgkmcnt(" #n ")" ::: "memory")
; #define PG8_BAR __builtin_amdgcn_s_barrier()
; #define PG8_SCHED __builtin_amdgcn_sched_barrier(0)
; template <class Epi>
; __device__ __forceinline__ void gemm_phase(LAS unsigned char* lds, const Gemm g, const StaticOrder& S, const Epi& E, const int tid) {
;     ...
;             const bool last = (t == nt - 2);
;             const char* a1 = cA + (size_t)(t + 1) * kstep;
;             const char* a2 = last ? nA : cA + (size_t)(t + 2) * kstep; const char* b2 = last ? nB : cB + (size_t)(t + 2) * kstep;
;             const char* a3 = a2 + kstep; const char* b3 = b2 + kstep;
;             PG8_LDB(B0, 0, 0); PG8_LDB(B1, 0, 1); PG8_SCHED; PG8_LDA(At, 0, 0); PG8_STAGE(PG8_SA(1, 1), a1 + hsA, voffA);
;             PG8_WAIT_V(8); PG8_WAIT_L(0); PG8_BAR; PG8_MMA(0, 0, At, B0); PG8_MMA(0, 1, At, B1); PG8_BAR; PG8_SCHED;
;             PG8_LDA(At, 0, 1); PG8_STAGE(PG8_SB(0, 0), b2, voffB); PG8_STAGE(PG8_SB(0, 1), b2 + hsB, voffB); PG8_STAGE(PG8_SA(0, 0), a2, voffA);
.LBB0_1004:
	s_add_u32 s0, s18, 0xfff80080
	s_addc_u32 s1, s19, -1
	s_add_i32 s2, 0, 0x10000
	s_cmp_eq_u32 s57, 28
	s_cselect_b32 s35, s13, s1
	s_cselect_b32 s34, s49, s0
	s_cselect_b32 s1, s11, s56
	s_cselect_b32 s0, s52, s53
	s_add_i32 s55, 0, 0x14000
	v_add_u32_e32 v154, s2, v143
	v_add_u32_e32 v166, s55, v143
	ds_read_b128 v[138:141], v154
	ds_read_b128 v[146:149], v154 offset:1024
	ds_read_b128 v[150:153], v154 offset:2048
	ds_read_b128 v[154:157], v154 offset:3072
	ds_read_b128 v[158:161], v166
	ds_read_b128 v[162:165], v166 offset:1024
	ds_read_b128 v[184:187], v166 offset:2048
	ds_read_b128 v[188:191], v166 offset:3072
	v_lshl_add_u64 v[166:167], s[18:19], 0, v[134:135]
	s_add_i32 m0, s40, 0xc000
	ds_read_b128 v[192:195], v145
	ds_read_b128 v[196:199], v145 offset:1024
	ds_read_b128 v[200:203], v145 offset:2048
	ds_read_b128 v[204:207], v145 offset:3072
	ds_read_b128 v[208:211], v145 offset:4096
	ds_read_b128 v[230:233], v145 offset:5120
	ds_read_b128 v[234:237], v145 offset:6144
	ds_read_b128 v[238:241], v145 offset:7168
	global_load_lds_dwordx4 v[166:167], off
	s_add_i32 m0, s40, 0xe000
	v_lshl_add_u64 v[166:167], s[18:19], 0, v[136:137]
	global_load_lds_dwordx4 v[166:167], off
	s_waitcnt vmcnt(8) lgkmcnt(0)
	s_barrier
	v_mfma_f32_16x16x32_bf16 v[124:127], v[138:141], v[192:195], v[124:127]
	v_mfma_f32_16x16x32_bf16 v[116:119], v[150:153], v[192:195], v[116:119]
	v_mfma_f32_16x16x32_bf16 v[108:111], v[138:141], v[200:203], v[108:111]
	v_mfma_f32_16x16x32_bf16 v[100:103], v[150:153], v[200:203], v[100:103]
	v_mfma_f32_16x16x32_bf16 v[92:95], v[138:141], v[208:211], v[92:95]
	v_mfma_f32_16x16x32_bf16 v[84:87], v[150:153], v[208:211], v[84:87]
	v_mfma_f32_16x16x32_bf16 v[76:79], v[138:141], v[234:237], v[76:79]
	v_mfma_f32_16x16x32_bf16 v[68:71], v[150:153], v[234:237], v[68:71]
	v_mfma_f32_16x16x32_bf16 v[124:127], v[146:149], v[196:199], v[124:127]
	v_mfma_f32_16x16x32_bf16 v[116:119], v[154:157], v[196:199], v[116:119]
	v_mfma_f32_16x16x32_bf16 v[108:111], v[146:149], v[204:207], v[108:111]
	v_mfma_f32_16x16x32_bf16 v[100:103], v[154:157], v[204:207], v[100:103]
	v_mfma_f32_16x16x32_bf16 v[92:95], v[146:149], v[230:233], v[92:95]
	v_mfma_f32_16x16x32_bf16 v[84:87], v[154:157], v[230:233], v[84:87]
	v_mfma_f32_16x16x32_bf16 v[76:79], v[146:149], v[238:241], v[76:79]
	v_mfma_f32_16x16x32_bf16 v[68:71], v[154:157], v[238:241], v[68:71]
	v_mfma_f32_16x16x32_bf16 v[120:123], v[158:161], v[192:195], v[120:123]
	v_mfma_f32_16x16x32_bf16 v[112:115], v[184:187], v[192:195], v[112:115]
	v_mfma_f32_16x16x32_bf16 v[104:107], v[158:161], v[200:203], v[104:107]
	v_mfma_f32_16x16x32_bf16 v[96:99], v[184:187], v[200:203], v[96:99]
	v_mfma_f32_16x16x32_bf16 v[88:91], v[158:161], v[208:211], v[88:91]
	v_mfma_f32_16x16x32_bf16 v[80:83], v[184:187], v[208:211], v[80:83]
	v_mfma_f32_16x16x32_bf16 v[72:75], v[158:161], v[234:237], v[72:75]
	v_mfma_f32_16x16x32_bf16 v[64:67], v[184:187], v[234:237], v[64:67]
	v_mfma_f32_16x16x32_bf16 v[120:123], v[162:165], v[196:199], v[120:123]
	v_mfma_f32_16x16x32_bf16 v[112:115], v[188:191], v[196:199], v[112:115]
	v_mfma_f32_16x16x32_bf16 v[104:107], v[162:165], v[204:207], v[104:107]
	v_mfma_f32_16x16x32_bf16 v[96:99], v[188:191], v[204:207], v[96:99]
	v_mfma_f32_16x16x32_bf16 v[88:91], v[162:165], v[230:233], v[88:91]
	v_mfma_f32_16x16x32_bf16 v[80:83], v[188:191], v[230:233], v[80:83]
	v_mfma_f32_16x16x32_bf16 v[72:75], v[162:165], v[238:241], v[72:75]
	v_mfma_f32_16x16x32_bf16 v[64:67], v[188:191], v[238:241], v[64:67]
	s_barrier
	s_add_i32 s2, s2, s27
	v_lshl_add_u64 v[166:167], s[0:1], 0, v[168:169]
	s_mov_b32 m0, s2
	ds_read_b128 v[192:195], v145 offset:16384
	ds_read_b128 v[196:199], v145 offset:17408
	ds_read_b128 v[200:203], v145 offset:18432
	ds_read_b128 v[204:207], v145 offset:19456
	ds_read_b128 v[208:211], v145 offset:20480
	ds_read_b128 v[230:233], v145 offset:21504
	ds_read_b128 v[234:237], v145 offset:22528
	ds_read_b128 v[238:241], v145 offset:23552
	global_load_lds_dwordx4 v[166:167], off
	s_add_i32 m0, s2, 0x2000
	s_add_u32 s24, s0, 0x80000
	v_lshl_add_u64 v[170:171], s[0:1], 0, v[132:133]
	s_addc_u32 s25, s1, 0
	s_add_i32 s2, s55, s27
	global_load_lds_dwordx4 v[170:171], off
	v_lshl_add_u64 v[172:173], s[24:25], 0, v[168:169]
	s_mov_b32 m0, s2
	v_lshl_add_u64 v[212:213], s[34:35], 0, v[130:131]
	global_load_lds_dwordx4 v[172:173], off
	s_add_i32 m0, s2, 0x2000
	v_lshl_add_u64 v[172:173], s[24:25], 0, v[132:133]
	global_load_lds_dwordx4 v[172:173], off
	s_mov_b32 m0, s40
	v_lshl_add_u64 v[172:173], s[34:35], 0, v[128:129]
	global_load_lds_dwordx4 v[172:173], off
	s_mov_b32 m0, s41
	s_nop 0
	global_load_lds_dwordx4 v[212:213], off
	s_waitcnt vmcnt(8) lgkmcnt(0)
	s_barrier
; #define PG8_STAGE(bufoff, gbase, voff) do { _Pragma("unroll") for (int _i = 0; _i < 2; ++_i) \
;         __builtin_amdgcn_global_load_lds((const unsigned*)((const char*)(gbase) + (voff)[_i]), (LAS unsigned*)(lds + (bufoff) + ldsw + _i * 8192), 16, 0, 0); } while (0)
; #define PG8_LDA(dst, b, h) do { _Pragma("unroll") for (int m = 0; m < 4; ++m) _Pragma("unroll") for (int k = 0; k < 2; ++k) dst[m][k] = *(const LAS bf16x8*)(lds + PG8_SA(b, h) + aoff + m * 2048 + k * 1024); } while (0)
; #define PG8_LDB(dst, b, h) do { _Pragma("unroll") for (int n = 0; n < 2; ++n) _Pragma("unroll") for (int k = 0; k < 2; ++k) dst[n][k] = *(const LAS bf16x8*)(lds + PG8_SB(b, h) + boff + n * 2048 + k * 1024); } while (0)
; #define PG8_MMA(ai, bj, At, Bt) do { __builtin_amdgcn_s_setprio(1); _Pragma("unroll") for (int m = 0; m < 4; ++m) _Pragma("unroll") for (int n = 0; n < 2; ++n) _Pragma("unroll") for (int k = 0; k < 2; ++k) \
;         acc[ai][bj][m][n] = __builtin_amdgcn_mfma_f32_16x16x32_bf16(Bt[n][k], At[m][k], acc[ai][bj][m][n], 0, 0, 0); __builtin_amdgcn_s_setprio(0); } while (0)
; #define PG8_WAIT_V(n) asm volatile("s_waitcnt vmcnt(" #n ")" ::: "memory")
; #define PG8_WAIT_L(n) asm volatile("s_waitcnt lgkmcnt(" #n ")" ::: "memory")
; #define PG8_BAR __builtin_amdgcn_s_barrier()
; #define PG8_SCHED __builtin_amdgcn_sched_barrier(0)
; template <class Epi>
; __device__ __forceinline__ void gemm_phase(LAS unsigned char* lds, const Gemm g, const StaticOrder& S, const Epi& E, const int tid) {
;     ...
;             PG8_WAIT_V(8); PG8_WAIT_L(0); PG8_BAR; PG8_MMA(1, 0, At, B0); PG8_MMA(1, 1, At, B1); PG8_BAR; PG8_SCHED;
;             PG8_LDB(B0, 1, 0); PG8_LDB(B1, 1, 1); PG8_SCHED; PG8_LDA(At, 1, 0); PG8_STAGE(PG8_SA(0, 1), a2 + hsA, voffA);
;             PG8_WAIT_V(8); PG8_WAIT_L(0); PG8_BAR; PG8_MMA(0, 0, At, B0); PG8_MMA(0, 1, At, B1); PG8_BAR; PG8_SCHED;
	v_mfma_f32_16x16x32_bf16 v[60:63], v[138:141], v[192:195], v[60:63]
	v_mfma_f32_16x16x32_bf16 v[52:55], v[150:153], v[192:195], v[52:55]
	v_mfma_f32_16x16x32_bf16 v[44:47], v[138:141], v[200:203], v[44:47]
	v_mfma_f32_16x16x32_bf16 v[36:39], v[150:153], v[200:203], v[36:39]
	v_mfma_f32_16x16x32_bf16 v[28:31], v[138:141], v[208:211], v[28:31]
	v_mfma_f32_16x16x32_bf16 v[20:23], v[150:153], v[208:211], v[20:23]
	v_mfma_f32_16x16x32_bf16 v[12:15], v[138:141], v[234:237], v[12:15]
	v_mfma_f32_16x16x32_bf16 v[4:7], v[150:153], v[234:237], v[4:7]
	v_mfma_f32_16x16x32_bf16 v[60:63], v[146:149], v[196:199], v[60:63]
	v_mfma_f32_16x16x32_bf16 v[52:55], v[154:157], v[196:199], v[52:55]
	v_mfma_f32_16x16x32_bf16 v[44:47], v[146:149], v[204:207], v[44:47]
	v_mfma_f32_16x16x32_bf16 v[36:39], v[154:157], v[204:207], v[36:39]
	v_mfma_f32_16x16x32_bf16 v[28:31], v[146:149], v[230:233], v[28:31]
	v_mfma_f32_16x16x32_bf16 v[20:23], v[154:157], v[230:233], v[20:23]
	v_mfma_f32_16x16x32_bf16 v[12:15], v[146:149], v[238:241], v[12:15]
	v_mfma_f32_16x16x32_bf16 v[4:7], v[154:157], v[238:241], v[4:7]
	v_mfma_f32_16x16x32_bf16 v[56:59], v[158:161], v[192:195], v[56:59]
	v_mfma_f32_16x16x32_bf16 v[48:51], v[184:187], v[192:195], v[48:51]
	v_mfma_f32_16x16x32_bf16 v[40:43], v[158:161], v[200:203], v[40:43]
	v_mfma_f32_16x16x32_bf16 v[32:35], v[184:187], v[200:203], v[32:35]
	v_mfma_f32_16x16x32_bf16 v[24:27], v[158:161], v[208:211], v[24:27]
	v_mfma_f32_16x16x32_bf16 v[16:19], v[184:187], v[208:211], v[16:19]
	v_mfma_f32_16x16x32_bf16 v[8:11], v[158:161], v[234:237], v[8:11]
	v_mfma_f32_16x16x32_bf16 v[0:3], v[184:187], v[234:237], v[0:3]
	v_mfma_f32_16x16x32_bf16 v[56:59], v[162:165], v[196:199], v[56:59]
	v_mfma_f32_16x16x32_bf16 v[48:51], v[188:191], v[196:199], v[48:51]
	v_mfma_f32_16x16x32_bf16 v[40:43], v[162:165], v[204:207], v[40:43]
	v_mfma_f32_16x16x32_bf16 v[32:35], v[188:191], v[204:207], v[32:35]
	v_mfma_f32_16x16x32_bf16 v[24:27], v[162:165], v[230:233], v[24:27]
	v_mfma_f32_16x16x32_bf16 v[16:19], v[188:191], v[230:233], v[16:19]
	v_mfma_f32_16x16x32_bf16 v[8:11], v[162:165], v[238:241], v[8:11]
	v_mfma_f32_16x16x32_bf16 v[0:3], v[188:191], v[238:241], v[0:3]
	s_barrier
	s_add_i32 s2, 0, 0x18000
	s_add_i32 s55, 0, 0x1c000
	v_add_u32_e32 v154, s2, v143
	v_add_u32_e32 v188, s55, v143
	ds_read_b128 v[138:141], v154
	ds_read_b128 v[146:149], v154 offset:1024
	ds_read_b128 v[150:153], v154 offset:2048
	ds_read_b128 v[154:157], v154 offset:3072
	ds_read_b128 v[158:161], v188
	ds_read_b128 v[162:165], v188 offset:1024
	ds_read_b128 v[184:187], v188 offset:2048
	ds_read_b128 v[188:191], v188 offset:3072
	s_add_u32 s24, s34, 0x80000
	s_addc_u32 s25, s35, 0
	s_mov_b32 m0, s42
	v_lshl_add_u64 v[242:243], s[24:25], 0, v[128:129]
	ds_read_b128 v[192:195], v145 offset:32768
	ds_read_b128 v[196:199], v145 offset:33792
	ds_read_b128 v[200:203], v145 offset:34816
	ds_read_b128 v[204:207], v145 offset:35840
	ds_read_b128 v[208:211], v145 offset:36864
	ds_read_b128 v[230:233], v145 offset:37888
	ds_read_b128 v[234:237], v145 offset:38912
	ds_read_b128 v[238:241], v145 offset:39936
	global_load_lds_dwordx4 v[242:243], off
	s_mov_b32 m0, s43
	v_lshl_add_u64 v[242:243], s[24:25], 0, v[130:131]
	global_load_lds_dwordx4 v[242:243], off
	s_waitcnt vmcnt(8) lgkmcnt(0)
	s_barrier
	v_mfma_f32_16x16x32_bf16 v[124:127], v[138:141], v[192:195], v[124:127]
	v_mfma_f32_16x16x32_bf16 v[116:119], v[150:153], v[192:195], v[116:119]
	v_mfma_f32_16x16x32_bf16 v[108:111], v[138:141], v[200:203], v[108:111]
	v_mfma_f32_16x16x32_bf16 v[100:103], v[150:153], v[200:203], v[100:103]
	v_mfma_f32_16x16x32_bf16 v[92:95], v[138:141], v[208:211], v[92:95]
	v_mfma_f32_16x16x32_bf16 v[84:87], v[150:153], v[208:211], v[84:87]
	v_mfma_f32_16x16x32_bf16 v[76:79], v[138:141], v[234:237], v[76:79]
	v_mfma_f32_16x16x32_bf16 v[68:71], v[150:153], v[234:237], v[68:71]
	v_mfma_f32_16x16x32_bf16 v[124:127], v[146:149], v[196:199], v[124:127]
	v_mfma_f32_16x16x32_bf16 v[116:119], v[154:157], v[196:199], v[116:119]
	v_mfma_f32_16x16x32_bf16 v[108:111], v[146:149], v[204:207], v[108:111]
	v_mfma_f32_16x16x32_bf16 v[100:103], v[154:157], v[204:207], v[100:103]
	v_mfma_f32_16x16x32_bf16 v[92:95], v[146:149], v[230:233], v[92:95]
	v_mfma_f32_16x16x32_bf16 v[84:87], v[154:157], v[230:233], v[84:87]
	v_mfma_f32_16x16x32_bf16 v[76:79], v[146:149], v[238:241], v[76:79]
	v_mfma_f32_16x16x32_bf16 v[68:71], v[154:157], v[238:241], v[68:71]
	v_mfma_f32_16x16x32_bf16 v[120:123], v[158:161], v[192:195], v[120:123]
	v_mfma_f32_16x16x32_bf16 v[112:115], v[184:187], v[192:195], v[112:115]
	v_mfma_f32_16x16x32_bf16 v[104:107], v[158:161], v[200:203], v[104:107]
	v_mfma_f32_16x16x32_bf16 v[96:99], v[184:187], v[200:203], v[96:99]
	v_mfma_f32_16x16x32_bf16 v[88:91], v[158:161], v[208:211], v[88:91]
	v_mfma_f32_16x16x32_bf16 v[80:83], v[184:187], v[208:211], v[80:83]
	v_mfma_f32_16x16x32_bf16 v[72:75], v[158:161], v[234:237], v[72:75]
	v_mfma_f32_16x16x32_bf16 v[64:67], v[184:187], v[234:237], v[64:67]
	v_mfma_f32_16x16x32_bf16 v[120:123], v[162:165], v[196:199], v[120:123]
	v_mfma_f32_16x16x32_bf16 v[112:115], v[188:191], v[196:199], v[112:115]
	v_mfma_f32_16x16x32_bf16 v[104:107], v[162:165], v[204:207], v[104:107]
	v_mfma_f32_16x16x32_bf16 v[96:99], v[188:191], v[204:207], v[96:99]
	v_mfma_f32_16x16x32_bf16 v[88:91], v[162:165], v[230:233], v[88:91]
	v_mfma_f32_16x16x32_bf16 v[80:83], v[188:191], v[230:233], v[80:83]
	v_mfma_f32_16x16x32_bf16 v[72:75], v[162:165], v[238:241], v[72:75]
	v_mfma_f32_16x16x32_bf16 v[64:67], v[188:191], v[238:241], v[64:67]
	s_barrier
; #define PG8_STAGE(bufoff, gbase, voff) do { _Pragma("unroll") for (int _i = 0; _i < 2; ++_i) \
;         __builtin_amdgcn_global_load_lds((const unsigned*)((const char*)(gbase) + (voff)[_i]), (LAS unsigned*)(lds + (bufoff) + ldsw + _i * 8192), 16, 0, 0); } while (0)
; #define PG8_LDA(dst, b, h) do { _Pragma("unroll") for (int m = 0; m < 4; ++m) _Pragma("unroll") for (int k = 0; k < 2; ++k) dst[m][k] = *(const LAS bf16x8*)(lds + PG8_SA(b, h) + aoff + m * 2048 + k * 1024); } while (0)
; #define PG8_MMA(ai, bj, At, Bt) do { __builtin_amdgcn_s_setprio(1); _Pragma("unroll") for (int m = 0; m < 4; ++m) _Pragma("unroll") for (int n = 0; n < 2; ++n) _Pragma("unroll") for (int k = 0; k < 2; ++k) \
;         acc[ai][bj][m][n] = __builtin_amdgcn_mfma_f32_16x16x32_bf16(Bt[n][k], At[m][k], acc[ai][bj][m][n], 0, 0, 0); __builtin_amdgcn_s_setprio(0); } while (0)
; #define PG8_WAIT_V(n) asm volatile("s_waitcnt vmcnt(" #n ")" ::: "memory")
; #define PG8_WAIT_L(n) asm volatile("s_waitcnt lgkmcnt(" #n ")" ::: "memory")
; #define PG8_BAR __builtin_amdgcn_s_barrier()
; #define PG8_SCHED __builtin_amdgcn_sched_barrier(0)
; template <class Epi>
; __device__ __forceinline__ void gemm_phase(LAS unsigned char* lds, const Gemm g, const StaticOrder& S, const Epi& E, const int tid) {
;     ...
;             PG8_LDA(At, 1, 1); PG8_STAGE(PG8_SB(1, 0), b3, voffB); PG8_STAGE(PG8_SB(1, 1), b3 + hsB, voffB); PG8_STAGE(PG8_SA(1, 0), a3, voffA);
;             PG8_WAIT_V(8); PG8_WAIT_L(0); PG8_BAR; PG8_MMA(1, 0, At, B0); PG8_MMA(1, 1, At, B1); PG8_BAR; PG8_SCHED;
;         }
;         if (wr == 0) PG8_BAR;
	s_add_i32 s2, s2, s27
	v_lshl_add_u64 v[166:167], v[166:167], 0, s[28:29]
	s_mov_b32 m0, s2
	ds_read_b128 v[192:195], v145 offset:49152
	ds_read_b128 v[196:199], v145 offset:50176
	ds_read_b128 v[200:203], v145 offset:51200
	ds_read_b128 v[204:207], v145 offset:52224
	ds_read_b128 v[208:211], v145 offset:53248
	ds_read_b128 v[230:233], v145 offset:54272
	ds_read_b128 v[234:237], v145 offset:55296
	ds_read_b128 v[238:241], v145 offset:56320
	global_load_lds_dwordx4 v[166:167], off
	s_add_i32 m0, s2, 0x2000
	s_add_u32 s0, s0, 0x80080
	v_lshl_add_u64 v[166:167], v[170:171], 0, s[28:29]
	s_addc_u32 s1, s1, 0
	s_add_i32 s2, s55, s27
	global_load_lds_dwordx4 v[166:167], off
	s_mov_b32 m0, s2
	v_lshl_add_u64 v[166:167], s[0:1], 0, v[168:169]
	global_load_lds_dwordx4 v[166:167], off
	s_add_i32 m0, s2, 0x2000
	v_lshl_add_u64 v[166:167], s[0:1], 0, v[132:133]
	global_load_lds_dwordx4 v[166:167], off
	s_mov_b32 m0, s44
	v_lshl_add_u64 v[166:167], v[172:173], 0, s[28:29]
	global_load_lds_dwordx4 v[166:167], off
	s_mov_b32 m0, s45
	v_lshl_add_u64 v[166:167], v[212:213], 0, s[28:29]
	global_load_lds_dwordx4 v[166:167], off
	s_waitcnt vmcnt(8) lgkmcnt(0)
	s_barrier
	v_mfma_f32_16x16x32_bf16 v[60:63], v[138:141], v[192:195], v[60:63]
	v_mfma_f32_16x16x32_bf16 v[52:55], v[150:153], v[192:195], v[52:55]
	v_mfma_f32_16x16x32_bf16 v[44:47], v[138:141], v[200:203], v[44:47]
	v_mfma_f32_16x16x32_bf16 v[36:39], v[150:153], v[200:203], v[36:39]
	v_mfma_f32_16x16x32_bf16 v[28:31], v[138:141], v[208:211], v[28:31]
	v_mfma_f32_16x16x32_bf16 v[20:23], v[150:153], v[208:211], v[20:23]
	v_mfma_f32_16x16x32_bf16 v[12:15], v[138:141], v[234:237], v[12:15]
	v_mfma_f32_16x16x32_bf16 v[4:7], v[150:153], v[234:237], v[4:7]
	v_mfma_f32_16x16x32_bf16 v[60:63], v[146:149], v[196:199], v[60:63]
	v_mfma_f32_16x16x32_bf16 v[52:55], v[154:157], v[196:199], v[52:55]
	v_mfma_f32_16x16x32_bf16 v[44:47], v[146:149], v[204:207], v[44:47]
	v_mfma_f32_16x16x32_bf16 v[36:39], v[154:157], v[204:207], v[36:39]
	v_mfma_f32_16x16x32_bf16 v[28:31], v[146:149], v[230:233], v[28:31]
	v_mfma_f32_16x16x32_bf16 v[20:23], v[154:157], v[230:233], v[20:23]
	v_mfma_f32_16x16x32_bf16 v[12:15], v[146:149], v[238:241], v[12:15]
	v_mfma_f32_16x16x32_bf16 v[4:7], v[154:157], v[238:241], v[4:7]
	v_mfma_f32_16x16x32_bf16 v[56:59], v[158:161], v[192:195], v[56:59]
	v_mfma_f32_16x16x32_bf16 v[48:51], v[184:187], v[192:195], v[48:51]
	v_mfma_f32_16x16x32_bf16 v[40:43], v[158:161], v[200:203], v[40:43]
	v_mfma_f32_16x16x32_bf16 v[32:35], v[184:187], v[200:203], v[32:35]
	v_mfma_f32_16x16x32_bf16 v[24:27], v[158:161], v[208:211], v[24:27]
	v_mfma_f32_16x16x32_bf16 v[16:19], v[184:187], v[208:211], v[16:19]
	v_mfma_f32_16x16x32_bf16 v[8:11], v[158:161], v[234:237], v[8:11]
	v_mfma_f32_16x16x32_bf16 v[0:3], v[184:187], v[234:237], v[0:3]
	v_mfma_f32_16x16x32_bf16 v[56:59], v[162:165], v[196:199], v[56:59]
	v_mfma_f32_16x16x32_bf16 v[48:51], v[188:191], v[196:199], v[48:51]
	v_mfma_f32_16x16x32_bf16 v[40:43], v[162:165], v[204:207], v[40:43]
	v_mfma_f32_16x16x32_bf16 v[32:35], v[188:191], v[204:207], v[32:35]
	v_mfma_f32_16x16x32_bf16 v[24:27], v[162:165], v[230:233], v[24:27]
	v_mfma_f32_16x16x32_bf16 v[16:19], v[188:191], v[230:233], v[16:19]
	v_mfma_f32_16x16x32_bf16 v[8:11], v[162:165], v[238:241], v[8:11]
	v_mfma_f32_16x16x32_bf16 v[0:3], v[188:191], v[238:241], v[0:3]
	s_barrier
	s_add_i32 s57, s57, 2
	s_add_u32 s18, s18, 0x100
	s_addc_u32 s19, s19, 0
	s_add_u32 s53, s53, 0x100
	s_addc_u32 s56, s56, 0
	s_cmp_gt_u32 s57, 29
	s_cbranch_scc0 .LBB0_1004
	s_and_b64 vcc, exec, s[8:9]
	s_cbranch_vccz .LBB0_1007
	s_barrier

; #define PG8_STAGE(bufoff, gbase, voff) do { _Pragma("unroll") for (int _i = 0; _i < 2; ++_i) \
;         __builtin_amdgcn_global_load_lds((const unsigned*)((const char*)(gbase) + (voff)[_i]), (LAS unsigned*)(lds + (bufoff) + ldsw + _i * 8192), 16, 0, 0); } while (0)
; #define PG8_LDA(dst, b, h) do { _Pragma("unroll") for (int m = 0; m < 4; ++m) _Pragma("unroll") for (int k = 0; k < 2; ++k) dst[m][k] = *(const LAS bf16x8*)(lds + PG8_SA(b, h) + aoff + m * 2048 + k * 1024); } while (0)
; #define PG8_LDB(dst, b, h) do { _Pragma("unroll") for (int n = 0; n < 2; ++n) _Pragma("unroll") for (int k = 0; k < 2; ++k) dst[n][k] = *(const LAS bf16x8*)(lds + PG8_SB(b, h) + boff + n * 2048 + k * 1024); } while (0)
; #define PG8_MMA(ai, bj, At, Bt) do { __builtin_amdgcn_s_setprio(1); _Pragma("unroll") for (int m = 0; m < 4; ++m) _Pragma("unroll") for (int n = 0; n < 2; ++n) _Pragma("unroll") for (int k = 0; k < 2; ++k) \
;         acc[ai][bj][m][n] = __builtin_amdgcn_mfma_f32_16x16x32_bf16(Bt[n][k], At[m][k], acc[ai][bj][m][n], 0, 0, 0); __builtin_amdgcn_s_setprio(0); } while (0)
; #define PG8_WAIT_V(n) asm volatile("s_waitcnt vmcnt(" #n ")" ::: "memory")
; #define PG8_WAIT_L(n) asm volatile("s_waitcnt lgkmcnt(" #n ")" ::: "memory")
; #define PG8_BAR __builtin_amdgcn_s_barrier()
; #define PG8_SCHED __builtin_amdgcn_sched_barrier(0)
; template <class Epi>
; __device__ __forceinline__ void gemm_phase(LAS unsigned char* lds, const Gemm g, const StaticOrder& S, const Epi& E, const int tid) {
;     ...
;             const bool last = (t == nt - 2);
;             const char* a1 = cA + (size_t)(t + 1) * kstep;
;             const char* a2 = last ? nA : cA + (size_t)(t + 2) * kstep; const char* b2 = last ? nB : cB + (size_t)(t + 2) * kstep;
;             const char* a3 = a2 + kstep; const char* b3 = b2 + kstep;
;             PG8_LDB(B0, 0, 0); PG8_LDB(B1, 0, 1); PG8_SCHED; PG8_LDA(At, 0, 0); PG8_STAGE(PG8_SA(1, 1), a1 + hsA, voffA);
;             PG8_WAIT_V(8); PG8_WAIT_L(0); PG8_BAR; PG8_MMA(0, 0, At, B0); PG8_MMA(0, 1, At, B1); PG8_BAR; PG8_SCHED;
;             PG8_LDA(At, 0, 1); PG8_STAGE(PG8_SB(0, 0), b2, voffB); PG8_STAGE(PG8_SB(0, 1), b2 + hsB, voffB); PG8_STAGE(PG8_SA(0, 0), a2, voffA);
;             PG8_WAIT_V(8); PG8_WAIT_L(0); PG8_BAR; PG8_MMA(1, 0, At, B0); PG8_MMA(1, 1, At, B1); PG8_BAR; PG8_SCHED;
.Lgprio_g:
	s_add_u32 s0, s12, 0x100
	s_addc_u32 s1, s13, 0
	s_add_i32 s2, 0, 0x10000
	s_cmpk_eq_i32 s53, 0x54
	s_cselect_b32 s17, s9, s1
	s_cselect_b32 s16, s8, s0
	s_cselect_b32 s15, s11, s39
	s_cselect_b32 s14, s10, s38
	s_add_i32 s24, 0, 0x14000
	v_add_u32_e32 v152, s2, v184
	v_add_u32_e32 v170, s24, v184
	ds_read_b128 v[128:131], v152
	ds_read_b128 v[144:147], v152 offset:1024
	ds_read_b128 v[148:151], v152 offset:2048
	ds_read_b128 v[152:155], v152 offset:3072
	ds_read_b128 v[156:159], v170
	ds_read_b128 v[160:163], v170 offset:1024
	ds_read_b128 v[164:167], v170 offset:2048
	ds_read_b128 v[190:193], v170 offset:3072
	v_lshl_add_u64 v[170:171], s[12:13], 0, v[140:141]
	s_add_i32 m0, s34, 0xc000
	ds_read_b128 v[194:197], v189
	ds_read_b128 v[198:201], v189 offset:1024
	ds_read_b128 v[202:205], v189 offset:2048
	ds_read_b128 v[206:209], v189 offset:3072
	ds_read_b128 v[210:213], v189 offset:4096
	ds_read_b128 v[230:233], v189 offset:5120
	ds_read_b128 v[234:237], v189 offset:6144
	ds_read_b128 v[238:241], v189 offset:7168
	global_load_lds_dwordx4 v[170:171], off
	s_add_i32 m0, s34, 0xe000
	v_lshl_add_u64 v[170:171], s[12:13], 0, v[142:143]
	global_load_lds_dwordx4 v[170:171], off
	s_waitcnt vmcnt(8) lgkmcnt(0)
	s_barrier
	v_mfma_f32_16x16x32_bf16 v[124:127], v[128:131], v[194:197], 0
	v_mfma_f32_16x16x32_bf16 v[120:123], v[148:151], v[194:197], 0
	v_mfma_f32_16x16x32_bf16 v[108:111], v[128:131], v[202:205], 0
	v_mfma_f32_16x16x32_bf16 v[104:107], v[148:151], v[202:205], 0
	v_mfma_f32_16x16x32_bf16 v[92:95], v[128:131], v[210:213], 0
	v_mfma_f32_16x16x32_bf16 v[88:91], v[148:151], v[210:213], 0
	v_mfma_f32_16x16x32_bf16 v[80:83], v[128:131], v[234:237], 0
	v_mfma_f32_16x16x32_bf16 v[72:75], v[148:151], v[234:237], 0
	v_mfma_f32_16x16x32_bf16 v[124:127], v[144:147], v[198:201], v[124:127]
	v_mfma_f32_16x16x32_bf16 v[120:123], v[152:155], v[198:201], v[120:123]
	v_mfma_f32_16x16x32_bf16 v[108:111], v[144:147], v[206:209], v[108:111]
	v_mfma_f32_16x16x32_bf16 v[104:107], v[152:155], v[206:209], v[104:107]
	v_mfma_f32_16x16x32_bf16 v[92:95], v[144:147], v[230:233], v[92:95]
	v_mfma_f32_16x16x32_bf16 v[88:91], v[152:155], v[230:233], v[88:91]
	v_mfma_f32_16x16x32_bf16 v[80:83], v[144:147], v[238:241], v[80:83]
	v_mfma_f32_16x16x32_bf16 v[72:75], v[152:155], v[238:241], v[72:75]
	v_mfma_f32_16x16x32_bf16 v[116:119], v[156:159], v[194:197], 0
	v_mfma_f32_16x16x32_bf16 v[112:115], v[164:167], v[194:197], 0
	v_mfma_f32_16x16x32_bf16 v[100:103], v[156:159], v[202:205], 0
	v_mfma_f32_16x16x32_bf16 v[96:99], v[164:167], v[202:205], 0
	v_mfma_f32_16x16x32_bf16 v[84:87], v[156:159], v[210:213], 0
	v_mfma_f32_16x16x32_bf16 v[76:79], v[164:167], v[210:213], 0
	v_mfma_f32_16x16x32_bf16 v[68:71], v[156:159], v[234:237], 0
	v_mfma_f32_16x16x32_bf16 v[64:67], v[164:167], v[234:237], 0
	v_mfma_f32_16x16x32_bf16 v[116:119], v[160:163], v[198:201], v[116:119]
	v_mfma_f32_16x16x32_bf16 v[112:115], v[190:193], v[198:201], v[112:115]
	v_mfma_f32_16x16x32_bf16 v[100:103], v[160:163], v[206:209], v[100:103]
	v_mfma_f32_16x16x32_bf16 v[96:99], v[190:193], v[206:209], v[96:99]
	v_mfma_f32_16x16x32_bf16 v[84:87], v[160:163], v[230:233], v[84:87]
	v_mfma_f32_16x16x32_bf16 v[76:79], v[190:193], v[230:233], v[76:79]
	v_mfma_f32_16x16x32_bf16 v[68:71], v[160:163], v[238:241], v[68:71]
	v_mfma_f32_16x16x32_bf16 v[64:67], v[190:193], v[238:241], v[64:67]
	s_barrier
	s_add_i32 s2, s2, s27
	v_lshl_add_u64 v[170:171], s[14:15], 0, v[136:137]
	s_mov_b32 m0, s2
	ds_read_b128 v[194:197], v189 offset:16384
	ds_read_b128 v[198:201], v189 offset:17408
	ds_read_b128 v[202:205], v189 offset:18432
	ds_read_b128 v[206:209], v189 offset:19456
	ds_read_b128 v[210:213], v189 offset:20480
	ds_read_b128 v[230:233], v189 offset:21504
	ds_read_b128 v[234:237], v189 offset:22528
	ds_read_b128 v[238:241], v189 offset:23552
	global_load_lds_dwordx4 v[170:171], off
	s_add_i32 m0, s2, 0x2000
	s_add_u32 s12, s14, 0x160000
	v_lshl_add_u64 v[172:173], s[14:15], 0, v[132:133]
	s_addc_u32 s13, s15, 0
	s_add_i32 s2, s24, s27
	global_load_lds_dwordx4 v[172:173], off
	v_lshl_add_u64 v[242:243], s[12:13], 0, v[136:137]
	s_mov_b32 m0, s2
	v_lshl_add_u64 v[244:245], s[16:17], 0, v[134:135]
	global_load_lds_dwordx4 v[242:243], off
	s_add_i32 m0, s2, 0x2000
	v_lshl_add_u64 v[242:243], s[12:13], 0, v[132:133]
	global_load_lds_dwordx4 v[242:243], off
	s_mov_b32 m0, s34
	v_lshl_add_u64 v[242:243], s[16:17], 0, v[138:139]
	global_load_lds_dwordx4 v[242:243], off
	s_mov_b32 m0, s35
	s_nop 0
	global_load_lds_dwordx4 v[244:245], off
	s_waitcnt vmcnt(8) lgkmcnt(0)
	s_barrier
	v_mfma_f32_16x16x32_bf16 v[60:63], v[128:131], v[194:197], 0
	v_mfma_f32_16x16x32_bf16 v[56:59], v[148:151], v[194:197], 0
	v_mfma_f32_16x16x32_bf16 v[44:47], v[128:131], v[202:205], 0
	v_mfma_f32_16x16x32_bf16 v[40:43], v[148:151], v[202:205], 0
	v_mfma_f32_16x16x32_bf16 v[28:31], v[128:131], v[210:213], 0
	v_mfma_f32_16x16x32_bf16 v[24:27], v[148:151], v[210:213], 0
	v_mfma_f32_16x16x32_bf16 v[12:15], v[128:131], v[234:237], 0
	v_mfma_f32_16x16x32_bf16 v[8:11], v[148:151], v[234:237], 0
	v_mfma_f32_16x16x32_bf16 v[60:63], v[144:147], v[198:201], v[60:63]
	v_mfma_f32_16x16x32_bf16 v[56:59], v[152:155], v[198:201], v[56:59]
	v_mfma_f32_16x16x32_bf16 v[44:47], v[144:147], v[206:209], v[44:47]
	v_mfma_f32_16x16x32_bf16 v[40:43], v[152:155], v[206:209], v[40:43]
	v_mfma_f32_16x16x32_bf16 v[28:31], v[144:147], v[230:233], v[28:31]
	v_mfma_f32_16x16x32_bf16 v[24:27], v[152:155], v[230:233], v[24:27]
	v_mfma_f32_16x16x32_bf16 v[12:15], v[144:147], v[238:241], v[12:15]
	v_mfma_f32_16x16x32_bf16 v[8:11], v[152:155], v[238:241], v[8:11]
	v_mfma_f32_16x16x32_bf16 v[52:55], v[156:159], v[194:197], 0
	v_mfma_f32_16x16x32_bf16 v[48:51], v[164:167], v[194:197], 0
	v_mfma_f32_16x16x32_bf16 v[36:39], v[156:159], v[202:205], 0
	v_mfma_f32_16x16x32_bf16 v[32:35], v[164:167], v[202:205], 0
	v_mfma_f32_16x16x32_bf16 v[20:23], v[156:159], v[210:213], 0
	v_mfma_f32_16x16x32_bf16 v[16:19], v[164:167], v[210:213], 0
	v_mfma_f32_16x16x32_bf16 v[4:7], v[156:159], v[234:237], 0
	v_mfma_f32_16x16x32_bf16 v[0:3], v[164:167], v[234:237], 0
	v_mfma_f32_16x16x32_bf16 v[52:55], v[160:163], v[198:201], v[52:55]
	v_mfma_f32_16x16x32_bf16 v[48:51], v[190:193], v[198:201], v[48:51]
	v_mfma_f32_16x16x32_bf16 v[36:39], v[160:163], v[206:209], v[36:39]
	v_mfma_f32_16x16x32_bf16 v[32:35], v[190:193], v[206:209], v[32:35]
	v_mfma_f32_16x16x32_bf16 v[20:23], v[160:163], v[230:233], v[20:23]
	v_mfma_f32_16x16x32_bf16 v[16:19], v[190:193], v[230:233], v[16:19]
	v_mfma_f32_16x16x32_bf16 v[4:7], v[160:163], v[238:241], v[4:7]
	v_mfma_f32_16x16x32_bf16 v[0:3], v[190:193], v[238:241], v[0:3]
	s_barrier
; #define PG8_STAGE(bufoff, gbase, voff) do { _Pragma("unroll") for (int _i = 0; _i < 2; ++_i) \
;         __builtin_amdgcn_global_load_lds((const unsigned*)((const char*)(gbase) + (voff)[_i]), (LAS unsigned*)(lds + (bufoff) + ldsw + _i * 8192), 16, 0, 0); } while (0)
; #define PG8_LDA(dst, b, h) do { _Pragma("unroll") for (int m = 0; m < 4; ++m) _Pragma("unroll") for (int k = 0; k < 2; ++k) dst[m][k] = *(const LAS bf16x8*)(lds + PG8_SA(b, h) + aoff + m * 2048 + k * 1024); } while (0)
; #define PG8_LDB(dst, b, h) do { _Pragma("unroll") for (int n = 0; n < 2; ++n) _Pragma("unroll") for (int k = 0; k < 2; ++k) dst[n][k] = *(const LAS bf16x8*)(lds + PG8_SB(b, h) + boff + n * 2048 + k * 1024); } while (0)
; #define PG8_MMA(ai, bj, At, Bt) do { __builtin_amdgcn_s_setprio(1); _Pragma("unroll") for (int m = 0; m < 4; ++m) _Pragma("unroll") for (int n = 0; n < 2; ++n) _Pragma("unroll") for (int k = 0; k < 2; ++k) \
;         acc[ai][bj][m][n] = __builtin_amdgcn_mfma_f32_16x16x32_bf16(Bt[n][k], At[m][k], acc[ai][bj][m][n], 0, 0, 0); __builtin_amdgcn_s_setprio(0); } while (0)
; #define PG8_WAIT_V(n) asm volatile("s_waitcnt vmcnt(" #n ")" ::: "memory")
; #define PG8_WAIT_L(n) asm volatile("s_waitcnt lgkmcnt(" #n ")" ::: "memory")
; #define PG8_BAR __builtin_amdgcn_s_barrier()
; #define PG8_SCHED __builtin_amdgcn_sched_barrier(0)
; template <class Epi>
; __device__ __forceinline__ void gemm_phase(LAS unsigned char* lds, const Gemm g, const StaticOrder& S, const Epi& E, const int tid) {
;     ...
;             PG8_LDB(B0, 1, 0); PG8_LDB(B1, 1, 1); PG8_SCHED; PG8_LDA(At, 1, 0); PG8_STAGE(PG8_SA(0, 1), a2 + hsA, voffA);
;             PG8_WAIT_V(8); PG8_WAIT_L(0); PG8_BAR; PG8_MMA(0, 0, At, B0); PG8_MMA(0, 1, At, B1); PG8_BAR; PG8_SCHED;
;             PG8_LDA(At, 1, 1); PG8_STAGE(PG8_SB(1, 0), b3, voffB); PG8_STAGE(PG8_SB(1, 1), b3 + hsB, voffB); PG8_STAGE(PG8_SA(1, 0), a3, voffA);
;             PG8_WAIT_V(8); PG8_WAIT_L(0); PG8_BAR; PG8_MMA(1, 0, At, B0); PG8_MMA(1, 1, At, B1); PG8_BAR; PG8_SCHED;
	s_add_i32 s2, 0, 0x18000
	s_add_i32 s24, 0, 0x1c000
	v_add_u32_e32 v152, s2, v184
	v_add_u32_e32 v190, s24, v184
	ds_read_b128 v[128:131], v152
	ds_read_b128 v[144:147], v152 offset:1024
	ds_read_b128 v[148:151], v152 offset:2048
	ds_read_b128 v[152:155], v152 offset:3072
	ds_read_b128 v[156:159], v190
	ds_read_b128 v[160:163], v190 offset:1024
	ds_read_b128 v[164:167], v190 offset:2048
	ds_read_b128 v[190:193], v190 offset:3072
	s_add_u32 s12, s16, 0x160000
	s_addc_u32 s13, s17, 0
	s_mov_b32 m0, s40
	v_lshl_add_u64 v[246:247], s[12:13], 0, v[138:139]
	ds_read_b128 v[194:197], v189 offset:32768
	ds_read_b128 v[198:201], v189 offset:33792
	ds_read_b128 v[202:205], v189 offset:34816
	ds_read_b128 v[206:209], v189 offset:35840
	ds_read_b128 v[210:213], v189 offset:36864
	ds_read_b128 v[230:233], v189 offset:37888
	ds_read_b128 v[234:237], v189 offset:38912
	ds_read_b128 v[238:241], v189 offset:39936
	global_load_lds_dwordx4 v[246:247], off
	s_mov_b32 m0, s41
	v_lshl_add_u64 v[246:247], s[12:13], 0, v[134:135]
	global_load_lds_dwordx4 v[246:247], off
	s_waitcnt vmcnt(8) lgkmcnt(0)
	s_barrier
	v_mfma_f32_16x16x32_bf16 v[124:127], v[128:131], v[194:197], v[124:127]
	v_mfma_f32_16x16x32_bf16 v[120:123], v[148:151], v[194:197], v[120:123]
	v_mfma_f32_16x16x32_bf16 v[108:111], v[128:131], v[202:205], v[108:111]
	v_mfma_f32_16x16x32_bf16 v[104:107], v[148:151], v[202:205], v[104:107]
	v_mfma_f32_16x16x32_bf16 v[92:95], v[128:131], v[210:213], v[92:95]
	v_mfma_f32_16x16x32_bf16 v[88:91], v[148:151], v[210:213], v[88:91]
	v_mfma_f32_16x16x32_bf16 v[80:83], v[128:131], v[234:237], v[80:83]
	v_mfma_f32_16x16x32_bf16 v[72:75], v[148:151], v[234:237], v[72:75]
	v_mfma_f32_16x16x32_bf16 v[124:127], v[144:147], v[198:201], v[124:127]
	v_mfma_f32_16x16x32_bf16 v[120:123], v[152:155], v[198:201], v[120:123]
	v_mfma_f32_16x16x32_bf16 v[108:111], v[144:147], v[206:209], v[108:111]
	v_mfma_f32_16x16x32_bf16 v[104:107], v[152:155], v[206:209], v[104:107]
	v_mfma_f32_16x16x32_bf16 v[92:95], v[144:147], v[230:233], v[92:95]
	v_mfma_f32_16x16x32_bf16 v[88:91], v[152:155], v[230:233], v[88:91]
	v_mfma_f32_16x16x32_bf16 v[80:83], v[144:147], v[238:241], v[80:83]
	v_mfma_f32_16x16x32_bf16 v[72:75], v[152:155], v[238:241], v[72:75]
	v_mfma_f32_16x16x32_bf16 v[116:119], v[156:159], v[194:197], v[116:119]
	v_mfma_f32_16x16x32_bf16 v[112:115], v[164:167], v[194:197], v[112:115]
	v_mfma_f32_16x16x32_bf16 v[100:103], v[156:159], v[202:205], v[100:103]
	v_mfma_f32_16x16x32_bf16 v[96:99], v[164:167], v[202:205], v[96:99]
	v_mfma_f32_16x16x32_bf16 v[84:87], v[156:159], v[210:213], v[84:87]
	v_mfma_f32_16x16x32_bf16 v[76:79], v[164:167], v[210:213], v[76:79]
	v_mfma_f32_16x16x32_bf16 v[68:71], v[156:159], v[234:237], v[68:71]
	v_mfma_f32_16x16x32_bf16 v[64:67], v[164:167], v[234:237], v[64:67]
	v_mfma_f32_16x16x32_bf16 v[116:119], v[160:163], v[198:201], v[116:119]
	v_mfma_f32_16x16x32_bf16 v[112:115], v[190:193], v[198:201], v[112:115]
	v_mfma_f32_16x16x32_bf16 v[100:103], v[160:163], v[206:209], v[100:103]
	v_mfma_f32_16x16x32_bf16 v[96:99], v[190:193], v[206:209], v[96:99]
	v_mfma_f32_16x16x32_bf16 v[84:87], v[160:163], v[230:233], v[84:87]
	v_mfma_f32_16x16x32_bf16 v[76:79], v[190:193], v[230:233], v[76:79]
	v_mfma_f32_16x16x32_bf16 v[68:71], v[160:163], v[238:241], v[68:71]
	v_mfma_f32_16x16x32_bf16 v[64:67], v[190:193], v[238:241], v[64:67]
	s_barrier
	s_add_i32 s2, s2, s27
	v_lshl_add_u64 v[170:171], v[170:171], 0, s[28:29]
	s_mov_b32 m0, s2
	ds_read_b128 v[194:197], v189 offset:49152
	ds_read_b128 v[198:201], v189 offset:50176
	ds_read_b128 v[202:205], v189 offset:51200
	ds_read_b128 v[206:209], v189 offset:52224
	ds_read_b128 v[210:213], v189 offset:53248
	ds_read_b128 v[230:233], v189 offset:54272
	ds_read_b128 v[234:237], v189 offset:55296
	ds_read_b128 v[238:241], v189 offset:56320
	global_load_lds_dwordx4 v[170:171], off
	s_add_i32 m0, s2, 0x2000
	s_add_u32 s12, s14, 0x160080
	v_lshl_add_u64 v[170:171], v[172:173], 0, s[28:29]
	s_addc_u32 s13, s15, 0
	s_add_i32 s2, s24, s27
	global_load_lds_dwordx4 v[170:171], off
	s_mov_b32 m0, s2
	v_lshl_add_u64 v[170:171], s[12:13], 0, v[136:137]
	global_load_lds_dwordx4 v[170:171], off
	s_add_i32 m0, s2, 0x2000
	v_lshl_add_u64 v[170:171], s[12:13], 0, v[132:133]
	global_load_lds_dwordx4 v[170:171], off
	s_mov_b32 m0, s44
	v_lshl_add_u64 v[170:171], v[242:243], 0, s[28:29]
	global_load_lds_dwordx4 v[170:171], off
	s_mov_b32 m0, s45
	v_lshl_add_u64 v[170:171], v[244:245], 0, s[28:29]
	global_load_lds_dwordx4 v[170:171], off
	s_waitcnt vmcnt(8) lgkmcnt(0)
	s_barrier
	v_mfma_f32_16x16x32_bf16 v[60:63], v[128:131], v[194:197], v[60:63]
	v_mfma_f32_16x16x32_bf16 v[56:59], v[148:151], v[194:197], v[56:59]
	v_mfma_f32_16x16x32_bf16 v[44:47], v[128:131], v[202:205], v[44:47]
	v_mfma_f32_16x16x32_bf16 v[40:43], v[148:151], v[202:205], v[40:43]
	v_mfma_f32_16x16x32_bf16 v[28:31], v[128:131], v[210:213], v[28:31]
	v_mfma_f32_16x16x32_bf16 v[24:27], v[148:151], v[210:213], v[24:27]
	v_mfma_f32_16x16x32_bf16 v[12:15], v[128:131], v[234:237], v[12:15]
	v_mfma_f32_16x16x32_bf16 v[8:11], v[148:151], v[234:237], v[8:11]
	v_mfma_f32_16x16x32_bf16 v[60:63], v[144:147], v[198:201], v[60:63]
	v_mfma_f32_16x16x32_bf16 v[56:59], v[152:155], v[198:201], v[56:59]
	v_mfma_f32_16x16x32_bf16 v[44:47], v[144:147], v[206:209], v[44:47]
	v_mfma_f32_16x16x32_bf16 v[40:43], v[152:155], v[206:209], v[40:43]
	v_mfma_f32_16x16x32_bf16 v[28:31], v[144:147], v[230:233], v[28:31]
	v_mfma_f32_16x16x32_bf16 v[24:27], v[152:155], v[230:233], v[24:27]
	v_mfma_f32_16x16x32_bf16 v[12:15], v[144:147], v[238:241], v[12:15]
	v_mfma_f32_16x16x32_bf16 v[8:11], v[152:155], v[238:241], v[8:11]
	v_mfma_f32_16x16x32_bf16 v[52:55], v[156:159], v[194:197], v[52:55]
	v_mfma_f32_16x16x32_bf16 v[48:51], v[164:167], v[194:197], v[48:51]
	v_mfma_f32_16x16x32_bf16 v[36:39], v[156:159], v[202:205], v[36:39]
	v_mfma_f32_16x16x32_bf16 v[32:35], v[164:167], v[202:205], v[32:35]
	v_mfma_f32_16x16x32_bf16 v[20:23], v[156:159], v[210:213], v[20:23]
	v_mfma_f32_16x16x32_bf16 v[16:19], v[164:167], v[210:213], v[16:19]
	v_mfma_f32_16x16x32_bf16 v[4:7], v[156:159], v[234:237], v[4:7]
	v_mfma_f32_16x16x32_bf16 v[0:3], v[164:167], v[234:237], v[0:3]
	v_mfma_f32_16x16x32_bf16 v[52:55], v[160:163], v[198:201], v[52:55]
	v_mfma_f32_16x16x32_bf16 v[48:51], v[190:193], v[198:201], v[48:51]
	v_mfma_f32_16x16x32_bf16 v[36:39], v[160:163], v[206:209], v[36:39]
	v_mfma_f32_16x16x32_bf16 v[32:35], v[190:193], v[206:209], v[32:35]
	v_mfma_f32_16x16x32_bf16 v[20:23], v[160:163], v[230:233], v[20:23]
	v_mfma_f32_16x16x32_bf16 v[16:19], v[190:193], v[230:233], v[16:19]
	v_mfma_f32_16x16x32_bf16 v[4:7], v[160:163], v[238:241], v[4:7]
	v_mfma_f32_16x16x32_bf16 v[0:3], v[190:193], v[238:241], v[0:3]
	s_barrier
	s_add_i32 s53, s53, 2
	s_add_u32 s38, s38, 0x100
	s_addc_u32 s39, s39, 0
	s_cmpk_gt_u32 s53, 0x55
	s_mov_b64 s[12:13], s[0:1]
; #define PG8_STAGE(bufoff, gbase, voff) do { _Pragma("unroll") for (int _i = 0; _i < 2; ++_i) \
;         __builtin_amdgcn_global_load_lds((const unsigned*)((const char*)(gbase) + (voff)[_i]), (LAS unsigned*)(lds + (bufoff) + ldsw + _i * 8192), 16, 0, 0); } while (0)
; #define PG8_LDA(dst, b, h) do { _Pragma("unroll") for (int m = 0; m < 4; ++m) _Pragma("unroll") for (int k = 0; k < 2; ++k) dst[m][k] = *(const LAS bf16x8*)(lds + PG8_SA(b, h) + aoff + m * 2048 + k * 1024); } while (0)
; #define PG8_LDB(dst, b, h) do { _Pragma("unroll") for (int n = 0; n < 2; ++n) _Pragma("unroll") for (int k = 0; k < 2; ++k) dst[n][k] = *(const LAS bf16x8*)(lds + PG8_SB(b, h) + boff + n * 2048 + k * 1024); } while (0)
; #define PG8_MMA(ai, bj, At, Bt) do { __builtin_amdgcn_s_setprio(1); _Pragma("unroll") for (int m = 0; m < 4; ++m) _Pragma("unroll") for (int n = 0; n < 2; ++n) _Pragma("unroll") for (int k = 0; k < 2; ++k) \
;         acc[ai][bj][m][n] = __builtin_amdgcn_mfma_f32_16x16x32_bf16(Bt[n][k], At[m][k], acc[ai][bj][m][n], 0, 0, 0); __builtin_amdgcn_s_setprio(0); } while (0)
; #define PG8_WAIT_V(n) asm volatile("s_waitcnt vmcnt(" #n ")" ::: "memory")
; #define PG8_WAIT_L(n) asm volatile("s_waitcnt lgkmcnt(" #n ")" ::: "memory")
; #define PG8_BAR __builtin_amdgcn_s_barrier()
; #define PG8_SCHED __builtin_amdgcn_sched_barrier(0)
; template <class Epi>
; __device__ __forceinline__ void gemm_phase(LAS unsigned char* lds, const Gemm g, const StaticOrder& S, const Epi& E, const int tid) {
;     ...
;             const bool last = (t == nt - 2);
;             const char* a1 = cA + (size_t)(t + 1) * kstep;
;             const char* a2 = last ? nA : cA + (size_t)(t + 2) * kstep; const char* b2 = last ? nB : cB + (size_t)(t + 2) * kstep;
;             const char* a3 = a2 + kstep; const char* b3 = b2 + kstep;
;             PG8_LDB(B0, 0, 0); PG8_LDB(B1, 0, 1); PG8_SCHED; PG8_LDA(At, 0, 0); PG8_STAGE(PG8_SA(1, 1), a1 + hsA, voffA);
;             PG8_WAIT_V(8); PG8_WAIT_L(0); PG8_BAR; PG8_MMA(0, 0, At, B0); PG8_MMA(0, 1, At, B1); PG8_BAR; PG8_SCHED;
;             PG8_LDA(At, 0, 1); PG8_STAGE(PG8_SB(0, 0), b2, voffB); PG8_STAGE(PG8_SB(0, 1), b2 + hsB, voffB); PG8_STAGE(PG8_SA(0, 0), a2, voffA);
;             PG8_WAIT_V(8); PG8_WAIT_L(0); PG8_BAR; PG8_MMA(1, 0, At, B0); PG8_MMA(1, 1, At, B1); PG8_BAR; PG8_SCHED;
.LBB0_1076:
	s_add_u32 s0, s12, 0x100
	s_addc_u32 s1, s13, 0
	s_add_i32 s2, 0, 0x10000
	s_cmpk_eq_i32 s53, 0x54
	s_cselect_b32 s17, s9, s1
	s_cselect_b32 s16, s8, s0
	s_cselect_b32 s15, s11, s39
	s_cselect_b32 s14, s10, s38
	s_add_i32 s24, 0, 0x14000
	v_add_u32_e32 v152, s2, v184
	v_add_u32_e32 v170, s24, v184
	ds_read_b128 v[128:131], v152
	ds_read_b128 v[144:147], v152 offset:1024
	ds_read_b128 v[148:151], v152 offset:2048
	ds_read_b128 v[152:155], v152 offset:3072
	ds_read_b128 v[156:159], v170
	ds_read_b128 v[160:163], v170 offset:1024
	ds_read_b128 v[164:167], v170 offset:2048
	ds_read_b128 v[190:193], v170 offset:3072
	v_lshl_add_u64 v[170:171], s[12:13], 0, v[140:141]
	s_add_i32 m0, s34, 0xc000
	ds_read_b128 v[194:197], v189
	ds_read_b128 v[198:201], v189 offset:1024
	ds_read_b128 v[202:205], v189 offset:2048
	ds_read_b128 v[206:209], v189 offset:3072
	ds_read_b128 v[210:213], v189 offset:4096
	ds_read_b128 v[230:233], v189 offset:5120
	ds_read_b128 v[234:237], v189 offset:6144
	ds_read_b128 v[238:241], v189 offset:7168
	global_load_lds_dwordx4 v[170:171], off
	s_add_i32 m0, s34, 0xe000
	v_lshl_add_u64 v[170:171], s[12:13], 0, v[142:143]
	global_load_lds_dwordx4 v[170:171], off
	s_waitcnt vmcnt(8) lgkmcnt(0)
	s_barrier
	v_mfma_f32_16x16x32_bf16 v[124:127], v[128:131], v[194:197], v[124:127]
	v_mfma_f32_16x16x32_bf16 v[120:123], v[148:151], v[194:197], v[120:123]
	v_mfma_f32_16x16x32_bf16 v[108:111], v[128:131], v[202:205], v[108:111]
	v_mfma_f32_16x16x32_bf16 v[104:107], v[148:151], v[202:205], v[104:107]
	v_mfma_f32_16x16x32_bf16 v[92:95], v[128:131], v[210:213], v[92:95]
	v_mfma_f32_16x16x32_bf16 v[88:91], v[148:151], v[210:213], v[88:91]
	v_mfma_f32_16x16x32_bf16 v[80:83], v[128:131], v[234:237], v[80:83]
	v_mfma_f32_16x16x32_bf16 v[72:75], v[148:151], v[234:237], v[72:75]
	v_mfma_f32_16x16x32_bf16 v[124:127], v[144:147], v[198:201], v[124:127]
	v_mfma_f32_16x16x32_bf16 v[120:123], v[152:155], v[198:201], v[120:123]
	v_mfma_f32_16x16x32_bf16 v[108:111], v[144:147], v[206:209], v[108:111]
	v_mfma_f32_16x16x32_bf16 v[104:107], v[152:155], v[206:209], v[104:107]
	v_mfma_f32_16x16x32_bf16 v[92:95], v[144:147], v[230:233], v[92:95]
	v_mfma_f32_16x16x32_bf16 v[88:91], v[152:155], v[230:233], v[88:91]
	v_mfma_f32_16x16x32_bf16 v[80:83], v[144:147], v[238:241], v[80:83]
	v_mfma_f32_16x16x32_bf16 v[72:75], v[152:155], v[238:241], v[72:75]
	v_mfma_f32_16x16x32_bf16 v[116:119], v[156:159], v[194:197], v[116:119]
	v_mfma_f32_16x16x32_bf16 v[112:115], v[164:167], v[194:197], v[112:115]
	v_mfma_f32_16x16x32_bf16 v[100:103], v[156:159], v[202:205], v[100:103]
	v_mfma_f32_16x16x32_bf16 v[96:99], v[164:167], v[202:205], v[96:99]
	v_mfma_f32_16x16x32_bf16 v[84:87], v[156:159], v[210:213], v[84:87]
	v_mfma_f32_16x16x32_bf16 v[76:79], v[164:167], v[210:213], v[76:79]
	v_mfma_f32_16x16x32_bf16 v[68:71], v[156:159], v[234:237], v[68:71]
	v_mfma_f32_16x16x32_bf16 v[64:67], v[164:167], v[234:237], v[64:67]
	v_mfma_f32_16x16x32_bf16 v[116:119], v[160:163], v[198:201], v[116:119]
	v_mfma_f32_16x16x32_bf16 v[112:115], v[190:193], v[198:201], v[112:115]
	v_mfma_f32_16x16x32_bf16 v[100:103], v[160:163], v[206:209], v[100:103]
	v_mfma_f32_16x16x32_bf16 v[96:99], v[190:193], v[206:209], v[96:99]
	v_mfma_f32_16x16x32_bf16 v[84:87], v[160:163], v[230:233], v[84:87]
	v_mfma_f32_16x16x32_bf16 v[76:79], v[190:193], v[230:233], v[76:79]
	v_mfma_f32_16x16x32_bf16 v[68:71], v[160:163], v[238:241], v[68:71]
	v_mfma_f32_16x16x32_bf16 v[64:67], v[190:193], v[238:241], v[64:67]
	s_barrier
	s_add_i32 s2, s2, s27
	v_lshl_add_u64 v[170:171], s[14:15], 0, v[136:137]
	s_mov_b32 m0, s2
	ds_read_b128 v[194:197], v189 offset:16384
	ds_read_b128 v[198:201], v189 offset:17408
	ds_read_b128 v[202:205], v189 offset:18432
	ds_read_b128 v[206:209], v189 offset:19456
	ds_read_b128 v[210:213], v189 offset:20480
	ds_read_b128 v[230:233], v189 offset:21504
	ds_read_b128 v[234:237], v189 offset:22528
	ds_read_b128 v[238:241], v189 offset:23552
	global_load_lds_dwordx4 v[170:171], off
	s_add_i32 m0, s2, 0x2000
	s_add_u32 s12, s14, 0x160000
	v_lshl_add_u64 v[172:173], s[14:15], 0, v[132:133]
	s_addc_u32 s13, s15, 0
	s_add_i32 s2, s24, s27
	global_load_lds_dwordx4 v[172:173], off
	v_lshl_add_u64 v[242:243], s[12:13], 0, v[136:137]
	s_mov_b32 m0, s2
	v_lshl_add_u64 v[244:245], s[16:17], 0, v[134:135]
	global_load_lds_dwordx4 v[242:243], off
	s_add_i32 m0, s2, 0x2000
	v_lshl_add_u64 v[242:243], s[12:13], 0, v[132:133]
	global_load_lds_dwordx4 v[242:243], off
	s_mov_b32 m0, s34
	v_lshl_add_u64 v[242:243], s[16:17], 0, v[138:139]
	global_load_lds_dwordx4 v[242:243], off
	s_mov_b32 m0, s35
	s_nop 0
	global_load_lds_dwordx4 v[244:245], off
	s_waitcnt vmcnt(8) lgkmcnt(0)
	s_barrier
; #define PG8_STAGE(bufoff, gbase, voff) do { _Pragma("unroll") for (int _i = 0; _i < 2; ++_i) \
;         __builtin_amdgcn_global_load_lds((const unsigned*)((const char*)(gbase) + (voff)[_i]), (LAS unsigned*)(lds + (bufoff) + ldsw + _i * 8192), 16, 0, 0); } while (0)
; #define PG8_LDA(dst, b, h) do { _Pragma("unroll") for (int m = 0; m < 4; ++m) _Pragma("unroll") for (int k = 0; k < 2; ++k) dst[m][k] = *(const LAS bf16x8*)(lds + PG8_SA(b, h) + aoff + m * 2048 + k * 1024); } while (0)
; #define PG8_LDB(dst, b, h) do { _Pragma("unroll") for (int n = 0; n < 2; ++n) _Pragma("unroll") for (int k = 0; k < 2; ++k) dst[n][k] = *(const LAS bf16x8*)(lds + PG8_SB(b, h) + boff + n * 2048 + k * 1024); } while (0)
; #define PG8_MMA(ai, bj, At, Bt) do { __builtin_amdgcn_s_setprio(1); _Pragma("unroll") for (int m = 0; m < 4; ++m) _Pragma("unroll") for (int n = 0; n < 2; ++n) _Pragma("unroll") for (int k = 0; k < 2; ++k) \
;         acc[ai][bj][m][n] = __builtin_amdgcn_mfma_f32_16x16x32_bf16(Bt[n][k], At[m][k], acc[ai][bj][m][n], 0, 0, 0); __builtin_amdgcn_s_setprio(0); } while (0)
; #define PG8_WAIT_V(n) asm volatile("s_waitcnt vmcnt(" #n ")" ::: "memory")
; #define PG8_WAIT_L(n) asm volatile("s_waitcnt lgkmcnt(" #n ")" ::: "memory")
; #define PG8_BAR __builtin_amdgcn_s_barrier()
; #define PG8_SCHED __builtin_amdgcn_sched_barrier(0)
; template <class Epi>
; __device__ __forceinline__ void gemm_phase(LAS unsigned char* lds, const Gemm g, const StaticOrder& S, const Epi& E, const int tid) {
;     ...
;             PG8_WAIT_V(8); PG8_WAIT_L(0); PG8_BAR; PG8_MMA(1, 0, At, B0); PG8_MMA(1, 1, At, B1); PG8_BAR; PG8_SCHED;
;             PG8_LDB(B0, 1, 0); PG8_LDB(B1, 1, 1); PG8_SCHED; PG8_LDA(At, 1, 0); PG8_STAGE(PG8_SA(0, 1), a2 + hsA, voffA);
;             PG8_WAIT_V(8); PG8_WAIT_L(0); PG8_BAR; PG8_MMA(0, 0, At, B0); PG8_MMA(0, 1, At, B1); PG8_BAR; PG8_SCHED;
	v_mfma_f32_16x16x32_bf16 v[60:63], v[128:131], v[194:197], v[60:63]
	v_mfma_f32_16x16x32_bf16 v[56:59], v[148:151], v[194:197], v[56:59]
	v_mfma_f32_16x16x32_bf16 v[44:47], v[128:131], v[202:205], v[44:47]
	v_mfma_f32_16x16x32_bf16 v[40:43], v[148:151], v[202:205], v[40:43]
	v_mfma_f32_16x16x32_bf16 v[28:31], v[128:131], v[210:213], v[28:31]
	v_mfma_f32_16x16x32_bf16 v[24:27], v[148:151], v[210:213], v[24:27]
	v_mfma_f32_16x16x32_bf16 v[12:15], v[128:131], v[234:237], v[12:15]
	v_mfma_f32_16x16x32_bf16 v[8:11], v[148:151], v[234:237], v[8:11]
	v_mfma_f32_16x16x32_bf16 v[60:63], v[144:147], v[198:201], v[60:63]
	v_mfma_f32_16x16x32_bf16 v[56:59], v[152:155], v[198:201], v[56:59]
	v_mfma_f32_16x16x32_bf16 v[44:47], v[144:147], v[206:209], v[44:47]
	v_mfma_f32_16x16x32_bf16 v[40:43], v[152:155], v[206:209], v[40:43]
	v_mfma_f32_16x16x32_bf16 v[28:31], v[144:147], v[230:233], v[28:31]
	v_mfma_f32_16x16x32_bf16 v[24:27], v[152:155], v[230:233], v[24:27]
	v_mfma_f32_16x16x32_bf16 v[12:15], v[144:147], v[238:241], v[12:15]
	v_mfma_f32_16x16x32_bf16 v[8:11], v[152:155], v[238:241], v[8:11]
	v_mfma_f32_16x16x32_bf16 v[52:55], v[156:159], v[194:197], v[52:55]
	v_mfma_f32_16x16x32_bf16 v[48:51], v[164:167], v[194:197], v[48:51]
	v_mfma_f32_16x16x32_bf16 v[36:39], v[156:159], v[202:205], v[36:39]
	v_mfma_f32_16x16x32_bf16 v[32:35], v[164:167], v[202:205], v[32:35]
	v_mfma_f32_16x16x32_bf16 v[20:23], v[156:159], v[210:213], v[20:23]
	v_mfma_f32_16x16x32_bf16 v[16:19], v[164:167], v[210:213], v[16:19]
	v_mfma_f32_16x16x32_bf16 v[4:7], v[156:159], v[234:237], v[4:7]
	v_mfma_f32_16x16x32_bf16 v[0:3], v[164:167], v[234:237], v[0:3]
	v_mfma_f32_16x16x32_bf16 v[52:55], v[160:163], v[198:201], v[52:55]
	v_mfma_f32_16x16x32_bf16 v[48:51], v[190:193], v[198:201], v[48:51]
	v_mfma_f32_16x16x32_bf16 v[36:39], v[160:163], v[206:209], v[36:39]
	v_mfma_f32_16x16x32_bf16 v[32:35], v[190:193], v[206:209], v[32:35]
	v_mfma_f32_16x16x32_bf16 v[20:23], v[160:163], v[230:233], v[20:23]
	v_mfma_f32_16x16x32_bf16 v[16:19], v[190:193], v[230:233], v[16:19]
	v_mfma_f32_16x16x32_bf16 v[4:7], v[160:163], v[238:241], v[4:7]
	v_mfma_f32_16x16x32_bf16 v[0:3], v[190:193], v[238:241], v[0:3]
	s_barrier
	s_add_i32 s2, 0, 0x18000
	s_add_i32 s24, 0, 0x1c000
	v_add_u32_e32 v152, s2, v184
	v_add_u32_e32 v190, s24, v184
	ds_read_b128 v[128:131], v152
	ds_read_b128 v[144:147], v152 offset:1024
	ds_read_b128 v[148:151], v152 offset:2048
	ds_read_b128 v[152:155], v152 offset:3072
	ds_read_b128 v[156:159], v190
	ds_read_b128 v[160:163], v190 offset:1024
	ds_read_b128 v[164:167], v190 offset:2048
	ds_read_b128 v[190:193], v190 offset:3072
	s_add_u32 s12, s16, 0x160000
	s_addc_u32 s13, s17, 0
	s_mov_b32 m0, s40
	v_lshl_add_u64 v[246:247], s[12:13], 0, v[138:139]
	ds_read_b128 v[194:197], v189 offset:32768
	ds_read_b128 v[198:201], v189 offset:33792
	ds_read_b128 v[202:205], v189 offset:34816
	ds_read_b128 v[206:209], v189 offset:35840
	ds_read_b128 v[210:213], v189 offset:36864
	ds_read_b128 v[230:233], v189 offset:37888
	ds_read_b128 v[234:237], v189 offset:38912
	ds_read_b128 v[238:241], v189 offset:39936
	global_load_lds_dwordx4 v[246:247], off
	s_mov_b32 m0, s41
	v_lshl_add_u64 v[246:247], s[12:13], 0, v[134:135]
	global_load_lds_dwordx4 v[246:247], off
	s_waitcnt vmcnt(8) lgkmcnt(0)
	s_barrier
	v_mfma_f32_16x16x32_bf16 v[124:127], v[128:131], v[194:197], v[124:127]
	v_mfma_f32_16x16x32_bf16 v[120:123], v[148:151], v[194:197], v[120:123]
	v_mfma_f32_16x16x32_bf16 v[108:111], v[128:131], v[202:205], v[108:111]
	v_mfma_f32_16x16x32_bf16 v[104:107], v[148:151], v[202:205], v[104:107]
	v_mfma_f32_16x16x32_bf16 v[92:95], v[128:131], v[210:213], v[92:95]
	v_mfma_f32_16x16x32_bf16 v[88:91], v[148:151], v[210:213], v[88:91]
	v_mfma_f32_16x16x32_bf16 v[80:83], v[128:131], v[234:237], v[80:83]
	v_mfma_f32_16x16x32_bf16 v[72:75], v[148:151], v[234:237], v[72:75]
	v_mfma_f32_16x16x32_bf16 v[124:127], v[144:147], v[198:201], v[124:127]
	v_mfma_f32_16x16x32_bf16 v[120:123], v[152:155], v[198:201], v[120:123]
	v_mfma_f32_16x16x32_bf16 v[108:111], v[144:147], v[206:209], v[108:111]
	v_mfma_f32_16x16x32_bf16 v[104:107], v[152:155], v[206:209], v[104:107]
	v_mfma_f32_16x16x32_bf16 v[92:95], v[144:147], v[230:233], v[92:95]
	v_mfma_f32_16x16x32_bf16 v[88:91], v[152:155], v[230:233], v[88:91]
	v_mfma_f32_16x16x32_bf16 v[80:83], v[144:147], v[238:241], v[80:83]
	v_mfma_f32_16x16x32_bf16 v[72:75], v[152:155], v[238:241], v[72:75]
	v_mfma_f32_16x16x32_bf16 v[116:119], v[156:159], v[194:197], v[116:119]
	v_mfma_f32_16x16x32_bf16 v[112:115], v[164:167], v[194:197], v[112:115]
	v_mfma_f32_16x16x32_bf16 v[100:103], v[156:159], v[202:205], v[100:103]
	v_mfma_f32_16x16x32_bf16 v[96:99], v[164:167], v[202:205], v[96:99]
	v_mfma_f32_16x16x32_bf16 v[84:87], v[156:159], v[210:213], v[84:87]
	v_mfma_f32_16x16x32_bf16 v[76:79], v[164:167], v[210:213], v[76:79]
	v_mfma_f32_16x16x32_bf16 v[68:71], v[156:159], v[234:237], v[68:71]
	v_mfma_f32_16x16x32_bf16 v[64:67], v[164:167], v[234:237], v[64:67]
	v_mfma_f32_16x16x32_bf16 v[116:119], v[160:163], v[198:201], v[116:119]
	v_mfma_f32_16x16x32_bf16 v[112:115], v[190:193], v[198:201], v[112:115]
	v_mfma_f32_16x16x32_bf16 v[100:103], v[160:163], v[206:209], v[100:103]
	v_mfma_f32_16x16x32_bf16 v[96:99], v[190:193], v[206:209], v[96:99]
	v_mfma_f32_16x16x32_bf16 v[84:87], v[160:163], v[230:233], v[84:87]
	v_mfma_f32_16x16x32_bf16 v[76:79], v[190:193], v[230:233], v[76:79]
	v_mfma_f32_16x16x32_bf16 v[68:71], v[160:163], v[238:241], v[68:71]
	v_mfma_f32_16x16x32_bf16 v[64:67], v[190:193], v[238:241], v[64:67]
	s_barrier
; #define PG8_STAGE(bufoff, gbase, voff) do { _Pragma("unroll") for (int _i = 0; _i < 2; ++_i) \
;         __builtin_amdgcn_global_load_lds((const unsigned*)((const char*)(gbase) + (voff)[_i]), (LAS unsigned*)(lds + (bufoff) + ldsw + _i * 8192), 16, 0, 0); } while (0)
; #define PG8_LDA(dst, b, h) do { _Pragma("unroll") for (int m = 0; m < 4; ++m) _Pragma("unroll") for (int k = 0; k < 2; ++k) dst[m][k] = *(const LAS bf16x8*)(lds + PG8_SA(b, h) + aoff + m * 2048 + k * 1024); } while (0)
; #define PG8_MMA(ai, bj, At, Bt) do { __builtin_amdgcn_s_setprio(1); _Pragma("unroll") for (int m = 0; m < 4; ++m) _Pragma("unroll") for (int n = 0; n < 2; ++n) _Pragma("unroll") for (int k = 0; k < 2; ++k) \
;         acc[ai][bj][m][n] = __builtin_amdgcn_mfma_f32_16x16x32_bf16(Bt[n][k], At[m][k], acc[ai][bj][m][n], 0, 0, 0); __builtin_amdgcn_s_setprio(0); } while (0)
; #define PG8_WAIT_V(n) asm volatile("s_waitcnt vmcnt(" #n ")" ::: "memory")
; #define PG8_WAIT_L(n) asm volatile("s_waitcnt lgkmcnt(" #n ")" ::: "memory")
; #define PG8_BAR __builtin_amdgcn_s_barrier()
; #define PG8_SCHED __builtin_amdgcn_sched_barrier(0)
; template <class Epi>
; __device__ __forceinline__ void gemm_phase(LAS unsigned char* lds, const Gemm g, const StaticOrder& S, const Epi& E, const int tid) {
;     ...
;             PG8_LDA(At, 1, 1); PG8_STAGE(PG8_SB(1, 0), b3, voffB); PG8_STAGE(PG8_SB(1, 1), b3 + hsB, voffB); PG8_STAGE(PG8_SA(1, 0), a3, voffA);
;             PG8_WAIT_V(8); PG8_WAIT_L(0); PG8_BAR; PG8_MMA(1, 0, At, B0); PG8_MMA(1, 1, At, B1); PG8_BAR; PG8_SCHED;
;         }
;         if (wr == 0) PG8_BAR;
	s_add_i32 s2, s2, s27
	v_lshl_add_u64 v[170:171], v[170:171], 0, s[28:29]
	s_mov_b32 m0, s2
	ds_read_b128 v[194:197], v189 offset:49152
	ds_read_b128 v[198:201], v189 offset:50176
	ds_read_b128 v[202:205], v189 offset:51200
	ds_read_b128 v[206:209], v189 offset:52224
	ds_read_b128 v[210:213], v189 offset:53248
	ds_read_b128 v[230:233], v189 offset:54272
	ds_read_b128 v[234:237], v189 offset:55296
	ds_read_b128 v[238:241], v189 offset:56320
	global_load_lds_dwordx4 v[170:171], off
	s_add_i32 m0, s2, 0x2000
	s_add_u32 s12, s14, 0x160080
	v_lshl_add_u64 v[170:171], v[172:173], 0, s[28:29]
	s_addc_u32 s13, s15, 0
	s_add_i32 s2, s24, s27
	global_load_lds_dwordx4 v[170:171], off
	s_mov_b32 m0, s2
	v_lshl_add_u64 v[170:171], s[12:13], 0, v[136:137]
	global_load_lds_dwordx4 v[170:171], off
	s_add_i32 m0, s2, 0x2000
	v_lshl_add_u64 v[170:171], s[12:13], 0, v[132:133]
	global_load_lds_dwordx4 v[170:171], off
	s_mov_b32 m0, s44
	v_lshl_add_u64 v[170:171], v[242:243], 0, s[28:29]
	global_load_lds_dwordx4 v[170:171], off
	s_mov_b32 m0, s45
	v_lshl_add_u64 v[170:171], v[244:245], 0, s[28:29]
	global_load_lds_dwordx4 v[170:171], off
	s_waitcnt vmcnt(8) lgkmcnt(0)
	s_barrier
	v_mfma_f32_16x16x32_bf16 v[60:63], v[128:131], v[194:197], v[60:63]
	v_mfma_f32_16x16x32_bf16 v[56:59], v[148:151], v[194:197], v[56:59]
	v_mfma_f32_16x16x32_bf16 v[44:47], v[128:131], v[202:205], v[44:47]
	v_mfma_f32_16x16x32_bf16 v[40:43], v[148:151], v[202:205], v[40:43]
	v_mfma_f32_16x16x32_bf16 v[28:31], v[128:131], v[210:213], v[28:31]
	v_mfma_f32_16x16x32_bf16 v[24:27], v[148:151], v[210:213], v[24:27]
	v_mfma_f32_16x16x32_bf16 v[12:15], v[128:131], v[234:237], v[12:15]
	v_mfma_f32_16x16x32_bf16 v[8:11], v[148:151], v[234:237], v[8:11]
	v_mfma_f32_16x16x32_bf16 v[60:63], v[144:147], v[198:201], v[60:63]
	v_mfma_f32_16x16x32_bf16 v[56:59], v[152:155], v[198:201], v[56:59]
	v_mfma_f32_16x16x32_bf16 v[44:47], v[144:147], v[206:209], v[44:47]
	v_mfma_f32_16x16x32_bf16 v[40:43], v[152:155], v[206:209], v[40:43]
	v_mfma_f32_16x16x32_bf16 v[28:31], v[144:147], v[230:233], v[28:31]
	v_mfma_f32_16x16x32_bf16 v[24:27], v[152:155], v[230:233], v[24:27]
	v_mfma_f32_16x16x32_bf16 v[12:15], v[144:147], v[238:241], v[12:15]
	v_mfma_f32_16x16x32_bf16 v[8:11], v[152:155], v[238:241], v[8:11]
	v_mfma_f32_16x16x32_bf16 v[52:55], v[156:159], v[194:197], v[52:55]
	v_mfma_f32_16x16x32_bf16 v[48:51], v[164:167], v[194:197], v[48:51]
	v_mfma_f32_16x16x32_bf16 v[36:39], v[156:159], v[202:205], v[36:39]
	v_mfma_f32_16x16x32_bf16 v[32:35], v[164:167], v[202:205], v[32:35]
	v_mfma_f32_16x16x32_bf16 v[20:23], v[156:159], v[210:213], v[20:23]
	v_mfma_f32_16x16x32_bf16 v[16:19], v[164:167], v[210:213], v[16:19]
	v_mfma_f32_16x16x32_bf16 v[4:7], v[156:159], v[234:237], v[4:7]
	v_mfma_f32_16x16x32_bf16 v[0:3], v[164:167], v[234:237], v[0:3]
	v_mfma_f32_16x16x32_bf16 v[52:55], v[160:163], v[198:201], v[52:55]
	v_mfma_f32_16x16x32_bf16 v[48:51], v[190:193], v[198:201], v[48:51]
	v_mfma_f32_16x16x32_bf16 v[36:39], v[160:163], v[206:209], v[36:39]
	v_mfma_f32_16x16x32_bf16 v[32:35], v[190:193], v[206:209], v[32:35]
	v_mfma_f32_16x16x32_bf16 v[20:23], v[160:163], v[230:233], v[20:23]
	v_mfma_f32_16x16x32_bf16 v[16:19], v[190:193], v[230:233], v[16:19]
	v_mfma_f32_16x16x32_bf16 v[4:7], v[160:163], v[238:241], v[4:7]
	v_mfma_f32_16x16x32_bf16 v[0:3], v[190:193], v[238:241], v[0:3]
	s_barrier
	s_add_i32 s53, s53, 2
	s_add_u32 s38, s38, 0x100
	s_addc_u32 s39, s39, 0
	s_cmpk_gt_u32 s53, 0x55
	s_mov_b64 s[12:13], s[0:1]
	s_cbranch_scc0 .LBB0_1076
	s_and_b64 vcc, exec, s[6:7]
	s_cbranch_vccz .LBB0_1079
	s_barrier
